# pool mixer weights staged into LDS once per MX phase (padded rows); pool units read their 32 weight fragments with ds_read_b128 instead of global loads
# speedup vs baseline: 1.0346x; 1.0053x over previous
.LBB0_577:
	s_lshr_b32 s2, s70, 5
	v_readlane_b32 s0, v253, 38
	s_cmp_ge_i32 s0, s2
	s_cbranch_scc1 .LBB0_595
	s_lshl_b32 s68, s74, 9
	v_readlane_b32 s8, v253, 16
	s_lshr_b32 s4, s70, 7
	s_lshl_b64 s[0:1], s[68:69], 2
	v_readlane_b32 s22, v253, 30
	v_readlane_b32 s23, v253, 31
	s_add_u32 s30, s22, s0
	s_addc_u32 s31, s23, s1
	v_readlane_b32 s0, v255, 7
	s_add_u32 s34, s0, 0x510000
	v_readlane_b32 s1, v255, 8
	s_addc_u32 s35, s1, 0
	s_add_u32 s36, s0, 0x508000
	s_addc_u32 s37, s1, 0
	s_add_u32 s38, s0, 0x500000
	s_addc_u32 s39, s1, 0
	s_add_u32 s74, s0, 0x518000
	s_addc_u32 s75, s1, 0
	s_abs_i32 s46, s4
	v_cvt_f32_u32_e32 v0, s46
	s_sub_i32 s0, 0, s46
	v_readlane_b32 s65, v253, 38
	s_ashr_i32 s3, s4, 31
	v_rcp_iflag_f32_e32 v0, v0
	s_lshl_b32 s56, s4, 7
	s_lshl_b32 s64, s51, 7
	v_readlane_b32 s9, v253, 17
	v_mul_f32_e32 v0, 0x4f7ffffe, v0
	v_cvt_u32_f32_e32 v0, v0
	v_readlane_b32 s10, v253, 18
	v_readlane_b32 s11, v253, 19
	v_readlane_b32 s12, v253, 20
	v_readfirstlane_b32 s1, v0
	s_mul_i32 s0, s0, s1
	s_mul_hi_u32 s0, s1, s0
	s_add_i32 s47, s1, s0
	s_lshl_b32 s0, s65, 7
	v_readlane_b32 s1, v253, 40
	s_add_i32 s59, s1, s0
	v_readlane_b32 s13, v253, 21
	v_readlane_b32 s14, v253, 22
	v_readlane_b32 s15, v253, 23
	v_readlane_b32 s16, v253, 24
	v_readlane_b32 s17, v253, 25
	v_readlane_b32 s18, v253, 26
	v_readlane_b32 s19, v253, 27
	v_readlane_b32 s20, v253, 28
	v_readlane_b32 s21, v253, 29
	s_barrier
	v_lshlrev_b32_e32 v84, 4, v209
	s_mov_b64 s[98:99], s[38:39]
	global_load_dwordx4 v[88:91], v84, s[98:99]
	s_add_u32 s98, s98, 0x2000
	s_addc_u32 s99, s99, 0
	global_load_dwordx4 v[92:95], v84, s[98:99]
	s_add_u32 s98, s98, 0x2000
	s_addc_u32 s99, s99, 0
	global_load_dwordx4 v[96:99], v84, s[98:99]
	s_add_u32 s98, s98, 0x2000
	s_addc_u32 s99, s99, 0
	global_load_dwordx4 v[100:103], v84, s[98:99]
	s_add_u32 s98, s98, 0x2000
	s_addc_u32 s99, s99, 0
	global_load_dwordx4 v[104:107], v84, s[98:99]
	s_add_u32 s98, s98, 0x2000
	s_addc_u32 s99, s99, 0
	global_load_dwordx4 v[108:111], v84, s[98:99]
	s_add_u32 s98, s98, 0x2000
	s_addc_u32 s99, s99, 0
	global_load_dwordx4 v[112:115], v84, s[98:99]
	s_add_u32 s98, s98, 0x2000
	s_addc_u32 s99, s99, 0
	global_load_dwordx4 v[116:119], v84, s[98:99]
	s_add_u32 s98, s98, 0x2000
	s_addc_u32 s99, s99, 0
	global_load_dwordx4 v[120:123], v84, s[98:99]
	s_add_u32 s98, s98, 0x2000
	s_addc_u32 s99, s99, 0
	global_load_dwordx4 v[124:127], v84, s[98:99]
	s_add_u32 s98, s98, 0x2000
	s_addc_u32 s99, s99, 0
	global_load_dwordx4 v[128:131], v84, s[98:99]
	s_add_u32 s98, s98, 0x2000
	s_addc_u32 s99, s99, 0
	global_load_dwordx4 v[132:135], v84, s[98:99]
	s_add_u32 s98, s98, 0x2000
	s_addc_u32 s99, s99, 0
	global_load_dwordx4 v[136:139], v84, s[98:99]
	s_add_u32 s98, s98, 0x2000
	s_addc_u32 s99, s99, 0
	global_load_dwordx4 v[140:143], v84, s[98:99]
	s_add_u32 s98, s98, 0x2000
	s_addc_u32 s99, s99, 0
	global_load_dwordx4 v[144:147], v84, s[98:99]
	s_add_u32 s98, s98, 0x2000
	s_addc_u32 s99, s99, 0
	global_load_dwordx4 v[148:151], v84, s[98:99]
	v_lshrrev_b32_e32 v85, 4, v209
	v_and_b32_e32 v86, 15, v209
	v_mul_u32_u24_e32 v85, 0x110, v85
	v_lshl_add_u32 v85, v86, 4, v85
	v_add_u32_e32 v86, 0x11000, v85
	s_waitcnt vmcnt(0)
	ds_write_b128 v85, v[88:91]
	ds_write_b128 v85, v[92:95] offset:8704
	ds_write_b128 v85, v[96:99] offset:17408
	ds_write_b128 v85, v[100:103] offset:26112
	ds_write_b128 v85, v[104:107] offset:34816
	ds_write_b128 v85, v[108:111] offset:43520
	ds_write_b128 v85, v[112:115] offset:52224
	ds_write_b128 v85, v[116:119] offset:60928
	ds_write_b128 v86, v[120:123]
	ds_write_b128 v86, v[124:127] offset:8704
	ds_write_b128 v86, v[128:131] offset:17408
	ds_write_b128 v86, v[132:135] offset:26112
	ds_write_b128 v86, v[136:139] offset:34816
	ds_write_b128 v86, v[140:143] offset:43520
	ds_write_b128 v86, v[144:147] offset:52224
	ds_write_b128 v86, v[148:151] offset:60928
	s_waitcnt lgkmcnt(0)
	s_barrier
	s_branch .LBB0_580

.LBB0_584:
	s_cmp_gt_i32 s16, 1
	s_cbranch_scc0 .LBB0_588
	s_cmp_eq_u32 s16, 2
	s_mov_b64 s[4:5], -1
	s_cbranch_scc0 .LBB0_587
	v_mov_b32_e32 v0, v209
	s_lshl_b32 s6, s56, 1
	v_readfirstlane_b32 s0, v0
	s_ashr_i32 s0, s0, 2
	v_and_b32_e32 v53, 15, v0
	v_bfi_b32 v32, -16, s0, v0
	v_bfe_u32 v51, v0, 4, 2
	v_subrev_u32_e32 v0, s6, v32
	v_add_u32_e32 v48, s59, v0
	s_mov_b32 s0, 0x38e38e39
	v_mul_hi_i32 v0, v48, s0
	v_lshrrev_b32_e32 v2, 31, v0
	v_ashrrev_i32_e32 v0, 13, v0
	v_add_u32_e32 v0, v0, v2
	v_mul_i32_i24_e32 v0, 0x9000, v0
	v_sub_u32_e32 v0, v48, v0
	s_mov_b32 s0, 0x8000
	v_cmp_gt_i32_e32 vcc, s0, v0
	v_lshlrev_b32_e32 v46, 4, v51
	v_mov_b32_e32 v47, v1
	v_cndmask_b32_e32 v2, v220, v221, vcc
	v_and_b32_e32 v56, v2, v0
	v_cndmask_b32_e32 v55, v217, v210, vcc
	v_add_u32_e32 v2, -4, v56
	v_add_u32_e32 v3, 4, v56
	v_max_i32_e32 v0, 0, v2
	v_min_u32_e32 v3, v3, v55
	v_sub_u32_e32 v0, v3, v0
	v_cvt_f32_i32_e32 v0, v0
	v_add_u32_e32 v10, -2, v56
	v_add_u32_e32 v14, -1, v56
	v_cmp_lt_u32_e64 s[4:5], v14, v55
	v_div_scale_f32 v3, s[0:1], v0, v0, 1.0
	v_rcp_f32_e32 v4, v3
	v_readlane_b32 s0, v253, 62
	v_readlane_b32 s1, v253, 63
	v_cndmask_b32_e64 v14, v56, v14, s[4:5]
	v_fma_f32 v5, -v3, v4, 1.0
	v_fmac_f32_e32 v4, v5, v4
	v_div_scale_f32 v5, vcc, 1.0, v0, 1.0
	v_mul_f32_e32 v6, v5, v4
	v_fma_f32 v7, -v3, v6, v5
	v_fmac_f32_e32 v6, v7, v4
	v_fma_f32 v3, -v3, v6, v5
	v_div_fmas_f32 v3, v3, v4, v6
	v_cmp_lt_u32_e32 vcc, v2, v55
	v_add_u32_e32 v6, -3, v56
	v_lshl_add_u64 v[30:31], s[0:1], 0, v[46:47]
	v_cndmask_b32_e64 v52, 0, 1.0, vcc
	v_cndmask_b32_e32 v2, v56, v2, vcc
	v_cmp_lt_u32_e32 vcc, v6, v55
	v_add_u32_e32 v2, v32, v2
	v_cmp_lt_u32_e64 s[0:1], v10, v55
	v_cndmask_b32_e32 v6, v56, v6, vcc
	v_subrev_u32_e32 v2, s6, v2
	v_add_u32_e32 v6, v32, v6
	v_cndmask_b32_e64 v10, v56, v10, s[0:1]
	v_sub_u32_e32 v2, v2, v56
	v_subrev_u32_e32 v6, s6, v6
	v_add_u32_e32 v10, v32, v10
	v_add_u32_e32 v22, 1, v56
	v_add_u32_e32 v2, s59, v2
	v_sub_u32_e32 v6, v6, v56
	v_subrev_u32_e32 v10, s6, v10
	v_add_u32_e32 v14, v32, v14
	v_cmp_lt_u32_e64 s[8:9], v22, v55
	v_add_u32_e32 v26, 2, v56
	v_div_fixup_f32 v50, v3, v0, 1.0
	v_ashrrev_i32_e32 v3, 31, v2
	v_add_u32_e32 v6, s59, v6
	v_sub_u32_e32 v10, v10, v56
	v_subrev_u32_e32 v14, s6, v14
	v_cndmask_b32_e64 v22, v56, v22, s[8:9]
	v_cmp_lt_u32_e64 s[10:11], v26, v55
	v_add_u32_e32 v33, 3, v56
	v_lshlrev_b64 v[2:3], 10, v[2:3]
	v_ashrrev_i32_e32 v7, 31, v6
	v_add_u32_e32 v10, s59, v10
	v_sub_u32_e32 v14, v14, v56
	v_add_u32_e32 v22, v32, v22
	v_cndmask_b32_e64 v26, v56, v26, s[10:11]
	v_cmp_lt_u32_e64 s[12:13], v33, v55
	v_lshl_add_u64 v[74:75], v[30:31], 0, v[2:3]
	v_lshlrev_b64 v[6:7], 10, v[6:7]
	v_ashrrev_i32_e32 v11, 31, v10
	v_add_u32_e32 v14, s59, v14
	v_subrev_u32_e32 v22, s6, v22
	v_add_u32_e32 v26, v32, v26
	v_cndmask_b32_e64 v33, v56, v33, s[12:13]
	global_load_dwordx4 v[2:5], v[74:75], off offset:512
	v_lshl_add_u64 v[72:73], v[30:31], 0, v[6:7]
	v_lshlrev_b64 v[10:11], 10, v[10:11]
	v_ashrrev_i32_e32 v15, 31, v14
	v_sub_u32_e32 v22, v22, v56
	v_subrev_u32_e32 v26, s6, v26
	v_add_u32_e32 v32, v32, v33
	v_ashrrev_i32_e32 v49, 31, v48
	global_load_dwordx4 v[6:9], v[72:73], off offset:512
	v_lshl_add_u64 v[70:71], v[30:31], 0, v[10:11]
	v_lshlrev_b64 v[14:15], 10, v[14:15]
	v_add_u32_e32 v22, s59, v22
	v_sub_u32_e32 v26, v26, v56
	v_subrev_u32_e32 v32, s6, v32
	v_lshlrev_b64 v[18:19], 10, v[48:49]
	global_load_dwordx4 v[10:13], v[70:71], off offset:512
	v_lshl_add_u64 v[68:69], v[30:31], 0, v[14:15]
	v_ashrrev_i32_e32 v23, 31, v22
	v_add_u32_e32 v26, s59, v26
	v_sub_u32_e32 v32, v32, v56
	global_load_dwordx4 v[14:17], v[68:69], off offset:512
	v_lshl_add_u64 v[38:39], v[30:31], 0, v[18:19]
	v_lshlrev_b64 v[22:23], 10, v[22:23]
	v_ashrrev_i32_e32 v27, 31, v26
	v_add_u32_e32 v32, s59, v32
	global_load_dwordx4 v[18:21], v[38:39], off offset:512
	v_lshl_add_u64 v[40:41], v[30:31], 0, v[22:23]
	v_lshlrev_b64 v[26:27], 10, v[26:27]
	v_ashrrev_i32_e32 v33, 31, v32
	global_load_dwordx4 v[22:25], v[40:41], off offset:512
	v_lshl_add_u64 v[42:43], v[30:31], 0, v[26:27]
	v_lshlrev_b64 v[32:33], 10, v[32:33]
	global_load_dwordx4 v[26:29], v[42:43], off offset:512
	v_lshl_add_u64 v[44:45], v[30:31], 0, v[32:33]
	global_load_dwordx4 v[30:33], v[44:45], off offset:512
	global_load_dwordx4 v[92:95], v[74:75], off offset:576
	global_load_dwordx4 v[96:99], v[72:73], off offset:576
	global_load_dwordx4 v[100:103], v[70:71], off offset:576
	global_load_dwordx4 v[104:107], v[68:69], off offset:576
	global_load_dwordx4 v[108:111], v[38:39], off offset:576
	global_load_dwordx4 v[112:115], v[40:41], off offset:576
	global_load_dwordx4 v[116:119], v[42:43], off offset:576
	global_load_dwordx4 v[120:123], v[44:45], off offset:576
	global_load_dwordx4 v[124:127], v[74:75], off offset:640
	global_load_dwordx4 v[128:131], v[72:73], off offset:640
	global_load_dwordx4 v[132:135], v[70:71], off offset:640
	global_load_dwordx4 v[136:139], v[68:69], off offset:640
	global_load_dwordx4 v[140:143], v[38:39], off offset:640
	global_load_dwordx4 v[144:147], v[40:41], off offset:640
	global_load_dwordx4 v[148:151], v[42:43], off offset:640
	global_load_dwordx4 v[152:155], v[44:45], off offset:640
	global_load_dwordx4 v[156:159], v[74:75], off offset:704
	global_load_dwordx4 v[160:163], v[72:73], off offset:704
	global_load_dwordx4 v[164:167], v[70:71], off offset:704
	global_load_dwordx4 v[168:171], v[68:69], off offset:704
	global_load_dwordx4 v[172:175], v[38:39], off offset:704
	global_load_dwordx4 v[176:179], v[40:41], off offset:704
	global_load_dwordx4 v[180:183], v[42:43], off offset:704
	global_load_dwordx4 v[184:187], v[44:45], off offset:704
	v_cndmask_b32_e64 v54, 0, 1.0, vcc
	v_cndmask_b32_e64 v58, 0, 1.0, s[0:1]
	v_cndmask_b32_e64 v66, 0, 1.0, s[4:5]
	v_cmp_lt_u32_e32 vcc, v56, v55
	v_cndmask_b32_e64 v62, 0, 1.0, s[8:9]
	v_cndmask_b32_e64 v60, 0, 1.0, s[10:11]
	v_cndmask_b32_e64 v64, 0, 1.0, vcc
	v_cndmask_b32_e64 v56, 0, 1.0, s[12:13]
	s_mov_b64 s[0:1], 0x400
	v_lshlrev_b32_e32 v0, 3, v51
	s_mov_b64 s[4:5], 0
	s_waitcnt vmcnt(31)
	v_lshlrev_b32_e32 v34, 16, v2
	v_and_b32_e32 v35, 0xffff0000, v2
	v_lshlrev_b32_e32 v36, 16, v3
	v_and_b32_e32 v37, 0xffff0000, v3
	v_pk_fma_f32 v[34:35], v[52:53], v[34:35], 0 op_sel_hi:[0, 1, 0]
	v_lshlrev_b32_e32 v76, 16, v4
	v_and_b32_e32 v77, 0xffff0000, v4
	v_lshlrev_b32_e32 v78, 16, v5
	s_waitcnt vmcnt(30)
	v_lshlrev_b32_e32 v2, 16, v6
	v_and_b32_e32 v3, 0xffff0000, v6
	v_pk_fma_f32 v[2:3], v[54:55], v[2:3], v[34:35] op_sel_hi:[0, 1, 1]
	v_and_b32_e32 v79, 0xffff0000, v5
	v_lshlrev_b32_e32 v4, 16, v7
	v_and_b32_e32 v5, 0xffff0000, v7
	v_lshlrev_b32_e32 v6, 16, v8
	s_waitcnt vmcnt(29)
	v_lshlrev_b32_e32 v80, 16, v10
	v_and_b32_e32 v81, 0xffff0000, v10
	v_pk_fma_f32 v[2:3], v[58:59], v[80:81], v[2:3] op_sel_hi:[0, 1, 1]
	v_lshlrev_b32_e32 v10, 16, v11
	v_and_b32_e32 v11, 0xffff0000, v11
	s_waitcnt vmcnt(28)
	v_lshlrev_b32_e32 v34, 16, v14
	v_and_b32_e32 v35, 0xffff0000, v14
	v_pk_fma_f32 v[2:3], v[66:67], v[34:35], v[2:3] op_sel_hi:[0, 1, 1]
	v_and_b32_e32 v7, 0xffff0000, v8
	v_lshlrev_b32_e32 v82, 16, v12
	s_waitcnt vmcnt(27)
	v_lshlrev_b32_e32 v34, 16, v18
	v_and_b32_e32 v35, 0xffff0000, v18
	v_pk_fma_f32 v[2:3], v[64:65], v[34:35], v[2:3] op_sel_hi:[0, 1, 1]
	v_and_b32_e32 v83, 0xffff0000, v12
	s_waitcnt vmcnt(26)
	v_lshlrev_b32_e32 v80, 16, v22
	v_and_b32_e32 v81, 0xffff0000, v22
	v_pk_fma_f32 v[2:3], v[62:63], v[80:81], v[2:3] op_sel_hi:[0, 1, 1]
	s_waitcnt vmcnt(25)
	v_lshlrev_b32_e32 v80, 16, v26
	v_and_b32_e32 v81, 0xffff0000, v26
	v_pk_fma_f32 v[2:3], v[60:61], v[80:81], v[2:3] op_sel_hi:[0, 1, 1]
	s_waitcnt vmcnt(24)
	v_lshlrev_b32_e32 v80, 16, v30
	v_and_b32_e32 v81, 0xffff0000, v30
	v_pk_fma_f32 v[2:3], v[56:57], v[80:81], v[2:3] op_sel_hi:[0, 1, 1]
	v_pk_fma_f32 v[2:3], v[50:51], v[2:3], v[34:35] op_sel_hi:[0, 1, 1] neg_lo:[0, 0, 1] neg_hi:[0, 0, 1]
	v_pk_fma_f32 v[34:35], v[52:53], v[36:37], 0 op_sel_hi:[0, 1, 0]
	v_pk_fma_f32 v[4:5], v[54:55], v[4:5], v[34:35] op_sel_hi:[0, 1, 1]
	v_pk_fma_f32 v[4:5], v[58:59], v[10:11], v[4:5] op_sel_hi:[0, 1, 1]
	v_lshlrev_b32_e32 v10, 16, v15
	v_and_b32_e32 v11, 0xffff0000, v15
	v_pk_fma_f32 v[4:5], v[66:67], v[10:11], v[4:5] op_sel_hi:[0, 1, 1]
	v_lshlrev_b32_e32 v10, 16, v19
	v_and_b32_e32 v11, 0xffff0000, v19
	v_pk_fma_f32 v[4:5], v[64:65], v[10:11], v[4:5] op_sel_hi:[0, 1, 1]
	v_lshlrev_b32_e32 v14, 16, v23
	v_and_b32_e32 v15, 0xffff0000, v23
	v_pk_fma_f32 v[4:5], v[62:63], v[14:15], v[4:5] op_sel_hi:[0, 1, 1]
	v_lshlrev_b32_e32 v14, 16, v27
	v_and_b32_e32 v15, 0xffff0000, v27
	v_pk_fma_f32 v[4:5], v[60:61], v[14:15], v[4:5] op_sel_hi:[0, 1, 1]
	v_lshlrev_b32_e32 v14, 16, v31
	v_and_b32_e32 v15, 0xffff0000, v31
	v_pk_fma_f32 v[4:5], v[56:57], v[14:15], v[4:5] op_sel_hi:[0, 1, 1]
	v_pk_fma_f32 v[4:5], v[50:51], v[4:5], v[10:11] op_sel_hi:[0, 1, 1] neg_lo:[0, 0, 1] neg_hi:[0, 0, 1]
	v_cvt_pk_bf16_f32 v2, v2, v3
	v_cvt_pk_bf16_f32 v3, v4, v5
	v_pk_fma_f32 v[4:5], v[52:53], v[76:77], 0 op_sel_hi:[0, 1, 0]
	v_pk_fma_f32 v[4:5], v[54:55], v[6:7], v[4:5] op_sel_hi:[0, 1, 1]
	v_pk_fma_f32 v[4:5], v[58:59], v[82:83], v[4:5] op_sel_hi:[0, 1, 1]
	v_lshlrev_b32_e32 v6, 16, v16
	v_and_b32_e32 v7, 0xffff0000, v16
	v_pk_fma_f32 v[4:5], v[66:67], v[6:7], v[4:5] op_sel_hi:[0, 1, 1]
	v_lshlrev_b32_e32 v6, 16, v20
	v_and_b32_e32 v7, 0xffff0000, v20
	v_pk_fma_f32 v[4:5], v[64:65], v[6:7], v[4:5] op_sel_hi:[0, 1, 1]
	v_lshlrev_b32_e32 v10, 16, v24
	v_and_b32_e32 v11, 0xffff0000, v24
	v_pk_fma_f32 v[4:5], v[62:63], v[10:11], v[4:5] op_sel_hi:[0, 1, 1]
	v_lshlrev_b32_e32 v10, 16, v28
	v_and_b32_e32 v11, 0xffff0000, v28
	v_pk_fma_f32 v[4:5], v[60:61], v[10:11], v[4:5] op_sel_hi:[0, 1, 1]
	v_lshlrev_b32_e32 v10, 16, v32
	v_and_b32_e32 v11, 0xffff0000, v32
	v_pk_fma_f32 v[4:5], v[56:57], v[10:11], v[4:5] op_sel_hi:[0, 1, 1]
	v_lshlrev_b32_e32 v8, 16, v9
	v_and_b32_e32 v9, 0xffff0000, v9
	v_pk_fma_f32 v[4:5], v[50:51], v[4:5], v[6:7] op_sel_hi:[0, 1, 1] neg_lo:[0, 0, 1] neg_hi:[0, 0, 1]
	v_pk_fma_f32 v[6:7], v[52:53], v[78:79], 0 op_sel_hi:[0, 1, 0]
	v_lshlrev_b32_e32 v12, 16, v13
	v_and_b32_e32 v13, 0xffff0000, v13
	v_pk_fma_f32 v[6:7], v[54:55], v[8:9], v[6:7] op_sel_hi:[0, 1, 1]
	v_pk_fma_f32 v[6:7], v[58:59], v[12:13], v[6:7] op_sel_hi:[0, 1, 1]
	v_lshlrev_b32_e32 v8, 16, v17
	v_and_b32_e32 v9, 0xffff0000, v17
	v_pk_fma_f32 v[6:7], v[66:67], v[8:9], v[6:7] op_sel_hi:[0, 1, 1]
	v_lshlrev_b32_e32 v8, 16, v21
	v_and_b32_e32 v9, 0xffff0000, v21
	v_pk_fma_f32 v[6:7], v[64:65], v[8:9], v[6:7] op_sel_hi:[0, 1, 1]
	v_lshlrev_b32_e32 v10, 16, v25
	v_and_b32_e32 v11, 0xffff0000, v25
	v_pk_fma_f32 v[6:7], v[62:63], v[10:11], v[6:7] op_sel_hi:[0, 1, 1]
	v_lshlrev_b32_e32 v10, 16, v29
	v_and_b32_e32 v11, 0xffff0000, v29
	v_pk_fma_f32 v[6:7], v[60:61], v[10:11], v[6:7] op_sel_hi:[0, 1, 1]
	v_lshlrev_b32_e32 v10, 16, v33
	v_and_b32_e32 v11, 0xffff0000, v33
	v_pk_fma_f32 v[6:7], v[56:57], v[10:11], v[6:7] op_sel_hi:[0, 1, 1]
	v_pk_fma_f32 v[6:7], v[50:51], v[6:7], v[8:9] op_sel_hi:[0, 1, 1] neg_lo:[0, 0, 1] neg_hi:[0, 0, 1]
	v_cvt_pk_bf16_f32 v4, v4, v5
	v_cvt_pk_bf16_f32 v5, v6, v7
	s_nop 0
	s_nop 0
	s_nop 0
	s_nop 0
	s_nop 0
	s_nop 0
	s_nop 0
	s_nop 0
	s_waitcnt vmcnt(23)
	v_lshlrev_b32_e32 v76, 16, v92
	v_and_b32_e32 v77, 0xffff0000, v92
	v_lshlrev_b32_e32 v78, 16, v93
	v_and_b32_e32 v79, 0xffff0000, v93
	s_waitcnt vmcnt(22)
	v_lshlrev_b32_e32 v6, 16, v96
	v_and_b32_e32 v7, 0xffff0000, v96
	v_pk_fma_f32 v[76:77], v[52:53], v[76:77], 0 op_sel_hi:[0, 1, 0]
	s_waitcnt vmcnt(21)
	v_lshlrev_b32_e32 v84, 16, v100
	v_and_b32_e32 v85, 0xffff0000, v100
	v_pk_fma_f32 v[6:7], v[54:55], v[6:7], v[76:77] op_sel_hi:[0, 1, 1]
	v_pk_fma_f32 v[6:7], v[58:59], v[84:85], v[6:7] op_sel_hi:[0, 1, 1]
	s_waitcnt vmcnt(20)
	v_lshlrev_b32_e32 v76, 16, v104
	v_and_b32_e32 v77, 0xffff0000, v104
	v_pk_fma_f32 v[6:7], v[66:67], v[76:77], v[6:7] op_sel_hi:[0, 1, 1]
	s_waitcnt vmcnt(19)
	v_lshlrev_b32_e32 v76, 16, v108
	v_and_b32_e32 v77, 0xffff0000, v108
	v_pk_fma_f32 v[6:7], v[64:65], v[76:77], v[6:7] op_sel_hi:[0, 1, 1]
	s_waitcnt vmcnt(18)
	v_lshlrev_b32_e32 v84, 16, v112
	v_and_b32_e32 v85, 0xffff0000, v112
	v_pk_fma_f32 v[6:7], v[62:63], v[84:85], v[6:7] op_sel_hi:[0, 1, 1]
	s_waitcnt vmcnt(17)
	v_lshlrev_b32_e32 v84, 16, v116
	v_and_b32_e32 v85, 0xffff0000, v116
	v_pk_fma_f32 v[6:7], v[60:61], v[84:85], v[6:7] op_sel_hi:[0, 1, 1]
	s_waitcnt vmcnt(16)
	v_lshlrev_b32_e32 v84, 16, v120
	v_and_b32_e32 v85, 0xffff0000, v120
	v_pk_fma_f32 v[6:7], v[56:57], v[84:85], v[6:7] op_sel_hi:[0, 1, 1]
	v_lshlrev_b32_e32 v80, 16, v94
	v_and_b32_e32 v81, 0xffff0000, v94
	v_lshlrev_b32_e32 v82, 16, v95
	v_and_b32_e32 v83, 0xffff0000, v95
	v_lshlrev_b32_e32 v8, 16, v97
	v_and_b32_e32 v9, 0xffff0000, v97
	v_pk_fma_f32 v[6:7], v[50:51], v[6:7], v[76:77] op_sel_hi:[0, 1, 1] neg_lo:[0, 0, 1] neg_hi:[0, 0, 1]
	v_pk_fma_f32 v[76:77], v[52:53], v[78:79], 0 op_sel_hi:[0, 1, 0]
	v_lshlrev_b32_e32 v22, 16, v101
	v_and_b32_e32 v23, 0xffff0000, v101
	v_pk_fma_f32 v[8:9], v[54:55], v[8:9], v[76:77] op_sel_hi:[0, 1, 1]
	v_pk_fma_f32 v[8:9], v[58:59], v[22:23], v[8:9] op_sel_hi:[0, 1, 1]
	v_lshlrev_b32_e32 v14, 16, v105
	v_and_b32_e32 v15, 0xffff0000, v105
	v_pk_fma_f32 v[8:9], v[66:67], v[14:15], v[8:9] op_sel_hi:[0, 1, 1]
	v_lshlrev_b32_e32 v14, 16, v109
	v_and_b32_e32 v15, 0xffff0000, v109
	v_pk_fma_f32 v[8:9], v[64:65], v[14:15], v[8:9] op_sel_hi:[0, 1, 1]
	v_lshlrev_b32_e32 v18, 16, v113
	v_and_b32_e32 v19, 0xffff0000, v113
	v_pk_fma_f32 v[8:9], v[62:63], v[18:19], v[8:9] op_sel_hi:[0, 1, 1]
	v_lshlrev_b32_e32 v18, 16, v117
	v_and_b32_e32 v19, 0xffff0000, v117
	v_pk_fma_f32 v[8:9], v[60:61], v[18:19], v[8:9] op_sel_hi:[0, 1, 1]
	v_lshlrev_b32_e32 v18, 16, v121
	v_and_b32_e32 v19, 0xffff0000, v121
	v_pk_fma_f32 v[8:9], v[56:57], v[18:19], v[8:9] op_sel_hi:[0, 1, 1]
	v_pk_fma_f32 v[8:9], v[50:51], v[8:9], v[14:15] op_sel_hi:[0, 1, 1] neg_lo:[0, 0, 1] neg_hi:[0, 0, 1]
	v_lshlrev_b32_e32 v10, 16, v98
	v_and_b32_e32 v11, 0xffff0000, v98
	v_cvt_pk_bf16_f32 v6, v6, v7
	v_cvt_pk_bf16_f32 v7, v8, v9
	v_pk_fma_f32 v[8:9], v[52:53], v[80:81], 0 op_sel_hi:[0, 1, 0]
	v_lshlrev_b32_e32 v86, 16, v102
	v_and_b32_e32 v87, 0xffff0000, v102
	v_pk_fma_f32 v[8:9], v[54:55], v[10:11], v[8:9] op_sel_hi:[0, 1, 1]
	v_pk_fma_f32 v[8:9], v[58:59], v[86:87], v[8:9] op_sel_hi:[0, 1, 1]
	v_lshlrev_b32_e32 v10, 16, v106
	v_and_b32_e32 v11, 0xffff0000, v106
	v_pk_fma_f32 v[8:9], v[66:67], v[10:11], v[8:9] op_sel_hi:[0, 1, 1]
	v_lshlrev_b32_e32 v10, 16, v110
	v_and_b32_e32 v11, 0xffff0000, v110
	v_pk_fma_f32 v[8:9], v[64:65], v[10:11], v[8:9] op_sel_hi:[0, 1, 1]
	v_lshlrev_b32_e32 v14, 16, v114
	v_and_b32_e32 v15, 0xffff0000, v114
	v_pk_fma_f32 v[8:9], v[62:63], v[14:15], v[8:9] op_sel_hi:[0, 1, 1]
	v_lshlrev_b32_e32 v14, 16, v118
	v_and_b32_e32 v15, 0xffff0000, v118
	v_pk_fma_f32 v[8:9], v[60:61], v[14:15], v[8:9] op_sel_hi:[0, 1, 1]
	v_lshlrev_b32_e32 v14, 16, v122
	v_and_b32_e32 v15, 0xffff0000, v122
	v_pk_fma_f32 v[8:9], v[56:57], v[14:15], v[8:9] op_sel_hi:[0, 1, 1]
	v_lshlrev_b32_e32 v12, 16, v99
	v_and_b32_e32 v13, 0xffff0000, v99
	v_pk_fma_f32 v[8:9], v[50:51], v[8:9], v[10:11] op_sel_hi:[0, 1, 1] neg_lo:[0, 0, 1] neg_hi:[0, 0, 1]
	v_pk_fma_f32 v[10:11], v[52:53], v[82:83], 0 op_sel_hi:[0, 1, 0]
	v_lshlrev_b32_e32 v24, 16, v103
	v_and_b32_e32 v25, 0xffff0000, v103
	v_pk_fma_f32 v[10:11], v[54:55], v[12:13], v[10:11] op_sel_hi:[0, 1, 1]
	v_pk_fma_f32 v[10:11], v[58:59], v[24:25], v[10:11] op_sel_hi:[0, 1, 1]
	v_lshlrev_b32_e32 v12, 16, v107
	v_and_b32_e32 v13, 0xffff0000, v107
	v_pk_fma_f32 v[10:11], v[66:67], v[12:13], v[10:11] op_sel_hi:[0, 1, 1]
	v_lshlrev_b32_e32 v12, 16, v111
	v_and_b32_e32 v13, 0xffff0000, v111
	v_pk_fma_f32 v[10:11], v[64:65], v[12:13], v[10:11] op_sel_hi:[0, 1, 1]
	v_lshlrev_b32_e32 v14, 16, v115
	v_and_b32_e32 v15, 0xffff0000, v115
	v_pk_fma_f32 v[10:11], v[62:63], v[14:15], v[10:11] op_sel_hi:[0, 1, 1]
	v_lshlrev_b32_e32 v14, 16, v119
	v_and_b32_e32 v15, 0xffff0000, v119
	v_pk_fma_f32 v[10:11], v[60:61], v[14:15], v[10:11] op_sel_hi:[0, 1, 1]
	v_lshlrev_b32_e32 v14, 16, v123
	v_and_b32_e32 v15, 0xffff0000, v123
	v_pk_fma_f32 v[10:11], v[56:57], v[14:15], v[10:11] op_sel_hi:[0, 1, 1]
	v_pk_fma_f32 v[10:11], v[50:51], v[10:11], v[12:13] op_sel_hi:[0, 1, 1] neg_lo:[0, 0, 1] neg_hi:[0, 0, 1]
	v_cvt_pk_bf16_f32 v8, v8, v9
	v_cvt_pk_bf16_f32 v9, v10, v11
	s_nop 0
	s_nop 0
	s_nop 0
	s_nop 0
	s_nop 0
	s_nop 0
	s_nop 0
	s_nop 0
	s_waitcnt vmcnt(15)
	v_lshlrev_b32_e32 v80, 16, v124
	v_and_b32_e32 v81, 0xffff0000, v124
	v_lshlrev_b32_e32 v82, 16, v125
	v_and_b32_e32 v83, 0xffff0000, v125
	s_waitcnt vmcnt(14)
	v_lshlrev_b32_e32 v10, 16, v128
	v_and_b32_e32 v11, 0xffff0000, v128
	v_pk_fma_f32 v[80:81], v[52:53], v[80:81], 0 op_sel_hi:[0, 1, 0]
	s_waitcnt vmcnt(13)
	v_lshlrev_b32_e32 v88, 16, v132
	v_and_b32_e32 v89, 0xffff0000, v132
	v_pk_fma_f32 v[10:11], v[54:55], v[10:11], v[80:81] op_sel_hi:[0, 1, 1]
	v_pk_fma_f32 v[10:11], v[58:59], v[88:89], v[10:11] op_sel_hi:[0, 1, 1]
	s_waitcnt vmcnt(12)
	v_lshlrev_b32_e32 v80, 16, v136
	v_and_b32_e32 v81, 0xffff0000, v136
	v_pk_fma_f32 v[10:11], v[66:67], v[80:81], v[10:11] op_sel_hi:[0, 1, 1]
	s_waitcnt vmcnt(11)
	v_lshlrev_b32_e32 v80, 16, v140
	v_and_b32_e32 v81, 0xffff0000, v140
	v_pk_fma_f32 v[10:11], v[64:65], v[80:81], v[10:11] op_sel_hi:[0, 1, 1]
	s_waitcnt vmcnt(10)
	v_lshlrev_b32_e32 v88, 16, v144
	v_and_b32_e32 v89, 0xffff0000, v144
	v_pk_fma_f32 v[10:11], v[62:63], v[88:89], v[10:11] op_sel_hi:[0, 1, 1]
	s_waitcnt vmcnt(9)
	v_lshlrev_b32_e32 v88, 16, v148
	v_and_b32_e32 v89, 0xffff0000, v148
	v_pk_fma_f32 v[10:11], v[60:61], v[88:89], v[10:11] op_sel_hi:[0, 1, 1]
	s_waitcnt vmcnt(8)
	v_lshlrev_b32_e32 v88, 16, v152
	v_and_b32_e32 v89, 0xffff0000, v152
	v_pk_fma_f32 v[10:11], v[56:57], v[88:89], v[10:11] op_sel_hi:[0, 1, 1]
	v_lshlrev_b32_e32 v84, 16, v126
	v_and_b32_e32 v85, 0xffff0000, v126
	v_lshlrev_b32_e32 v86, 16, v127
	v_and_b32_e32 v87, 0xffff0000, v127
	v_lshlrev_b32_e32 v12, 16, v129
	v_and_b32_e32 v13, 0xffff0000, v129
	v_pk_fma_f32 v[10:11], v[50:51], v[10:11], v[80:81] op_sel_hi:[0, 1, 1] neg_lo:[0, 0, 1] neg_hi:[0, 0, 1]
	v_pk_fma_f32 v[80:81], v[52:53], v[82:83], 0 op_sel_hi:[0, 1, 0]
	v_lshlrev_b32_e32 v18, 16, v133
	v_and_b32_e32 v19, 0xffff0000, v133
	v_pk_fma_f32 v[12:13], v[54:55], v[12:13], v[80:81] op_sel_hi:[0, 1, 1]
	v_pk_fma_f32 v[12:13], v[58:59], v[18:19], v[12:13] op_sel_hi:[0, 1, 1]
	v_lshlrev_b32_e32 v18, 16, v137
	v_and_b32_e32 v19, 0xffff0000, v137
	v_pk_fma_f32 v[12:13], v[66:67], v[18:19], v[12:13] op_sel_hi:[0, 1, 1]
	v_lshlrev_b32_e32 v18, 16, v141
	v_and_b32_e32 v19, 0xffff0000, v141
	v_pk_fma_f32 v[12:13], v[64:65], v[18:19], v[12:13] op_sel_hi:[0, 1, 1]
	v_lshlrev_b32_e32 v22, 16, v145
	v_and_b32_e32 v23, 0xffff0000, v145
	v_pk_fma_f32 v[12:13], v[62:63], v[22:23], v[12:13] op_sel_hi:[0, 1, 1]
	v_lshlrev_b32_e32 v22, 16, v149
	v_and_b32_e32 v23, 0xffff0000, v149
	v_pk_fma_f32 v[12:13], v[60:61], v[22:23], v[12:13] op_sel_hi:[0, 1, 1]
	v_lshlrev_b32_e32 v22, 16, v153
	v_and_b32_e32 v23, 0xffff0000, v153
	v_pk_fma_f32 v[12:13], v[56:57], v[22:23], v[12:13] op_sel_hi:[0, 1, 1]
	v_pk_fma_f32 v[12:13], v[50:51], v[12:13], v[18:19] op_sel_hi:[0, 1, 1] neg_lo:[0, 0, 1] neg_hi:[0, 0, 1]
	v_lshlrev_b32_e32 v14, 16, v130
	v_and_b32_e32 v15, 0xffff0000, v130
	v_cvt_pk_bf16_f32 v10, v10, v11
	v_cvt_pk_bf16_f32 v11, v12, v13
	v_pk_fma_f32 v[12:13], v[52:53], v[84:85], 0 op_sel_hi:[0, 1, 0]
	v_lshlrev_b32_e32 v90, 16, v134
	v_and_b32_e32 v91, 0xffff0000, v134
	v_pk_fma_f32 v[12:13], v[54:55], v[14:15], v[12:13] op_sel_hi:[0, 1, 1]
	v_pk_fma_f32 v[12:13], v[58:59], v[90:91], v[12:13] op_sel_hi:[0, 1, 1]
	v_lshlrev_b32_e32 v14, 16, v138
	v_and_b32_e32 v15, 0xffff0000, v138
	v_pk_fma_f32 v[12:13], v[66:67], v[14:15], v[12:13] op_sel_hi:[0, 1, 1]
	v_lshlrev_b32_e32 v14, 16, v142
	v_and_b32_e32 v15, 0xffff0000, v142
	v_pk_fma_f32 v[12:13], v[64:65], v[14:15], v[12:13] op_sel_hi:[0, 1, 1]
	v_lshlrev_b32_e32 v18, 16, v146
	v_and_b32_e32 v19, 0xffff0000, v146
	v_pk_fma_f32 v[12:13], v[62:63], v[18:19], v[12:13] op_sel_hi:[0, 1, 1]
	v_lshlrev_b32_e32 v18, 16, v150
	v_and_b32_e32 v19, 0xffff0000, v150
	v_pk_fma_f32 v[12:13], v[60:61], v[18:19], v[12:13] op_sel_hi:[0, 1, 1]
	v_lshlrev_b32_e32 v18, 16, v154
	v_and_b32_e32 v19, 0xffff0000, v154
	v_pk_fma_f32 v[12:13], v[56:57], v[18:19], v[12:13] op_sel_hi:[0, 1, 1]
	v_lshlrev_b32_e32 v16, 16, v131
	v_and_b32_e32 v17, 0xffff0000, v131
	v_pk_fma_f32 v[12:13], v[50:51], v[12:13], v[14:15] op_sel_hi:[0, 1, 1] neg_lo:[0, 0, 1] neg_hi:[0, 0, 1]
	v_pk_fma_f32 v[14:15], v[52:53], v[86:87], 0 op_sel_hi:[0, 1, 0]
	v_lshlrev_b32_e32 v20, 16, v135
	v_and_b32_e32 v21, 0xffff0000, v135
	v_pk_fma_f32 v[14:15], v[54:55], v[16:17], v[14:15] op_sel_hi:[0, 1, 1]
	v_pk_fma_f32 v[14:15], v[58:59], v[20:21], v[14:15] op_sel_hi:[0, 1, 1]
	v_lshlrev_b32_e32 v16, 16, v139
	v_and_b32_e32 v17, 0xffff0000, v139
	v_pk_fma_f32 v[14:15], v[66:67], v[16:17], v[14:15] op_sel_hi:[0, 1, 1]
	v_lshlrev_b32_e32 v16, 16, v143
	v_and_b32_e32 v17, 0xffff0000, v143
	v_pk_fma_f32 v[14:15], v[64:65], v[16:17], v[14:15] op_sel_hi:[0, 1, 1]
	v_lshlrev_b32_e32 v18, 16, v147
	v_and_b32_e32 v19, 0xffff0000, v147
	v_pk_fma_f32 v[14:15], v[62:63], v[18:19], v[14:15] op_sel_hi:[0, 1, 1]
	v_lshlrev_b32_e32 v18, 16, v151
	v_and_b32_e32 v19, 0xffff0000, v151
	v_pk_fma_f32 v[14:15], v[60:61], v[18:19], v[14:15] op_sel_hi:[0, 1, 1]
	v_lshlrev_b32_e32 v18, 16, v155
	v_and_b32_e32 v19, 0xffff0000, v155
	v_pk_fma_f32 v[14:15], v[56:57], v[18:19], v[14:15] op_sel_hi:[0, 1, 1]
	v_pk_fma_f32 v[14:15], v[50:51], v[14:15], v[16:17] op_sel_hi:[0, 1, 1] neg_lo:[0, 0, 1] neg_hi:[0, 0, 1]
	v_cvt_pk_bf16_f32 v12, v12, v13
	v_cvt_pk_bf16_f32 v13, v14, v15
	s_nop 0
	s_nop 0
	s_nop 0
	s_nop 0
	s_nop 0
	s_nop 0
	s_nop 0
	s_nop 0
	s_nop 0
	s_nop 0
	s_waitcnt vmcnt(7)
	v_lshlrev_b32_e32 v68, 16, v156
	v_and_b32_e32 v69, 0xffff0000, v156
	v_lshlrev_b32_e32 v70, 16, v157
	v_and_b32_e32 v71, 0xffff0000, v157
	s_waitcnt vmcnt(6)
	v_lshlrev_b32_e32 v14, 16, v160
	v_and_b32_e32 v15, 0xffff0000, v160
	v_pk_fma_f32 v[68:69], v[52:53], v[68:69], 0 op_sel_hi:[0, 1, 0]
	s_waitcnt vmcnt(5)
	v_lshlrev_b32_e32 v76, 16, v164
	v_and_b32_e32 v77, 0xffff0000, v164
	v_pk_fma_f32 v[14:15], v[54:55], v[14:15], v[68:69] op_sel_hi:[0, 1, 1]
	v_pk_fma_f32 v[14:15], v[58:59], v[76:77], v[14:15] op_sel_hi:[0, 1, 1]
	s_waitcnt vmcnt(4)
	v_lshlrev_b32_e32 v68, 16, v168
	v_and_b32_e32 v69, 0xffff0000, v168
	v_pk_fma_f32 v[14:15], v[66:67], v[68:69], v[14:15] op_sel_hi:[0, 1, 1]
	s_waitcnt vmcnt(3)
	v_lshlrev_b32_e32 v68, 16, v172
	v_and_b32_e32 v69, 0xffff0000, v172
	v_pk_fma_f32 v[14:15], v[64:65], v[68:69], v[14:15] op_sel_hi:[0, 1, 1]
	s_waitcnt vmcnt(2)
	v_lshlrev_b32_e32 v76, 16, v176
	v_and_b32_e32 v77, 0xffff0000, v176
	v_pk_fma_f32 v[14:15], v[62:63], v[76:77], v[14:15] op_sel_hi:[0, 1, 1]
	s_waitcnt vmcnt(1)
	v_lshlrev_b32_e32 v76, 16, v180
	v_and_b32_e32 v77, 0xffff0000, v180
	v_pk_fma_f32 v[14:15], v[60:61], v[76:77], v[14:15] op_sel_hi:[0, 1, 1]
	s_waitcnt vmcnt(0)
	v_lshlrev_b32_e32 v76, 16, v184
	v_and_b32_e32 v77, 0xffff0000, v184
	v_pk_fma_f32 v[14:15], v[56:57], v[76:77], v[14:15] op_sel_hi:[0, 1, 1]
	v_lshlrev_b32_e32 v72, 16, v158
	v_and_b32_e32 v73, 0xffff0000, v158
	v_lshlrev_b32_e32 v74, 16, v159
	v_and_b32_e32 v75, 0xffff0000, v159
	v_lshlrev_b32_e32 v16, 16, v161
	v_and_b32_e32 v17, 0xffff0000, v161
	v_pk_fma_f32 v[14:15], v[50:51], v[14:15], v[68:69] op_sel_hi:[0, 1, 1] neg_lo:[0, 0, 1] neg_hi:[0, 0, 1]
	v_pk_fma_f32 v[68:69], v[52:53], v[70:71], 0 op_sel_hi:[0, 1, 0]
	v_lshlrev_b32_e32 v30, 16, v165
	v_and_b32_e32 v31, 0xffff0000, v165
	v_pk_fma_f32 v[16:17], v[54:55], v[16:17], v[68:69] op_sel_hi:[0, 1, 1]
	v_pk_fma_f32 v[16:17], v[58:59], v[30:31], v[16:17] op_sel_hi:[0, 1, 1]
	v_lshlrev_b32_e32 v22, 16, v169
	v_and_b32_e32 v23, 0xffff0000, v169
	v_pk_fma_f32 v[16:17], v[66:67], v[22:23], v[16:17] op_sel_hi:[0, 1, 1]
	v_lshlrev_b32_e32 v22, 16, v173
	v_and_b32_e32 v23, 0xffff0000, v173
	v_pk_fma_f32 v[16:17], v[64:65], v[22:23], v[16:17] op_sel_hi:[0, 1, 1]
	v_lshlrev_b32_e32 v26, 16, v177
	v_and_b32_e32 v27, 0xffff0000, v177
	v_pk_fma_f32 v[16:17], v[62:63], v[26:27], v[16:17] op_sel_hi:[0, 1, 1]
	v_lshlrev_b32_e32 v26, 16, v181
	v_and_b32_e32 v27, 0xffff0000, v181
	v_pk_fma_f32 v[16:17], v[60:61], v[26:27], v[16:17] op_sel_hi:[0, 1, 1]
	v_lshlrev_b32_e32 v26, 16, v185
	v_and_b32_e32 v27, 0xffff0000, v185
	v_pk_fma_f32 v[16:17], v[56:57], v[26:27], v[16:17] op_sel_hi:[0, 1, 1]
	v_pk_fma_f32 v[16:17], v[50:51], v[16:17], v[22:23] op_sel_hi:[0, 1, 1] neg_lo:[0, 0, 1] neg_hi:[0, 0, 1]
	v_lshlrev_b32_e32 v18, 16, v162
	v_and_b32_e32 v19, 0xffff0000, v162
	v_cvt_pk_bf16_f32 v14, v14, v15
	v_cvt_pk_bf16_f32 v15, v16, v17
	v_pk_fma_f32 v[16:17], v[52:53], v[72:73], 0 op_sel_hi:[0, 1, 0]
	v_lshlrev_b32_e32 v78, 16, v166
	v_and_b32_e32 v79, 0xffff0000, v166
	v_pk_fma_f32 v[16:17], v[54:55], v[18:19], v[16:17] op_sel_hi:[0, 1, 1]
	v_pk_fma_f32 v[16:17], v[58:59], v[78:79], v[16:17] op_sel_hi:[0, 1, 1]
	v_lshlrev_b32_e32 v18, 16, v170
	v_and_b32_e32 v19, 0xffff0000, v170
	v_pk_fma_f32 v[16:17], v[66:67], v[18:19], v[16:17] op_sel_hi:[0, 1, 1]
	v_lshlrev_b32_e32 v18, 16, v174
	v_and_b32_e32 v19, 0xffff0000, v174
	v_pk_fma_f32 v[16:17], v[64:65], v[18:19], v[16:17] op_sel_hi:[0, 1, 1]
	v_lshlrev_b32_e32 v22, 16, v178
	v_and_b32_e32 v23, 0xffff0000, v178
	v_pk_fma_f32 v[16:17], v[62:63], v[22:23], v[16:17] op_sel_hi:[0, 1, 1]
	v_lshlrev_b32_e32 v22, 16, v182
	v_and_b32_e32 v23, 0xffff0000, v182
	v_pk_fma_f32 v[16:17], v[60:61], v[22:23], v[16:17] op_sel_hi:[0, 1, 1]
	v_lshlrev_b32_e32 v22, 16, v186
	v_and_b32_e32 v23, 0xffff0000, v186
	v_pk_fma_f32 v[16:17], v[56:57], v[22:23], v[16:17] op_sel_hi:[0, 1, 1]
	v_lshlrev_b32_e32 v20, 16, v163
	v_and_b32_e32 v21, 0xffff0000, v163
	v_pk_fma_f32 v[16:17], v[50:51], v[16:17], v[18:19] op_sel_hi:[0, 1, 1] neg_lo:[0, 0, 1] neg_hi:[0, 0, 1]
	v_pk_fma_f32 v[18:19], v[52:53], v[74:75], 0 op_sel_hi:[0, 1, 0]
	v_lshlrev_b32_e32 v32, 16, v167
	v_and_b32_e32 v33, 0xffff0000, v167
	v_pk_fma_f32 v[18:19], v[54:55], v[20:21], v[18:19] op_sel_hi:[0, 1, 1]
	v_pk_fma_f32 v[18:19], v[58:59], v[32:33], v[18:19] op_sel_hi:[0, 1, 1]
	v_lshlrev_b32_e32 v20, 16, v171
	v_and_b32_e32 v21, 0xffff0000, v171
	v_pk_fma_f32 v[18:19], v[66:67], v[20:21], v[18:19] op_sel_hi:[0, 1, 1]
	v_lshlrev_b32_e32 v20, 16, v175
	v_and_b32_e32 v21, 0xffff0000, v175
	v_pk_fma_f32 v[18:19], v[64:65], v[20:21], v[18:19] op_sel_hi:[0, 1, 1]
	v_lshlrev_b32_e32 v22, 16, v179
	v_and_b32_e32 v23, 0xffff0000, v179
	v_pk_fma_f32 v[18:19], v[62:63], v[22:23], v[18:19] op_sel_hi:[0, 1, 1]
	v_lshlrev_b32_e32 v22, 16, v183
	v_and_b32_e32 v23, 0xffff0000, v183
	v_pk_fma_f32 v[18:19], v[60:61], v[22:23], v[18:19] op_sel_hi:[0, 1, 1]
	v_lshlrev_b32_e32 v22, 16, v187
	v_and_b32_e32 v23, 0xffff0000, v187
	v_pk_fma_f32 v[18:19], v[56:57], v[22:23], v[18:19] op_sel_hi:[0, 1, 1]
	v_pk_fma_f32 v[18:19], v[50:51], v[18:19], v[20:21] op_sel_hi:[0, 1, 1] neg_lo:[0, 0, 1] neg_hi:[0, 0, 1]
	v_lshlrev_b64 v[20:21], 11, v[48:49]
	v_cvt_pk_bf16_f32 v16, v16, v17
	v_cvt_pk_bf16_f32 v17, v18, v19
	v_lshl_add_u64 v[18:19], s[34:35], 0, v[46:47]
	v_lshl_add_u64 v[30:31], s[84:85], 0, v[20:21]
	v_lshlrev_b32_e32 v20, 8, v53
	v_mov_b32_e32 v21, v1
	v_lshl_add_u64 v[28:29], v[18:19], 0, v[20:21]
	v_add_co_u32_e32 v56, vcc, 0x1000, v28
	s_nop 1
	v_addc_co_u32_e32 v57, vcc, 0, v29, vcc
	v_add_co_u32_e32 v58, vcc, 0x3000, v28
	s_nop 1
	v_addc_co_u32_e32 v59, vcc, 0, v29, vcc
	v_add_co_u32_e32 v60, vcc, 0x5000, v28
	s_nop 1
	v_addc_co_u32_e32 v61, vcc, 0, v29, vcc
	v_add_co_u32_e32 v62, vcc, 0x7000, v28
	s_nop 1
	v_addc_co_u32_e32 v63, vcc, 0, v29, vcc
	global_load_dwordx4 v[100:103], v46, s[30:31] offset:1024
	global_load_dwordx4 v[120:123], v46, s[30:31] offset:1088
	global_load_dwordx4 v[140:143], v46, s[30:31] offset:1152
	global_load_dwordx4 v[160:163], v46, s[30:31] offset:1216
	global_load_dwordx4 v[180:183], v46, s[30:31] offset:1280
	global_load_dwordx4 v[200:203], v46, s[30:31] offset:1344
	global_load_dwordx4 v[234:237], v46, s[30:31] offset:1408
	v_and_b32_e32 v56, 15, v209
	v_bfe_u32 v57, v209, 4, 2
	v_mul_u32_u24_e32 v56, 0x110, v56
	v_lshl_add_u32 v56, v57, 4, v56
	v_add_u32_e32 v56, 0x11000, v56
	ds_read_b128 v[84:87], v56 offset:0
	ds_read_b128 v[88:91], v56 offset:64
	ds_read_b128 v[92:95], v56 offset:128
	ds_read_b128 v[96:99], v56 offset:192
	ds_read_b128 v[104:107], v56 offset:4352
	ds_read_b128 v[108:111], v56 offset:4416
	ds_read_b128 v[112:115], v56 offset:4480
	ds_read_b128 v[116:119], v56 offset:4544
	ds_read_b128 v[124:127], v56 offset:8704
	ds_read_b128 v[128:131], v56 offset:8768
	ds_read_b128 v[132:135], v56 offset:8832
	ds_read_b128 v[136:139], v56 offset:8896
	ds_read_b128 v[144:147], v56 offset:13056
	ds_read_b128 v[148:151], v56 offset:13120
	ds_read_b128 v[152:155], v56 offset:13184
	ds_read_b128 v[156:159], v56 offset:13248
	s_nop 0
	s_nop 0
	s_waitcnt lgkmcnt(12)
	v_mfma_f32_16x16x32_bf16 v[18:21], v[84:87], v[2:5], 0
	v_lshl_add_u64 v[26:27], v[30:31], 0, s[0:1]
	s_movk_i32 s0, 0x1000
	v_mfma_f32_16x16x32_bf16 v[18:21], v[88:91], v[6:9], v[18:21]
	s_nop 0
	v_mfma_f32_16x16x32_bf16 v[18:21], v[92:95], v[10:13], v[18:21]
	s_nop 0
	v_mfma_f32_16x16x32_bf16 v[18:21], v[96:99], v[14:17], v[18:21]
	s_nop 0
	s_waitcnt vmcnt(6)
	s_nop 5
	v_pk_mul_f32 v[20:21], v[20:21], v[102:103]
	v_add_co_u32_e32 v24, vcc, s0, v28
	v_pk_mul_f32 v[18:19], v[18:19], v[100:101]
	s_nop 0
	v_addc_co_u32_e32 v25, vcc, 0, v29, vcc
	s_movk_i32 s0, 0x2000
	v_cvt_pk_bf16_f32 v22, v18, v19
	v_cvt_pk_bf16_f32 v23, v20, v21
	v_lshl_add_u64 v[18:19], v[30:31], 0, v[0:1]
	v_add_co_u32_e32 v34, vcc, s0, v28
	global_store_dwordx2 v[18:19], v[22:23], off offset:1536
	s_nop 0
	v_addc_co_u32_e32 v35, vcc, 0, v29, vcc
	s_nop 0
	s_nop 0
	s_waitcnt lgkmcnt(8)
	v_mfma_f32_16x16x32_bf16 v[20:23], v[104:107], v[2:5], 0
	s_movk_i32 s0, 0x3000
	v_mov_b32_e32 v0, 0x170
	v_lshl_or_b32 v0, v51, 2, v0
	v_mfma_f32_16x16x32_bf16 v[20:23], v[108:111], v[6:9], v[20:23]
	s_nop 0
	v_mfma_f32_16x16x32_bf16 v[20:23], v[112:115], v[10:13], v[20:23]
	s_nop 0
	v_add_co_u32_e32 v24, vcc, s0, v28
	v_mfma_f32_16x16x32_bf16 v[20:23], v[116:119], v[14:17], v[20:23]
	s_nop 0
	v_addc_co_u32_e32 v25, vcc, 0, v29, vcc
	s_movk_i32 s0, 0x4000
	s_waitcnt vmcnt(6)
	s_nop 3
	v_pk_mul_f32 v[22:23], v[22:23], v[122:123]
	v_pk_mul_f32 v[20:21], v[20:21], v[120:121]
	s_nop 0
	v_cvt_pk_bf16_f32 v20, v20, v21
	v_cvt_pk_bf16_f32 v21, v22, v23
	global_store_dwordx2 v[18:19], v[20:21], off offset:1568
	s_nop 0
	s_nop 0
	s_nop 0
	s_waitcnt lgkmcnt(4)
	v_mfma_f32_16x16x32_bf16 v[20:23], v[124:127], v[2:5], 0
	v_mfma_f32_16x16x32_bf16 v[20:23], v[128:131], v[6:9], v[20:23]
	s_nop 0
	v_mfma_f32_16x16x32_bf16 v[20:23], v[132:135], v[10:13], v[20:23]
	s_nop 0
	v_add_co_u32_e32 v34, vcc, s0, v28
	v_mfma_f32_16x16x32_bf16 v[20:23], v[136:139], v[14:17], v[20:23]
	s_nop 0
	v_addc_co_u32_e32 v35, vcc, 0, v29, vcc
	s_movk_i32 s0, 0x5000
	s_waitcnt vmcnt(6)
	s_nop 3
	v_pk_mul_f32 v[22:23], v[22:23], v[142:143]
	v_pk_mul_f32 v[20:21], v[20:21], v[140:141]
	s_nop 0
	v_cvt_pk_bf16_f32 v20, v20, v21
	v_cvt_pk_bf16_f32 v21, v22, v23
	global_store_dwordx2 v[18:19], v[20:21], off offset:1600
	s_nop 0
	s_nop 0
	s_nop 0
	s_waitcnt lgkmcnt(0)
	v_mfma_f32_16x16x32_bf16 v[20:23], v[144:147], v[2:5], 0
	v_mfma_f32_16x16x32_bf16 v[20:23], v[148:151], v[6:9], v[20:23]
	s_nop 0
	v_mfma_f32_16x16x32_bf16 v[20:23], v[152:155], v[10:13], v[20:23]
	s_nop 0
	v_add_co_u32_e32 v24, vcc, s0, v28
	v_mfma_f32_16x16x32_bf16 v[20:23], v[156:159], v[14:17], v[20:23]
	s_nop 0
	v_addc_co_u32_e32 v25, vcc, 0, v29, vcc
	s_movk_i32 s0, 0x6000
	s_waitcnt vmcnt(6)
	s_nop 3
	v_pk_mul_f32 v[22:23], v[22:23], v[162:163]
	v_pk_mul_f32 v[20:21], v[20:21], v[160:161]
	s_nop 0
	v_cvt_pk_bf16_f32 v20, v20, v21
	v_cvt_pk_bf16_f32 v21, v22, v23
	global_store_dwordx2 v[18:19], v[20:21], off offset:1632
	s_nop 0
	s_nop 0
	s_nop 0
	ds_read_b128 v[164:167], v56 offset:17408
	ds_read_b128 v[168:171], v56 offset:17472
	ds_read_b128 v[172:175], v56 offset:17536
	ds_read_b128 v[176:179], v56 offset:17600
	ds_read_b128 v[184:187], v56 offset:21760
	ds_read_b128 v[188:191], v56 offset:21824
	ds_read_b128 v[192:195], v56 offset:21888
	ds_read_b128 v[196:199], v56 offset:21952
	ds_read_b128 v[204:207], v56 offset:26112
	ds_read_b128 v[222:225], v56 offset:26176
	ds_read_b128 v[226:229], v56 offset:26240
	ds_read_b128 v[230:233], v56 offset:26304
	ds_read_b128 v[238:241], v56 offset:30464
	ds_read_b128 v[242:245], v56 offset:30528
	ds_read_b128 v[246:249], v56 offset:30592
	ds_read_b128 v[52:55], v56 offset:30656
	s_waitcnt lgkmcnt(12)
	v_mfma_f32_16x16x32_bf16 v[20:23], v[164:167], v[2:5], 0
	v_mfma_f32_16x16x32_bf16 v[20:23], v[168:171], v[6:9], v[20:23]
	s_nop 0
	v_mfma_f32_16x16x32_bf16 v[20:23], v[172:175], v[10:13], v[20:23]
	s_nop 0
	v_add_co_u32_e32 v34, vcc, s0, v28
	v_mfma_f32_16x16x32_bf16 v[20:23], v[176:179], v[14:17], v[20:23]
	s_nop 0
	v_addc_co_u32_e32 v35, vcc, 0, v29, vcc
	s_waitcnt vmcnt(6)
	s_nop 4
	v_pk_mul_f32 v[22:23], v[22:23], v[182:183]
	v_pk_mul_f32 v[20:21], v[20:21], v[180:181]
	s_nop 0
	v_cvt_pk_bf16_f32 v20, v20, v21
	v_cvt_pk_bf16_f32 v21, v22, v23
	global_store_dwordx2 v[18:19], v[20:21], off offset:1664
	s_nop 0
	s_nop 0
	s_nop 0
	s_waitcnt lgkmcnt(8)
	v_mfma_f32_16x16x32_bf16 v[20:23], v[184:187], v[2:5], 0
	v_mfma_f32_16x16x32_bf16 v[20:23], v[188:191], v[6:9], v[20:23]
	s_nop 0
	v_mfma_f32_16x16x32_bf16 v[20:23], v[192:195], v[10:13], v[20:23]
	s_nop 0
	v_mfma_f32_16x16x32_bf16 v[20:23], v[196:199], v[14:17], v[20:23]
	s_nop 0
	s_waitcnt vmcnt(6)
	s_nop 5
	v_pk_mul_f32 v[22:23], v[22:23], v[202:203]
	v_pk_mul_f32 v[20:21], v[20:21], v[200:201]
	s_nop 0
	v_cvt_pk_bf16_f32 v20, v20, v21
	v_cvt_pk_bf16_f32 v21, v22, v23
	global_store_dwordx2 v[18:19], v[20:21], off offset:1696
	s_nop 0
	s_nop 0
	s_nop 0
	s_waitcnt lgkmcnt(4)
	v_mfma_f32_16x16x32_bf16 v[20:23], v[204:207], v[2:5], 0
	v_mfma_f32_16x16x32_bf16 v[20:23], v[222:225], v[6:9], v[20:23]
	s_nop 0
	v_mfma_f32_16x16x32_bf16 v[20:23], v[226:229], v[10:13], v[20:23]
	s_nop 0
	v_mfma_f32_16x16x32_bf16 v[20:23], v[230:233], v[14:17], v[20:23]
	s_nop 0
	s_waitcnt vmcnt(6)
	s_nop 5
	v_pk_mul_f32 v[22:23], v[22:23], v[236:237]
	v_pk_mul_f32 v[20:21], v[20:21], v[234:235]
	s_nop 0
	v_cvt_pk_bf16_f32 v20, v20, v21
	v_cvt_pk_bf16_f32 v21, v22, v23
	v_add_co_u32_e32 v22, vcc, 0x7000, v28
	global_store_dwordx2 v[18:19], v[20:21], off offset:1728
	s_nop 0
	v_addc_co_u32_e32 v23, vcc, 0, v29, vcc
	s_nop 0
	s_waitcnt lgkmcnt(0)
	v_mfma_f32_16x16x32_bf16 v[2:5], v[238:241], v[2:5], 0
	s_nop 0
	v_mfma_f32_16x16x32_bf16 v[2:5], v[242:245], v[6:9], v[2:5]
	s_nop 0
	v_mfma_f32_16x16x32_bf16 v[2:5], v[246:249], v[10:13], v[2:5]
	s_nop 0
	v_mfma_f32_16x16x32_bf16 v[2:5], v[52:55], v[14:17], v[2:5]

.LBB0_588:
	s_and_b64 vcc, exec, s[0:1]
	s_cbranch_vccz .LBB0_590
	v_mov_b32_e32 v0, v209
	v_mov_b32_e32 v29, v1
	v_readfirstlane_b32 s0, v0
	s_ashr_i32 s0, s0, 2
	v_and_b32_e32 v21, 15, v0
	v_bfi_b32 v23, -16, s0, v0
	v_bfe_u32 v36, v0, 4, 2
	v_subrev_u32_e32 v0, s56, v23
	v_add_u32_e32 v18, s59, v0
	s_mov_b32 s0, 0x38e38e39
	v_mul_hi_i32 v0, v18, s0
	v_lshrrev_b32_e32 v2, 31, v0
	v_ashrrev_i32_e32 v0, 13, v0
	v_add_u32_e32 v0, v0, v2
	v_mul_i32_i24_e32 v0, 0x9000, v0
	v_sub_u32_e32 v0, v18, v0
	s_mov_b32 s0, 0x8000
	v_cmp_gt_i32_e32 vcc, s0, v0
	v_lshlrev_b32_e32 v28, 4, v36
	v_ashrrev_i32_e32 v19, 31, v18
	v_cndmask_b32_e32 v2, v220, v221, vcc
	v_and_b32_e32 v37, v2, v0
	v_cndmask_b32_e32 v31, v217, v210, vcc
	v_add_u32_e32 v2, -2, v37
	v_add_u32_e32 v3, 2, v37
	v_max_i32_e32 v0, 0, v2
	v_min_u32_e32 v3, v3, v31
	v_sub_u32_e32 v0, v3, v0
	v_cvt_f32_i32_e32 v0, v0
	v_add_u32_e32 v26, 1, v37
	v_lshlrev_b64 v[10:11], 10, v[18:19]
	v_lshlrev_b64 v[18:19], 11, v[18:19]
	v_div_scale_f32 v3, s[0:1], v0, v0, 1.0
	v_rcp_f32_e32 v4, v3
	v_readlane_b32 s0, v253, 62
	v_readlane_b32 s1, v253, 63
	v_fma_f32 v5, -v3, v4, 1.0
	v_fmac_f32_e32 v4, v5, v4
	v_div_scale_f32 v5, vcc, 1.0, v0, 1.0
	v_mul_f32_e32 v6, v5, v4
	v_fma_f32 v7, -v3, v6, v5
	v_fmac_f32_e32 v6, v7, v4
	v_fma_f32 v3, -v3, v6, v5
	v_div_fmas_f32 v3, v3, v4, v6
	v_cmp_lt_u32_e32 vcc, v2, v31
	v_add_u32_e32 v6, -1, v37
	v_lshl_add_u64 v[24:25], s[0:1], 0, v[28:29]
	v_cndmask_b32_e64 v22, 0, 1.0, vcc
	v_cndmask_b32_e32 v2, v37, v2, vcc
	v_cmp_lt_u32_e32 vcc, v6, v31
	v_add_u32_e32 v2, v23, v2
	v_subrev_u32_e32 v2, s56, v2
	v_cndmask_b32_e32 v6, v37, v6, vcc
	v_add_u32_e32 v6, v23, v6
	v_cmp_lt_u32_e64 s[0:1], v26, v31
	v_sub_u32_e32 v2, v2, v37
	v_subrev_u32_e32 v6, s56, v6
	v_cndmask_b32_e64 v26, v37, v26, s[0:1]
	v_add_u32_e32 v2, s59, v2
	v_sub_u32_e32 v6, v6, v37
	v_add_u32_e32 v23, v23, v26
	v_div_fixup_f32 v20, v3, v0, 1.0
	v_ashrrev_i32_e32 v3, 31, v2
	v_add_u32_e32 v6, s59, v6
	v_subrev_u32_e32 v23, s56, v23
	v_lshlrev_b64 v[2:3], 10, v[2:3]
	v_ashrrev_i32_e32 v7, 31, v6
	v_sub_u32_e32 v23, v23, v37
	v_lshl_add_u64 v[14:15], v[24:25], 0, v[2:3]
	v_lshlrev_b64 v[6:7], 10, v[6:7]
	v_add_u32_e32 v26, s59, v23
	global_load_dwordx4 v[2:5], v[14:15], off offset:256
	v_lshl_add_u64 v[34:35], v[24:25], 0, v[6:7]
	v_ashrrev_i32_e32 v27, 31, v26
	global_load_dwordx4 v[6:9], v[34:35], off offset:256
	v_lshl_add_u64 v[16:17], v[24:25], 0, v[10:11]
	v_lshlrev_b64 v[26:27], 10, v[26:27]
	global_load_dwordx4 v[10:13], v[16:17], off offset:256
	v_lshl_add_u64 v[32:33], v[24:25], 0, v[26:27]
	global_load_dwordx4 v[38:41], v[32:33], off offset:256
	global_load_dwordx4 v[92:95], v[14:15], off offset:320
	global_load_dwordx4 v[96:99], v[34:35], off offset:320
	global_load_dwordx4 v[100:103], v[16:17], off offset:320
	global_load_dwordx4 v[104:107], v[32:33], off offset:320
	global_load_dwordx4 v[108:111], v[14:15], off offset:384
	global_load_dwordx4 v[112:115], v[34:35], off offset:384
	global_load_dwordx4 v[116:119], v[16:17], off offset:384
	global_load_dwordx4 v[120:123], v[32:33], off offset:384
	global_load_dwordx4 v[124:127], v[14:15], off offset:448
	global_load_dwordx4 v[128:131], v[34:35], off offset:448
	global_load_dwordx4 v[132:135], v[16:17], off offset:448
	global_load_dwordx4 v[136:139], v[32:33], off offset:448
	v_cndmask_b32_e64 v30, 0, 1.0, vcc
	v_cmp_lt_u32_e32 vcc, v37, v31
	v_cndmask_b32_e64 v24, 0, 1.0, s[0:1]
	s_mov_b64 s[0:1], 0x400
	v_cndmask_b32_e64 v26, 0, 1.0, vcc
	v_lshlrev_b32_e32 v0, 3, v36
	s_waitcnt vmcnt(15)
	v_lshlrev_b32_e32 v42, 16, v2
	v_and_b32_e32 v43, 0xffff0000, v2
	v_pk_fma_f32 v[42:43], v[22:23], v[42:43], 0 op_sel_hi:[0, 1, 0]
	s_waitcnt vmcnt(14)
	v_lshlrev_b32_e32 v44, 16, v6
	v_and_b32_e32 v45, 0xffff0000, v6
	v_pk_fma_f32 v[42:43], v[30:31], v[44:45], v[42:43] op_sel_hi:[0, 1, 1]
	s_waitcnt vmcnt(13)
	v_lshlrev_b32_e32 v44, 16, v10
	v_and_b32_e32 v45, 0xffff0000, v10
	v_pk_fma_f32 v[42:43], v[26:27], v[44:45], v[42:43] op_sel_hi:[0, 1, 1]
	s_waitcnt vmcnt(12)
	v_lshlrev_b32_e32 v46, 16, v38
	v_and_b32_e32 v47, 0xffff0000, v38
	v_pk_fma_f32 v[42:43], v[24:25], v[46:47], v[42:43] op_sel_hi:[0, 1, 1]
	v_pk_fma_f32 v[42:43], v[20:21], v[42:43], v[44:45] op_sel_hi:[0, 1, 1] neg_lo:[0, 0, 1] neg_hi:[0, 0, 1]
	v_cvt_pk_bf16_f32 v2, v42, v43
	v_lshlrev_b32_e32 v42, 16, v3
	v_and_b32_e32 v43, 0xffff0000, v3
	v_pk_fma_f32 v[42:43], v[22:23], v[42:43], 0 op_sel_hi:[0, 1, 0]
	v_lshlrev_b32_e32 v6, 16, v7
	v_and_b32_e32 v7, 0xffff0000, v7
	v_pk_fma_f32 v[6:7], v[30:31], v[6:7], v[42:43] op_sel_hi:[0, 1, 1]
	v_lshlrev_b32_e32 v10, 16, v11
	v_and_b32_e32 v11, 0xffff0000, v11
	v_pk_fma_f32 v[6:7], v[26:27], v[10:11], v[6:7] op_sel_hi:[0, 1, 1]
	v_lshlrev_b32_e32 v38, 16, v39
	v_and_b32_e32 v39, 0xffff0000, v39
	v_pk_fma_f32 v[6:7], v[24:25], v[38:39], v[6:7] op_sel_hi:[0, 1, 1]
	v_pk_fma_f32 v[6:7], v[20:21], v[6:7], v[10:11] op_sel_hi:[0, 1, 1] neg_lo:[0, 0, 1] neg_hi:[0, 0, 1]
	v_cvt_pk_bf16_f32 v3, v6, v7
	v_lshlrev_b32_e32 v6, 16, v4
	v_and_b32_e32 v7, 0xffff0000, v4
	v_pk_fma_f32 v[6:7], v[22:23], v[6:7], 0 op_sel_hi:[0, 1, 0]
	v_lshlrev_b32_e32 v10, 16, v8
	v_and_b32_e32 v11, 0xffff0000, v8
	v_pk_fma_f32 v[6:7], v[30:31], v[10:11], v[6:7] op_sel_hi:[0, 1, 1]
	v_lshlrev_b32_e32 v10, 16, v12
	v_and_b32_e32 v11, 0xffff0000, v12
	v_pk_fma_f32 v[6:7], v[26:27], v[10:11], v[6:7] op_sel_hi:[0, 1, 1]
	v_lshlrev_b32_e32 v38, 16, v40
	v_and_b32_e32 v39, 0xffff0000, v40
	v_pk_fma_f32 v[6:7], v[24:25], v[38:39], v[6:7] op_sel_hi:[0, 1, 1]
	v_pk_fma_f32 v[6:7], v[20:21], v[6:7], v[10:11] op_sel_hi:[0, 1, 1] neg_lo:[0, 0, 1] neg_hi:[0, 0, 1]
	v_cvt_pk_bf16_f32 v4, v6, v7
	v_lshlrev_b32_e32 v6, 16, v5
	v_and_b32_e32 v7, 0xffff0000, v5
	v_pk_fma_f32 v[6:7], v[22:23], v[6:7], 0 op_sel_hi:[0, 1, 0]
	v_lshlrev_b32_e32 v8, 16, v9
	v_and_b32_e32 v9, 0xffff0000, v9
	v_pk_fma_f32 v[6:7], v[30:31], v[8:9], v[6:7] op_sel_hi:[0, 1, 1]
	v_lshlrev_b32_e32 v8, 16, v13
	v_and_b32_e32 v9, 0xffff0000, v13
	v_pk_fma_f32 v[6:7], v[26:27], v[8:9], v[6:7] op_sel_hi:[0, 1, 1]
	v_lshlrev_b32_e32 v10, 16, v41
	v_and_b32_e32 v11, 0xffff0000, v41
	v_pk_fma_f32 v[6:7], v[24:25], v[10:11], v[6:7] op_sel_hi:[0, 1, 1]
	v_pk_fma_f32 v[6:7], v[20:21], v[6:7], v[8:9] op_sel_hi:[0, 1, 1] neg_lo:[0, 0, 1] neg_hi:[0, 0, 1]
	v_cvt_pk_bf16_f32 v5, v6, v7
	s_nop 0
	s_nop 0
	s_nop 0
	s_nop 0
	s_waitcnt vmcnt(11)
	v_lshlrev_b32_e32 v46, 16, v92
	v_and_b32_e32 v47, 0xffff0000, v92
	v_pk_fma_f32 v[46:47], v[22:23], v[46:47], 0 op_sel_hi:[0, 1, 0]
	s_waitcnt vmcnt(10)
	v_lshlrev_b32_e32 v48, 16, v96
	v_and_b32_e32 v49, 0xffff0000, v96
	v_pk_fma_f32 v[46:47], v[30:31], v[48:49], v[46:47] op_sel_hi:[0, 1, 1]
	s_waitcnt vmcnt(9)
	v_lshlrev_b32_e32 v48, 16, v100
	v_and_b32_e32 v49, 0xffff0000, v100
	v_pk_fma_f32 v[46:47], v[26:27], v[48:49], v[46:47] op_sel_hi:[0, 1, 1]
	s_waitcnt vmcnt(8)
	v_lshlrev_b32_e32 v50, 16, v104
	v_and_b32_e32 v51, 0xffff0000, v104
	v_pk_fma_f32 v[46:47], v[24:25], v[50:51], v[46:47] op_sel_hi:[0, 1, 1]
	v_pk_fma_f32 v[46:47], v[20:21], v[46:47], v[48:49] op_sel_hi:[0, 1, 1] neg_lo:[0, 0, 1] neg_hi:[0, 0, 1]
	v_lshlrev_b32_e32 v10, 16, v93
	v_and_b32_e32 v11, 0xffff0000, v93
	v_cvt_pk_bf16_f32 v6, v46, v47
	v_pk_fma_f32 v[10:11], v[22:23], v[10:11], 0 op_sel_hi:[0, 1, 0]
	v_lshlrev_b32_e32 v46, 16, v97
	v_and_b32_e32 v47, 0xffff0000, v97
	v_pk_fma_f32 v[10:11], v[30:31], v[46:47], v[10:11] op_sel_hi:[0, 1, 1]
	v_lshlrev_b32_e32 v38, 16, v101
	v_and_b32_e32 v39, 0xffff0000, v101
	v_pk_fma_f32 v[10:11], v[26:27], v[38:39], v[10:11] op_sel_hi:[0, 1, 1]
	v_lshlrev_b32_e32 v42, 16, v105
	v_and_b32_e32 v43, 0xffff0000, v105
	v_pk_fma_f32 v[10:11], v[24:25], v[42:43], v[10:11] op_sel_hi:[0, 1, 1]
	v_pk_fma_f32 v[10:11], v[20:21], v[10:11], v[38:39] op_sel_hi:[0, 1, 1] neg_lo:[0, 0, 1] neg_hi:[0, 0, 1]
	v_cvt_pk_bf16_f32 v7, v10, v11
	v_lshlrev_b32_e32 v10, 16, v94
	v_and_b32_e32 v11, 0xffff0000, v94
	v_pk_fma_f32 v[10:11], v[22:23], v[10:11], 0 op_sel_hi:[0, 1, 0]
	v_lshlrev_b32_e32 v38, 16, v98
	v_and_b32_e32 v39, 0xffff0000, v98
	v_pk_fma_f32 v[10:11], v[30:31], v[38:39], v[10:11] op_sel_hi:[0, 1, 1]
	v_lshlrev_b32_e32 v38, 16, v102
	v_and_b32_e32 v39, 0xffff0000, v102
	v_pk_fma_f32 v[10:11], v[26:27], v[38:39], v[10:11] op_sel_hi:[0, 1, 1]
	v_lshlrev_b32_e32 v42, 16, v106
	v_and_b32_e32 v43, 0xffff0000, v106
	v_pk_fma_f32 v[10:11], v[24:25], v[42:43], v[10:11] op_sel_hi:[0, 1, 1]
	v_pk_fma_f32 v[10:11], v[20:21], v[10:11], v[38:39] op_sel_hi:[0, 1, 1] neg_lo:[0, 0, 1] neg_hi:[0, 0, 1]
	v_cvt_pk_bf16_f32 v8, v10, v11
	v_lshlrev_b32_e32 v10, 16, v95
	v_and_b32_e32 v11, 0xffff0000, v95
	v_pk_fma_f32 v[10:11], v[22:23], v[10:11], 0 op_sel_hi:[0, 1, 0]
	v_lshlrev_b32_e32 v12, 16, v99
	v_and_b32_e32 v13, 0xffff0000, v99
	v_pk_fma_f32 v[10:11], v[30:31], v[12:13], v[10:11] op_sel_hi:[0, 1, 1]
	v_lshlrev_b32_e32 v12, 16, v103
	v_and_b32_e32 v13, 0xffff0000, v103
	v_pk_fma_f32 v[10:11], v[26:27], v[12:13], v[10:11] op_sel_hi:[0, 1, 1]
	v_lshlrev_b32_e32 v38, 16, v107
	v_and_b32_e32 v39, 0xffff0000, v107
	v_pk_fma_f32 v[10:11], v[24:25], v[38:39], v[10:11] op_sel_hi:[0, 1, 1]
	v_pk_fma_f32 v[10:11], v[20:21], v[10:11], v[12:13] op_sel_hi:[0, 1, 1] neg_lo:[0, 0, 1] neg_hi:[0, 0, 1]
	v_cvt_pk_bf16_f32 v9, v10, v11
	s_nop 0
	s_nop 0
	s_nop 0
	s_nop 0
	s_waitcnt vmcnt(7)
	v_lshlrev_b32_e32 v50, 16, v108
	v_and_b32_e32 v51, 0xffff0000, v108
	v_pk_fma_f32 v[50:51], v[22:23], v[50:51], 0 op_sel_hi:[0, 1, 0]
	s_waitcnt vmcnt(6)
	v_lshlrev_b32_e32 v52, 16, v112
	v_and_b32_e32 v53, 0xffff0000, v112
	v_pk_fma_f32 v[50:51], v[30:31], v[52:53], v[50:51] op_sel_hi:[0, 1, 1]
	s_waitcnt vmcnt(5)
	v_lshlrev_b32_e32 v52, 16, v116
	v_and_b32_e32 v53, 0xffff0000, v116
	v_pk_fma_f32 v[50:51], v[26:27], v[52:53], v[50:51] op_sel_hi:[0, 1, 1]
	s_waitcnt vmcnt(4)
	v_lshlrev_b32_e32 v54, 16, v120
	v_and_b32_e32 v55, 0xffff0000, v120
	v_pk_fma_f32 v[50:51], v[24:25], v[54:55], v[50:51] op_sel_hi:[0, 1, 1]
	v_pk_fma_f32 v[50:51], v[20:21], v[50:51], v[52:53] op_sel_hi:[0, 1, 1] neg_lo:[0, 0, 1] neg_hi:[0, 0, 1]
	v_cvt_pk_bf16_f32 v10, v50, v51
	v_lshlrev_b32_e32 v50, 16, v109
	v_and_b32_e32 v51, 0xffff0000, v109
	v_pk_fma_f32 v[50:51], v[22:23], v[50:51], 0 op_sel_hi:[0, 1, 0]
	v_lshlrev_b32_e32 v38, 16, v113
	v_and_b32_e32 v39, 0xffff0000, v113
	v_pk_fma_f32 v[38:39], v[30:31], v[38:39], v[50:51] op_sel_hi:[0, 1, 1]
	v_lshlrev_b32_e32 v42, 16, v117
	v_and_b32_e32 v43, 0xffff0000, v117
	v_pk_fma_f32 v[38:39], v[26:27], v[42:43], v[38:39] op_sel_hi:[0, 1, 1]
	v_lshlrev_b32_e32 v46, 16, v121
	v_and_b32_e32 v47, 0xffff0000, v121
	v_pk_fma_f32 v[38:39], v[24:25], v[46:47], v[38:39] op_sel_hi:[0, 1, 1]
	v_pk_fma_f32 v[38:39], v[20:21], v[38:39], v[42:43] op_sel_hi:[0, 1, 1] neg_lo:[0, 0, 1] neg_hi:[0, 0, 1]
	v_cvt_pk_bf16_f32 v11, v38, v39
	v_lshlrev_b32_e32 v38, 16, v110
	v_and_b32_e32 v39, 0xffff0000, v110
	v_pk_fma_f32 v[38:39], v[22:23], v[38:39], 0 op_sel_hi:[0, 1, 0]
	v_lshlrev_b32_e32 v42, 16, v114
	v_and_b32_e32 v43, 0xffff0000, v114
	v_pk_fma_f32 v[38:39], v[30:31], v[42:43], v[38:39] op_sel_hi:[0, 1, 1]
	v_lshlrev_b32_e32 v42, 16, v118
	v_and_b32_e32 v43, 0xffff0000, v118
	v_pk_fma_f32 v[38:39], v[26:27], v[42:43], v[38:39] op_sel_hi:[0, 1, 1]
	v_lshlrev_b32_e32 v46, 16, v122
	v_and_b32_e32 v47, 0xffff0000, v122
	v_pk_fma_f32 v[38:39], v[24:25], v[46:47], v[38:39] op_sel_hi:[0, 1, 1]
	v_pk_fma_f32 v[38:39], v[20:21], v[38:39], v[42:43] op_sel_hi:[0, 1, 1] neg_lo:[0, 0, 1] neg_hi:[0, 0, 1]
	v_cvt_pk_bf16_f32 v12, v38, v39
	v_lshlrev_b32_e32 v38, 16, v111
	v_and_b32_e32 v39, 0xffff0000, v111
	v_pk_fma_f32 v[38:39], v[22:23], v[38:39], 0 op_sel_hi:[0, 1, 0]
	v_lshlrev_b32_e32 v40, 16, v115
	v_and_b32_e32 v41, 0xffff0000, v115
	v_pk_fma_f32 v[38:39], v[30:31], v[40:41], v[38:39] op_sel_hi:[0, 1, 1]
	v_lshlrev_b32_e32 v40, 16, v119
	v_and_b32_e32 v41, 0xffff0000, v119
	v_pk_fma_f32 v[38:39], v[26:27], v[40:41], v[38:39] op_sel_hi:[0, 1, 1]
	v_lshlrev_b32_e32 v42, 16, v123
	v_and_b32_e32 v43, 0xffff0000, v123
	v_pk_fma_f32 v[38:39], v[24:25], v[42:43], v[38:39] op_sel_hi:[0, 1, 1]
	v_pk_fma_f32 v[38:39], v[20:21], v[38:39], v[40:41] op_sel_hi:[0, 1, 1] neg_lo:[0, 0, 1] neg_hi:[0, 0, 1]
	v_cvt_pk_bf16_f32 v13, v38, v39
	s_nop 0
	s_nop 0
	s_nop 0
	s_nop 0
	s_nop 0
	s_nop 0
	s_waitcnt vmcnt(3)
	v_lshlrev_b32_e32 v46, 16, v124
	v_and_b32_e32 v47, 0xffff0000, v124
	v_lshlrev_b32_e32 v38, 16, v125
	v_and_b32_e32 v39, 0xffff0000, v125
	s_waitcnt vmcnt(2)
	v_lshlrev_b32_e32 v48, 16, v128
	v_and_b32_e32 v49, 0xffff0000, v128
	v_pk_fma_f32 v[38:39], v[22:23], v[38:39], 0 op_sel_hi:[0, 1, 0]
	v_lshlrev_b32_e32 v42, 16, v129
	v_and_b32_e32 v43, 0xffff0000, v129
	v_pk_fma_f32 v[38:39], v[30:31], v[42:43], v[38:39] op_sel_hi:[0, 1, 1]
	s_waitcnt vmcnt(1)
	v_lshlrev_b32_e32 v42, 16, v133
	v_and_b32_e32 v43, 0xffff0000, v133
	s_waitcnt vmcnt(0)
	v_lshlrev_b32_e32 v50, 16, v136
	v_and_b32_e32 v51, 0xffff0000, v136
	v_pk_fma_f32 v[38:39], v[26:27], v[42:43], v[38:39] op_sel_hi:[0, 1, 1]
	v_lshlrev_b32_e32 v32, 16, v137
	v_and_b32_e32 v33, 0xffff0000, v137
	v_pk_fma_f32 v[32:33], v[24:25], v[32:33], v[38:39] op_sel_hi:[0, 1, 1]
	v_pk_fma_f32 v[32:33], v[20:21], v[32:33], v[42:43] op_sel_hi:[0, 1, 1] neg_lo:[0, 0, 1] neg_hi:[0, 0, 1]
	v_cvt_pk_bf16_f32 v15, v32, v33
	v_lshlrev_b32_e32 v32, 16, v126
	v_and_b32_e32 v33, 0xffff0000, v126
	v_pk_fma_f32 v[32:33], v[22:23], v[32:33], 0 op_sel_hi:[0, 1, 0]
	v_lshlrev_b32_e32 v38, 16, v130
	v_and_b32_e32 v39, 0xffff0000, v130
	v_pk_fma_f32 v[32:33], v[30:31], v[38:39], v[32:33] op_sel_hi:[0, 1, 1]
	v_lshlrev_b32_e32 v38, 16, v134
	v_and_b32_e32 v39, 0xffff0000, v134
	v_pk_fma_f32 v[32:33], v[26:27], v[38:39], v[32:33] op_sel_hi:[0, 1, 1]
	v_lshlrev_b32_e32 v42, 16, v138
	v_and_b32_e32 v43, 0xffff0000, v138
	v_pk_fma_f32 v[32:33], v[24:25], v[42:43], v[32:33] op_sel_hi:[0, 1, 1]
	v_pk_fma_f32 v[32:33], v[20:21], v[32:33], v[38:39] op_sel_hi:[0, 1, 1] neg_lo:[0, 0, 1] neg_hi:[0, 0, 1]
	v_cvt_pk_bf16_f32 v16, v32, v33
	v_lshlrev_b32_e32 v32, 16, v127
	v_and_b32_e32 v33, 0xffff0000, v127
	v_pk_fma_f32 v[46:47], v[22:23], v[46:47], 0 op_sel_hi:[0, 1, 0]
	v_pk_fma_f32 v[22:23], v[22:23], v[32:33], 0 op_sel_hi:[0, 1, 0]
	v_lshlrev_b32_e32 v32, 16, v131
	v_and_b32_e32 v33, 0xffff0000, v131
	v_pk_fma_f32 v[46:47], v[30:31], v[48:49], v[46:47] op_sel_hi:[0, 1, 1]
	v_lshlrev_b32_e32 v48, 16, v132
	v_and_b32_e32 v49, 0xffff0000, v132
	v_pk_fma_f32 v[22:23], v[30:31], v[32:33], v[22:23] op_sel_hi:[0, 1, 1]
	v_lshlrev_b32_e32 v30, 16, v135
	v_and_b32_e32 v31, 0xffff0000, v135
	v_pk_fma_f32 v[46:47], v[26:27], v[48:49], v[46:47] op_sel_hi:[0, 1, 1]
	v_pk_fma_f32 v[22:23], v[26:27], v[30:31], v[22:23] op_sel_hi:[0, 1, 1]
	v_lshlrev_b32_e32 v26, 16, v139
	v_and_b32_e32 v27, 0xffff0000, v139
	v_pk_fma_f32 v[22:23], v[24:25], v[26:27], v[22:23] op_sel_hi:[0, 1, 1]
	v_pk_fma_f32 v[22:23], v[20:21], v[22:23], v[30:31] op_sel_hi:[0, 1, 1] neg_lo:[0, 0, 1] neg_hi:[0, 0, 1]
	v_cvt_pk_bf16_f32 v17, v22, v23
	v_lshl_add_u64 v[22:23], s[36:37], 0, v[28:29]
	v_lshl_add_u64 v[32:33], s[84:85], 0, v[18:19]
	v_lshlrev_b32_e32 v18, 8, v21
	v_mov_b32_e32 v19, v1
	v_pk_fma_f32 v[46:47], v[24:25], v[50:51], v[46:47] op_sel_hi:[0, 1, 1]
	v_lshl_add_u64 v[30:31], v[22:23], 0, v[18:19]
	v_pk_fma_f32 v[46:47], v[20:21], v[46:47], v[48:49] op_sel_hi:[0, 1, 1] neg_lo:[0, 0, 1] neg_hi:[0, 0, 1]
	v_add_co_u32_e32 v56, vcc, 0x1000, v30
	s_nop 1
	v_addc_co_u32_e32 v57, vcc, 0, v31, vcc
	v_add_co_u32_e32 v58, vcc, 0x3000, v30
	s_nop 1
	v_addc_co_u32_e32 v59, vcc, 0, v31, vcc
	v_add_co_u32_e32 v60, vcc, 0x5000, v30
	s_nop 1
	v_addc_co_u32_e32 v61, vcc, 0, v31, vcc
	v_add_co_u32_e32 v62, vcc, 0x7000, v30
	s_nop 1
	v_addc_co_u32_e32 v63, vcc, 0, v31, vcc
	global_load_dwordx4 v[100:103], v28, s[30:31] offset:512
	global_load_dwordx4 v[120:123], v28, s[30:31] offset:576
	global_load_dwordx4 v[140:143], v28, s[30:31] offset:640
	global_load_dwordx4 v[160:163], v28, s[30:31] offset:704
	global_load_dwordx4 v[180:183], v28, s[30:31] offset:768
	global_load_dwordx4 v[200:203], v28, s[30:31] offset:832
	global_load_dwordx4 v[234:237], v28, s[30:31] offset:896
	v_and_b32_e32 v56, 15, v209
	v_bfe_u32 v57, v209, 4, 2
	v_mul_u32_u24_e32 v56, 0x110, v56
	v_lshl_add_u32 v56, v57, 4, v56
	v_add_u32_e32 v56, 0x8800, v56
	ds_read_b128 v[84:87], v56 offset:0
	ds_read_b128 v[88:91], v56 offset:64
	ds_read_b128 v[92:95], v56 offset:128
	ds_read_b128 v[96:99], v56 offset:192
	ds_read_b128 v[104:107], v56 offset:4352
	ds_read_b128 v[108:111], v56 offset:4416
	ds_read_b128 v[112:115], v56 offset:4480
	ds_read_b128 v[116:119], v56 offset:4544
	ds_read_b128 v[124:127], v56 offset:8704
	ds_read_b128 v[128:131], v56 offset:8768
	ds_read_b128 v[132:135], v56 offset:8832
	ds_read_b128 v[136:139], v56 offset:8896
	ds_read_b128 v[144:147], v56 offset:13056
	ds_read_b128 v[148:151], v56 offset:13120
	ds_read_b128 v[152:155], v56 offset:13184
	ds_read_b128 v[156:159], v56 offset:13248
	s_nop 0
	s_nop 0
	s_waitcnt lgkmcnt(12)
	v_mfma_f32_16x16x32_bf16 v[18:21], v[84:87], v[2:5], 0
	v_cvt_pk_bf16_f32 v14, v46, v47
	v_lshl_add_u64 v[26:27], v[32:33], 0, s[0:1]
	s_movk_i32 s0, 0x1000
	v_mfma_f32_16x16x32_bf16 v[18:21], v[88:91], v[6:9], v[18:21]
	s_nop 0
	v_mfma_f32_16x16x32_bf16 v[18:21], v[92:95], v[10:13], v[18:21]
	s_nop 0
	v_mfma_f32_16x16x32_bf16 v[18:21], v[96:99], v[14:17], v[18:21]
	s_nop 0
	s_waitcnt vmcnt(6)
	s_nop 5
	v_pk_mul_f32 v[20:21], v[20:21], v[102:103]
	v_add_co_u32_e32 v24, vcc, s0, v30
	v_pk_mul_f32 v[18:19], v[18:19], v[100:101]
	s_nop 0
	v_addc_co_u32_e32 v25, vcc, 0, v31, vcc
	s_movk_i32 s0, 0x2000
	v_cvt_pk_bf16_f32 v22, v18, v19
	v_cvt_pk_bf16_f32 v23, v20, v21
	v_lshl_add_u64 v[18:19], v[32:33], 0, v[0:1]
	v_add_co_u32_e32 v38, vcc, s0, v30
	global_store_dwordx2 v[18:19], v[22:23], off offset:1280
	s_nop 0
	v_addc_co_u32_e32 v39, vcc, 0, v31, vcc
	s_nop 0
	s_nop 0
	s_waitcnt lgkmcnt(8)
	v_mfma_f32_16x16x32_bf16 v[20:23], v[104:107], v[2:5], 0
	s_movk_i32 s0, 0x3000
	v_mov_b32_e32 v0, 0xf0
	v_lshl_or_b32 v0, v36, 2, v0
	v_mfma_f32_16x16x32_bf16 v[20:23], v[108:111], v[6:9], v[20:23]
	s_nop 0
	v_mfma_f32_16x16x32_bf16 v[20:23], v[112:115], v[10:13], v[20:23]
	s_nop 0
	v_add_co_u32_e32 v24, vcc, s0, v30
	v_mfma_f32_16x16x32_bf16 v[20:23], v[116:119], v[14:17], v[20:23]
	s_nop 0
	v_addc_co_u32_e32 v25, vcc, 0, v31, vcc
	s_movk_i32 s0, 0x4000
	s_waitcnt vmcnt(6)
	s_nop 3
	v_pk_mul_f32 v[22:23], v[22:23], v[122:123]
	v_pk_mul_f32 v[20:21], v[20:21], v[120:121]
	s_nop 0
	v_cvt_pk_bf16_f32 v20, v20, v21
	v_cvt_pk_bf16_f32 v21, v22, v23
	global_store_dwordx2 v[18:19], v[20:21], off offset:1312
	s_nop 0
	s_nop 0
	s_nop 0
	s_waitcnt lgkmcnt(4)
	v_mfma_f32_16x16x32_bf16 v[20:23], v[124:127], v[2:5], 0
	v_mfma_f32_16x16x32_bf16 v[20:23], v[128:131], v[6:9], v[20:23]
	s_nop 0
	v_mfma_f32_16x16x32_bf16 v[20:23], v[132:135], v[10:13], v[20:23]
	s_nop 0
	v_add_co_u32_e32 v38, vcc, s0, v30
	v_mfma_f32_16x16x32_bf16 v[20:23], v[136:139], v[14:17], v[20:23]
	s_nop 0
	v_addc_co_u32_e32 v39, vcc, 0, v31, vcc
	s_movk_i32 s0, 0x5000
	s_waitcnt vmcnt(6)
	s_nop 3
	v_pk_mul_f32 v[22:23], v[22:23], v[142:143]
	v_pk_mul_f32 v[20:21], v[20:21], v[140:141]
	s_nop 0
	v_cvt_pk_bf16_f32 v20, v20, v21
	v_cvt_pk_bf16_f32 v21, v22, v23
	global_store_dwordx2 v[18:19], v[20:21], off offset:1344
	s_nop 0
	s_nop 0
	s_nop 0
	s_waitcnt lgkmcnt(0)
	v_mfma_f32_16x16x32_bf16 v[20:23], v[144:147], v[2:5], 0
	v_mfma_f32_16x16x32_bf16 v[20:23], v[148:151], v[6:9], v[20:23]
	s_nop 0
	v_mfma_f32_16x16x32_bf16 v[20:23], v[152:155], v[10:13], v[20:23]
	s_nop 0
	v_add_co_u32_e32 v24, vcc, s0, v30
	v_mfma_f32_16x16x32_bf16 v[20:23], v[156:159], v[14:17], v[20:23]
	s_nop 0
	v_addc_co_u32_e32 v25, vcc, 0, v31, vcc
	s_movk_i32 s0, 0x6000
	s_waitcnt vmcnt(6)
	s_nop 3
	v_pk_mul_f32 v[22:23], v[22:23], v[162:163]
	v_pk_mul_f32 v[20:21], v[20:21], v[160:161]
	s_nop 0
	v_cvt_pk_bf16_f32 v20, v20, v21
	v_cvt_pk_bf16_f32 v21, v22, v23
	global_store_dwordx2 v[18:19], v[20:21], off offset:1376
	s_nop 0
	s_nop 0
	s_nop 0
	ds_read_b128 v[164:167], v56 offset:17408
	ds_read_b128 v[168:171], v56 offset:17472
	ds_read_b128 v[172:175], v56 offset:17536
	ds_read_b128 v[176:179], v56 offset:17600
	ds_read_b128 v[184:187], v56 offset:21760
	ds_read_b128 v[188:191], v56 offset:21824
	ds_read_b128 v[192:195], v56 offset:21888
	ds_read_b128 v[196:199], v56 offset:21952
	ds_read_b128 v[204:207], v56 offset:26112
	ds_read_b128 v[222:225], v56 offset:26176
	ds_read_b128 v[226:229], v56 offset:26240
	ds_read_b128 v[230:233], v56 offset:26304
	ds_read_b128 v[238:241], v56 offset:30464
	ds_read_b128 v[242:245], v56 offset:30528
	ds_read_b128 v[246:249], v56 offset:30592
	ds_read_b128 v[52:55], v56 offset:30656
	s_waitcnt lgkmcnt(12)
	v_mfma_f32_16x16x32_bf16 v[20:23], v[164:167], v[2:5], 0
	v_mfma_f32_16x16x32_bf16 v[20:23], v[168:171], v[6:9], v[20:23]
	s_nop 0
	v_mfma_f32_16x16x32_bf16 v[20:23], v[172:175], v[10:13], v[20:23]
	s_nop 0
	v_add_co_u32_e32 v38, vcc, s0, v30
	v_mfma_f32_16x16x32_bf16 v[20:23], v[176:179], v[14:17], v[20:23]
	s_nop 0
	v_addc_co_u32_e32 v39, vcc, 0, v31, vcc
	s_waitcnt vmcnt(6)
	s_nop 4
	v_pk_mul_f32 v[22:23], v[22:23], v[182:183]
	v_pk_mul_f32 v[20:21], v[20:21], v[180:181]
	s_nop 0
	v_cvt_pk_bf16_f32 v20, v20, v21
	v_cvt_pk_bf16_f32 v21, v22, v23
	global_store_dwordx2 v[18:19], v[20:21], off offset:1408
	s_nop 0
	s_nop 0
	s_nop 0
	s_waitcnt lgkmcnt(8)
	v_mfma_f32_16x16x32_bf16 v[20:23], v[184:187], v[2:5], 0
	v_mfma_f32_16x16x32_bf16 v[20:23], v[188:191], v[6:9], v[20:23]
	s_nop 0
	v_mfma_f32_16x16x32_bf16 v[20:23], v[192:195], v[10:13], v[20:23]
	s_nop 0
	v_mfma_f32_16x16x32_bf16 v[20:23], v[196:199], v[14:17], v[20:23]
	s_nop 0
	s_waitcnt vmcnt(6)
	s_nop 5
	v_pk_mul_f32 v[22:23], v[22:23], v[202:203]
	v_pk_mul_f32 v[20:21], v[20:21], v[200:201]
	s_nop 0
	v_cvt_pk_bf16_f32 v20, v20, v21
	v_cvt_pk_bf16_f32 v21, v22, v23
	global_store_dwordx2 v[18:19], v[20:21], off offset:1440
	s_nop 0
	s_nop 0
	s_nop 0
	s_waitcnt lgkmcnt(4)
	v_mfma_f32_16x16x32_bf16 v[20:23], v[204:207], v[2:5], 0
	v_mfma_f32_16x16x32_bf16 v[20:23], v[222:225], v[6:9], v[20:23]
	s_nop 0
	v_mfma_f32_16x16x32_bf16 v[20:23], v[226:229], v[10:13], v[20:23]
	s_nop 0
	v_mfma_f32_16x16x32_bf16 v[20:23], v[230:233], v[14:17], v[20:23]
	s_nop 0
	s_waitcnt vmcnt(6)
	s_nop 5
	v_pk_mul_f32 v[22:23], v[22:23], v[236:237]
	v_pk_mul_f32 v[20:21], v[20:21], v[234:235]
	s_nop 0
	v_cvt_pk_bf16_f32 v20, v20, v21
	v_cvt_pk_bf16_f32 v21, v22, v23
	v_add_co_u32_e32 v22, vcc, 0x7000, v30
	global_store_dwordx2 v[18:19], v[20:21], off offset:1472
	s_nop 0
	v_addc_co_u32_e32 v23, vcc, 0, v31, vcc
	s_nop 0
	s_waitcnt lgkmcnt(0)
	v_mfma_f32_16x16x32_bf16 v[2:5], v[238:241], v[2:5], 0
	s_nop 0
	v_mfma_f32_16x16x32_bf16 v[2:5], v[242:245], v[6:9], v[2:5]
	s_nop 0
	v_mfma_f32_16x16x32_bf16 v[2:5], v[246:249], v[10:13], v[2:5]
	s_nop 0
	v_mfma_f32_16x16x32_bf16 v[2:5], v[52:55], v[14:17], v[2:5]

.LBB0_592:
	v_mov_b32_e32 v0, v209
	s_mul_i32 s6, s56, s16
	v_readfirstlane_b32 s0, v0
	s_ashr_i32 s0, s0, 2
	v_and_b32_e32 v85, 15, v0
	v_bfi_b32 v64, -16, s0, v0
	v_bfe_u32 v83, v0, 4, 2
	v_subrev_u32_e32 v0, s6, v64
	v_add_u32_e32 v80, s59, v0
	s_mov_b32 s0, 0x38e38e39
	v_mul_hi_i32 v0, v80, s0
	v_lshrrev_b32_e32 v2, 31, v0
	v_ashrrev_i32_e32 v0, 13, v0
	v_add_u32_e32 v0, v0, v2
	v_mul_i32_i24_e32 v0, 0x9000, v0
	v_sub_u32_e32 v0, v80, v0
	s_mov_b32 s0, 0x8000
	v_cmp_gt_i32_e32 vcc, s0, v0
	v_lshlrev_b32_e32 v78, 4, v83
	v_mov_b32_e32 v79, v1
	v_cndmask_b32_e32 v2, v220, v221, vcc
	v_and_b32_e32 v88, v2, v0
	v_cndmask_b32_e32 v87, v217, v210, vcc
	v_add_u32_e32 v4, -8, v88
	v_add_u32_e32 v2, 8, v88
	v_max_i32_e32 v0, 0, v4
	v_min_u32_e32 v2, v2, v87
	v_sub_u32_e32 v0, v2, v0
	v_cvt_f32_i32_e32 v0, v0
	v_add_u32_e32 v10, 1, v88
	v_add_u32_e32 v50, 4, v88
	v_cmp_lt_u32_e64 s[14:15], v50, v87
	v_div_scale_f32 v2, s[0:1], v0, v0, 1.0
	v_rcp_f32_e32 v3, v2
	v_readlane_b32 s0, v253, 62
	v_readlane_b32 s1, v253, 63
	v_add_u32_e32 v54, 5, v88
	v_fma_f32 v5, -v2, v3, 1.0
	v_fmac_f32_e32 v3, v5, v3
	v_div_scale_f32 v5, vcc, 1.0, v0, 1.0
	v_mul_f32_e32 v6, v5, v3
	v_fma_f32 v7, -v2, v6, v5
	v_fmac_f32_e32 v6, v7, v3
	v_fma_f32 v2, -v2, v6, v5
	v_div_fmas_f32 v2, v2, v3, v6
	v_cmp_lt_u32_e32 vcc, v4, v87
	v_lshl_add_u64 v[62:63], s[0:1], 0, v[78:79]
	v_cmp_lt_u32_e64 s[0:1], v10, v87
	v_cndmask_b32_e32 v4, v88, v4, vcc
	v_add_u32_e32 v4, v64, v4
	v_subrev_u32_e32 v4, s6, v4
	v_sub_u32_e32 v4, v4, v88
	v_add_u32_e32 v4, s59, v4
	v_ashrrev_i32_e32 v5, 31, v4
	v_lshlrev_b64 v[4:5], 10, v[4:5]
	v_lshl_add_u64 v[126:127], v[62:63], 0, v[4:5]
	v_add_u32_e32 v4, -7, v88
	v_cmp_lt_u32_e64 s[8:9], v4, v87
	v_cndmask_b32_e64 v10, v88, v10, s[0:1]
	v_add_u32_e32 v10, v64, v10
	v_cndmask_b32_e64 v4, v88, v4, s[8:9]
	v_add_u32_e32 v4, v64, v4
	v_subrev_u32_e32 v4, s6, v4
	v_sub_u32_e32 v4, v4, v88
	v_add_u32_e32 v4, s59, v4
	v_ashrrev_i32_e32 v5, 31, v4
	v_lshlrev_b64 v[4:5], 10, v[4:5]
	v_lshl_add_u64 v[128:129], v[62:63], 0, v[4:5]
	v_add_u32_e32 v4, -6, v88
	v_cmp_lt_u32_e64 s[12:13], v4, v87
	v_subrev_u32_e32 v10, s6, v10
	v_sub_u32_e32 v10, v10, v88
	v_cndmask_b32_e64 v4, v88, v4, s[12:13]
	v_add_u32_e32 v4, v64, v4
	v_subrev_u32_e32 v4, s6, v4
	v_sub_u32_e32 v4, v4, v88
	v_add_u32_e32 v4, s59, v4
	v_ashrrev_i32_e32 v5, 31, v4
	v_lshlrev_b64 v[4:5], 10, v[4:5]
	v_lshl_add_u64 v[130:131], v[62:63], 0, v[4:5]
	v_add_u32_e32 v4, -5, v88
	v_cmp_lt_u32_e64 s[16:17], v4, v87
	v_add_u32_e32 v10, s59, v10
	v_ashrrev_i32_e32 v11, 31, v10
	v_cndmask_b32_e64 v4, v88, v4, s[16:17]
	v_add_u32_e32 v4, v64, v4
	v_subrev_u32_e32 v4, s6, v4
	v_sub_u32_e32 v4, v4, v88
	v_add_u32_e32 v4, s59, v4
	v_ashrrev_i32_e32 v5, 31, v4
	v_lshlrev_b64 v[4:5], 10, v[4:5]
	v_lshl_add_u64 v[132:133], v[62:63], 0, v[4:5]
	v_add_u32_e32 v4, -4, v88
	v_cmp_lt_u32_e64 s[20:21], v4, v87
	v_lshlrev_b64 v[10:11], 10, v[10:11]
	v_lshl_add_u64 v[76:77], v[62:63], 0, v[10:11]
	v_cndmask_b32_e64 v4, v88, v4, s[20:21]
	v_add_u32_e32 v4, v64, v4
	v_subrev_u32_e32 v4, s6, v4
	v_sub_u32_e32 v4, v4, v88
	v_add_u32_e32 v4, s59, v4
	v_ashrrev_i32_e32 v5, 31, v4
	v_lshlrev_b64 v[4:5], 10, v[4:5]
	v_lshl_add_u64 v[134:135], v[62:63], 0, v[4:5]
	v_add_u32_e32 v4, -3, v88
	v_cmp_lt_u32_e64 s[24:25], v4, v87
	v_add_u32_e32 v10, 2, v88
	global_load_dwordx4 v[6:9], v[126:127], off offset:768
	v_cndmask_b32_e64 v4, v88, v4, s[24:25]
	v_add_u32_e32 v4, v64, v4
	v_subrev_u32_e32 v4, s6, v4
	v_sub_u32_e32 v4, v4, v88
	v_add_u32_e32 v4, s59, v4
	v_ashrrev_i32_e32 v5, 31, v4
	v_lshlrev_b64 v[4:5], 10, v[4:5]
	v_lshl_add_u64 v[136:137], v[62:63], 0, v[4:5]
	v_add_u32_e32 v4, -2, v88
	v_cmp_lt_u32_e64 s[28:29], v4, v87
	v_cmp_lt_u32_e64 s[4:5], v10, v87
	global_load_dwordx4 v[14:17], v[128:129], off offset:768
	global_load_dwordx4 v[18:21], v[130:131], off offset:768
	v_cndmask_b32_e64 v4, v88, v4, s[28:29]
	v_add_u32_e32 v4, v64, v4
	v_subrev_u32_e32 v4, s6, v4
	v_sub_u32_e32 v4, v4, v88
	v_add_u32_e32 v4, s59, v4
	v_cndmask_b32_e64 v10, v88, v10, s[4:5]
	v_ashrrev_i32_e32 v5, 31, v4
	v_add_u32_e32 v10, v64, v10
	global_load_dwordx4 v[22:25], v[132:133], off offset:768
	global_load_dwordx4 v[26:29], v[134:135], off offset:768
	v_lshlrev_b64 v[4:5], 10, v[4:5]
	v_subrev_u32_e32 v10, s6, v10
	v_lshl_add_u64 v[138:139], v[62:63], 0, v[4:5]
	v_add_u32_e32 v4, -1, v88
	v_sub_u32_e32 v10, v10, v88
	v_cndmask_b32_e64 v84, 0, 1.0, vcc
	global_load_dwordx4 v[30:33], v[136:137], off offset:768
	global_load_dwordx4 v[34:37], v[138:139], off offset:768
	v_cmp_lt_u32_e32 vcc, v4, v87
	v_add_u32_e32 v10, s59, v10
	v_ashrrev_i32_e32 v11, 31, v10
	v_cndmask_b32_e32 v4, v88, v4, vcc
	v_add_u32_e32 v4, v64, v4
	v_lshlrev_b64 v[10:11], 10, v[10:11]
	v_subrev_u32_e32 v4, s6, v4
	v_lshl_add_u64 v[74:75], v[62:63], 0, v[10:11]
	v_add_u32_e32 v10, 3, v88
	v_sub_u32_e32 v4, v4, v88
	v_cmp_lt_u32_e64 s[10:11], v10, v87
	v_add_u32_e32 v4, s59, v4
	v_ashrrev_i32_e32 v5, 31, v4
	v_cndmask_b32_e64 v10, v88, v10, s[10:11]
	v_add_u32_e32 v10, v64, v10
	v_cndmask_b32_e64 v50, v88, v50, s[14:15]
	v_cmp_lt_u32_e64 s[18:19], v54, v87
	v_add_u32_e32 v58, 6, v88
	v_ashrrev_i32_e32 v81, 31, v80
	v_lshlrev_b64 v[4:5], 10, v[4:5]
	v_subrev_u32_e32 v10, s6, v10
	v_add_u32_e32 v50, v64, v50
	v_cndmask_b32_e64 v54, v88, v54, s[18:19]
	v_cmp_lt_u32_e64 s[22:23], v58, v87
	v_add_u32_e32 v65, 7, v88
	v_div_fixup_f32 v82, v2, v0, 1.0
	v_lshlrev_b64 v[2:3], 10, v[80:81]
	v_lshl_add_u64 v[122:123], v[62:63], 0, v[4:5]
	v_sub_u32_e32 v10, v10, v88
	v_subrev_u32_e32 v50, s6, v50
	v_add_u32_e32 v54, v64, v54
	v_cndmask_b32_e64 v58, v88, v58, s[22:23]
	v_cmp_lt_u32_e64 s[26:27], v65, v87
	global_load_dwordx4 v[38:41], v[122:123], off offset:768
	v_lshl_add_u64 v[124:125], v[62:63], 0, v[2:3]
	v_add_u32_e32 v10, s59, v10
	v_sub_u32_e32 v50, v50, v88
	v_subrev_u32_e32 v54, s6, v54
	v_add_u32_e32 v58, v64, v58
	v_cndmask_b32_e64 v65, v88, v65, s[26:27]
	global_load_dwordx4 v[2:5], v[124:125], off offset:768
	v_ashrrev_i32_e32 v11, 31, v10
	v_add_u32_e32 v50, s59, v50
	v_sub_u32_e32 v54, v54, v88
	v_subrev_u32_e32 v58, s6, v58
	v_add_u32_e32 v64, v64, v65
	global_load_dwordx4 v[42:45], v[76:77], off offset:768
	global_load_dwordx4 v[46:49], v[74:75], off offset:768
	v_lshlrev_b64 v[10:11], 10, v[10:11]
	v_ashrrev_i32_e32 v51, 31, v50
	v_add_u32_e32 v54, s59, v54
	v_sub_u32_e32 v58, v58, v88
	v_subrev_u32_e32 v64, s6, v64
	v_lshl_add_u64 v[70:71], v[62:63], 0, v[10:11]
	v_lshlrev_b64 v[50:51], 10, v[50:51]
	v_ashrrev_i32_e32 v55, 31, v54
	v_add_u32_e32 v58, s59, v58
	v_sub_u32_e32 v64, v64, v88
	global_load_dwordx4 v[10:13], v[70:71], off offset:768
	v_lshl_add_u64 v[72:73], v[62:63], 0, v[50:51]
	v_lshlrev_b64 v[54:55], 10, v[54:55]
	v_ashrrev_i32_e32 v59, 31, v58
	v_add_u32_e32 v64, s59, v64
	global_load_dwordx4 v[50:53], v[72:73], off offset:768
	v_lshl_add_u64 v[116:117], v[62:63], 0, v[54:55]
	v_lshlrev_b64 v[58:59], 10, v[58:59]
	v_ashrrev_i32_e32 v65, 31, v64
	global_load_dwordx4 v[54:57], v[116:117], off offset:768
	v_lshl_add_u64 v[118:119], v[62:63], 0, v[58:59]
	v_lshlrev_b64 v[64:65], 10, v[64:65]
	global_load_dwordx4 v[58:61], v[118:119], off offset:768
	v_lshl_add_u64 v[120:121], v[62:63], 0, v[64:65]
	global_load_dwordx4 v[62:65], v[120:121], off offset:768
	global_load_dwordx4 v[148:151], v[126:127], off offset:832
	global_load_dwordx4 v[152:155], v[128:129], off offset:832
	global_load_dwordx4 v[156:159], v[130:131], off offset:832
	global_load_dwordx4 v[160:163], v[132:133], off offset:832
	global_load_dwordx4 v[164:167], v[134:135], off offset:832
	global_load_dwordx4 v[168:171], v[136:137], off offset:832
	global_load_dwordx4 v[172:175], v[138:139], off offset:832
	global_load_dwordx4 v[176:179], v[122:123], off offset:832
	global_load_dwordx4 v[180:183], v[124:125], off offset:832
	global_load_dwordx4 v[184:187], v[76:77], off offset:832
	global_load_dwordx4 v[188:191], v[74:75], off offset:832
	global_load_dwordx4 v[192:195], v[70:71], off offset:832
	global_load_dwordx4 v[196:199], v[72:73], off offset:832
	global_load_dwordx4 v[200:203], v[116:117], off offset:832
	global_load_dwordx4 v[204:207], v[118:119], off offset:832
	global_load_dwordx4 v[222:225], v[120:121], off offset:832
	global_load_dwordx4 v[226:229], v[126:127], off offset:896
	global_load_dwordx4 v[230:233], v[128:129], off offset:896
	global_load_dwordx4 v[234:237], v[130:131], off offset:896
	global_load_dwordx4 v[238:241], v[132:133], off offset:896
	global_load_dwordx4 v[242:245], v[134:135], off offset:896
	global_load_dwordx4 v[246:249], v[136:137], off offset:896
	s_waitcnt vmcnt(37)
	v_lshlrev_b32_e32 v66, 16, v6
	v_and_b32_e32 v67, 0xffff0000, v6
	v_lshlrev_b32_e32 v6, 16, v7
	v_and_b32_e32 v7, 0xffff0000, v7
	v_cndmask_b32_e64 v114, 0, 1.0, s[8:9]
	s_waitcnt vmcnt(36)
	v_lshlrev_b32_e32 v68, 16, v14
	v_and_b32_e32 v69, 0xffff0000, v14
	v_pk_fma_f32 v[6:7], v[84:85], v[6:7], 0 op_sel_hi:[0, 1, 0]
	v_lshlrev_b32_e32 v14, 16, v15
	v_and_b32_e32 v15, 0xffff0000, v15
	v_cndmask_b32_e64 v112, 0, 1.0, s[12:13]
	v_pk_fma_f32 v[6:7], v[114:115], v[14:15], v[6:7] op_sel_hi:[0, 1, 1]
	s_waitcnt vmcnt(35)
	v_lshlrev_b32_e32 v14, 16, v19
	v_and_b32_e32 v15, 0xffff0000, v19
	v_cndmask_b32_e64 v110, 0, 1.0, s[16:17]
	v_pk_fma_f32 v[6:7], v[112:113], v[14:15], v[6:7] op_sel_hi:[0, 1, 1]
	s_waitcnt vmcnt(34)
	v_lshlrev_b32_e32 v14, 16, v23
	v_and_b32_e32 v15, 0xffff0000, v23
	v_cndmask_b32_e64 v108, 0, 1.0, s[20:21]
	v_pk_fma_f32 v[6:7], v[110:111], v[14:15], v[6:7] op_sel_hi:[0, 1, 1]
	s_waitcnt vmcnt(33)
	v_lshlrev_b32_e32 v14, 16, v27
	v_and_b32_e32 v15, 0xffff0000, v27
	v_cndmask_b32_e64 v106, 0, 1.0, s[24:25]
	v_pk_fma_f32 v[6:7], v[108:109], v[14:15], v[6:7] op_sel_hi:[0, 1, 1]
	s_waitcnt vmcnt(32)
	v_lshlrev_b32_e32 v14, 16, v31
	v_and_b32_e32 v15, 0xffff0000, v31
	v_cndmask_b32_e64 v104, 0, 1.0, s[28:29]
	v_pk_fma_f32 v[6:7], v[106:107], v[14:15], v[6:7] op_sel_hi:[0, 1, 1]
	s_waitcnt vmcnt(31)
	v_lshlrev_b32_e32 v14, 16, v35
	v_and_b32_e32 v15, 0xffff0000, v35
	v_pk_fma_f32 v[66:67], v[84:85], v[66:67], 0 op_sel_hi:[0, 1, 0]
	v_pk_fma_f32 v[6:7], v[104:105], v[14:15], v[6:7] op_sel_hi:[0, 1, 1]
	v_lshlrev_b32_e32 v14, 16, v8
	v_and_b32_e32 v15, 0xffff0000, v8
	v_lshlrev_b32_e32 v8, 16, v9
	v_and_b32_e32 v9, 0xffff0000, v9
	v_pk_fma_f32 v[66:67], v[114:115], v[68:69], v[66:67] op_sel_hi:[0, 1, 1]
	v_lshlrev_b32_e32 v68, 16, v18
	v_and_b32_e32 v69, 0xffff0000, v18
	v_lshlrev_b32_e32 v18, 16, v16
	v_and_b32_e32 v19, 0xffff0000, v16
	v_pk_fma_f32 v[8:9], v[84:85], v[8:9], 0 op_sel_hi:[0, 1, 0]
	v_lshlrev_b32_e32 v16, 16, v17
	v_and_b32_e32 v17, 0xffff0000, v17
	v_pk_fma_f32 v[8:9], v[114:115], v[16:17], v[8:9] op_sel_hi:[0, 1, 1]
	v_lshlrev_b32_e32 v16, 16, v21
	v_and_b32_e32 v17, 0xffff0000, v21
	v_pk_fma_f32 v[66:67], v[112:113], v[68:69], v[66:67] op_sel_hi:[0, 1, 1]
	v_lshlrev_b32_e32 v68, 16, v22
	v_and_b32_e32 v69, 0xffff0000, v22
	v_pk_fma_f32 v[8:9], v[112:113], v[16:17], v[8:9] op_sel_hi:[0, 1, 1]
	v_lshlrev_b32_e32 v16, 16, v25
	v_and_b32_e32 v17, 0xffff0000, v25
	v_pk_fma_f32 v[66:67], v[110:111], v[68:69], v[66:67] op_sel_hi:[0, 1, 1]
	v_lshlrev_b32_e32 v68, 16, v26
	v_and_b32_e32 v69, 0xffff0000, v26
	v_pk_fma_f32 v[8:9], v[110:111], v[16:17], v[8:9] op_sel_hi:[0, 1, 1]
	v_lshlrev_b32_e32 v16, 16, v29
	v_and_b32_e32 v17, 0xffff0000, v29
	v_pk_fma_f32 v[66:67], v[108:109], v[68:69], v[66:67] op_sel_hi:[0, 1, 1]
	v_lshlrev_b32_e32 v68, 16, v30
	v_and_b32_e32 v69, 0xffff0000, v30
	v_pk_fma_f32 v[8:9], v[108:109], v[16:17], v[8:9] op_sel_hi:[0, 1, 1]
	v_lshlrev_b32_e32 v16, 16, v33
	v_and_b32_e32 v17, 0xffff0000, v33
	v_pk_fma_f32 v[66:67], v[106:107], v[68:69], v[66:67] op_sel_hi:[0, 1, 1]
	v_lshlrev_b32_e32 v68, 16, v34
	v_and_b32_e32 v69, 0xffff0000, v34
	v_pk_fma_f32 v[14:15], v[84:85], v[14:15], 0 op_sel_hi:[0, 1, 0]
	v_pk_fma_f32 v[8:9], v[106:107], v[16:17], v[8:9] op_sel_hi:[0, 1, 1]
	v_lshlrev_b32_e32 v16, 16, v37
	v_and_b32_e32 v17, 0xffff0000, v37
	v_pk_fma_f32 v[66:67], v[104:105], v[68:69], v[66:67] op_sel_hi:[0, 1, 1]
	v_pk_fma_f32 v[14:15], v[114:115], v[18:19], v[14:15] op_sel_hi:[0, 1, 1]
	v_lshlrev_b32_e32 v18, 16, v20
	v_and_b32_e32 v19, 0xffff0000, v20
	v_pk_fma_f32 v[8:9], v[104:105], v[16:17], v[8:9] op_sel_hi:[0, 1, 1]
	v_cndmask_b32_e64 v86, 0, 1.0, vcc
	s_waitcnt vmcnt(30)
	v_lshlrev_b32_e32 v16, 16, v38
	v_and_b32_e32 v17, 0xffff0000, v38
	v_cmp_lt_u32_e32 vcc, v88, v87
	v_pk_fma_f32 v[14:15], v[112:113], v[18:19], v[14:15] op_sel_hi:[0, 1, 1]
	v_lshlrev_b32_e32 v18, 16, v24
	v_and_b32_e32 v19, 0xffff0000, v24
	v_lshlrev_b32_e32 v20, 16, v40
	v_and_b32_e32 v21, 0xffff0000, v40
	v_lshlrev_b32_e32 v22, 16, v41
	v_and_b32_e32 v23, 0xffff0000, v41
	v_cndmask_b32_e64 v88, 0, 1.0, vcc
	v_pk_fma_f32 v[16:17], v[86:87], v[16:17], v[66:67] op_sel_hi:[0, 1, 1]
	s_waitcnt vmcnt(29)
	v_lshlrev_b32_e32 v40, 16, v2
	v_and_b32_e32 v41, 0xffff0000, v2
	v_pk_fma_f32 v[14:15], v[110:111], v[18:19], v[14:15] op_sel_hi:[0, 1, 1]
	v_lshlrev_b32_e32 v18, 16, v28
	v_and_b32_e32 v19, 0xffff0000, v28
	v_cndmask_b32_e64 v90, 0, 1.0, s[0:1]
	s_waitcnt vmcnt(28)
	v_lshlrev_b32_e32 v24, 16, v42
	v_and_b32_e32 v25, 0xffff0000, v42
	v_pk_fma_f32 v[16:17], v[88:89], v[40:41], v[16:17] op_sel_hi:[0, 1, 1]
	v_pk_fma_f32 v[14:15], v[108:109], v[18:19], v[14:15] op_sel_hi:[0, 1, 1]
	v_lshlrev_b32_e32 v18, 16, v32
	v_and_b32_e32 v19, 0xffff0000, v32
	v_cndmask_b32_e64 v94, 0, 1.0, s[4:5]
	s_waitcnt vmcnt(27)
	v_lshlrev_b32_e32 v32, 16, v46
	v_and_b32_e32 v33, 0xffff0000, v46
	v_pk_fma_f32 v[16:17], v[90:91], v[24:25], v[16:17] op_sel_hi:[0, 1, 1]
	v_cndmask_b32_e64 v102, 0, 1.0, s[10:11]
	v_pk_fma_f32 v[16:17], v[94:95], v[32:33], v[16:17] op_sel_hi:[0, 1, 1]
	s_waitcnt vmcnt(26)
	v_lshlrev_b32_e32 v24, 16, v10
	v_and_b32_e32 v25, 0xffff0000, v10
	v_cndmask_b32_e64 v100, 0, 1.0, s[14:15]
	v_pk_fma_f32 v[16:17], v[102:103], v[24:25], v[16:17] op_sel_hi:[0, 1, 1]
	s_waitcnt vmcnt(25)
	v_lshlrev_b32_e32 v24, 16, v50
	v_and_b32_e32 v25, 0xffff0000, v50
	v_cndmask_b32_e64 v98, 0, 1.0, s[18:19]
	v_pk_fma_f32 v[16:17], v[100:101], v[24:25], v[16:17] op_sel_hi:[0, 1, 1]
	s_waitcnt vmcnt(24)
	v_lshlrev_b32_e32 v24, 16, v54
	v_and_b32_e32 v25, 0xffff0000, v54
	v_cndmask_b32_e64 v96, 0, 1.0, s[22:23]
	v_pk_fma_f32 v[16:17], v[98:99], v[24:25], v[16:17] op_sel_hi:[0, 1, 1]
	s_waitcnt vmcnt(23)
	v_lshlrev_b32_e32 v24, 16, v58
	v_and_b32_e32 v25, 0xffff0000, v58
	v_cndmask_b32_e64 v92, 0, 1.0, s[26:27]
	v_pk_fma_f32 v[16:17], v[96:97], v[24:25], v[16:17] op_sel_hi:[0, 1, 1]
	s_waitcnt vmcnt(22)
	v_lshlrev_b32_e32 v24, 16, v62
	v_and_b32_e32 v25, 0xffff0000, v62
	v_pk_fma_f32 v[14:15], v[106:107], v[18:19], v[14:15] op_sel_hi:[0, 1, 1]
	v_lshlrev_b32_e32 v18, 16, v36
	v_and_b32_e32 v19, 0xffff0000, v36
	v_pk_fma_f32 v[16:17], v[92:93], v[24:25], v[16:17] op_sel_hi:[0, 1, 1]
	v_pk_fma_f32 v[14:15], v[104:105], v[18:19], v[14:15] op_sel_hi:[0, 1, 1]
	v_lshlrev_b32_e32 v18, 16, v39
	v_and_b32_e32 v19, 0xffff0000, v39
	v_pk_fma_f32 v[16:17], v[82:83], v[16:17], v[40:41] op_sel_hi:[0, 1, 1] neg_lo:[0, 0, 1] neg_hi:[0, 0, 1]
	v_cvt_pk_bf16_f32 v2, v16, v17
	v_pk_fma_f32 v[6:7], v[86:87], v[18:19], v[6:7] op_sel_hi:[0, 1, 1]
	v_lshlrev_b32_e32 v16, 16, v3
	v_and_b32_e32 v17, 0xffff0000, v3
	v_lshlrev_b32_e32 v26, 16, v43
	v_and_b32_e32 v27, 0xffff0000, v43
	v_pk_fma_f32 v[6:7], v[88:89], v[16:17], v[6:7] op_sel_hi:[0, 1, 1]
	v_lshlrev_b32_e32 v34, 16, v47
	v_and_b32_e32 v35, 0xffff0000, v47
	v_pk_fma_f32 v[6:7], v[90:91], v[26:27], v[6:7] op_sel_hi:[0, 1, 1]
	v_pk_fma_f32 v[6:7], v[94:95], v[34:35], v[6:7] op_sel_hi:[0, 1, 1]
	v_lshlrev_b32_e32 v10, 16, v11
	v_and_b32_e32 v11, 0xffff0000, v11
	v_pk_fma_f32 v[6:7], v[102:103], v[10:11], v[6:7] op_sel_hi:[0, 1, 1]
	v_lshlrev_b32_e32 v10, 16, v51
	v_and_b32_e32 v11, 0xffff0000, v51
	v_pk_fma_f32 v[6:7], v[100:101], v[10:11], v[6:7] op_sel_hi:[0, 1, 1]
	v_lshlrev_b32_e32 v10, 16, v55
	v_and_b32_e32 v11, 0xffff0000, v55
	v_pk_fma_f32 v[6:7], v[98:99], v[10:11], v[6:7] op_sel_hi:[0, 1, 1]
	v_lshlrev_b32_e32 v10, 16, v59
	v_and_b32_e32 v11, 0xffff0000, v59
	v_pk_fma_f32 v[6:7], v[96:97], v[10:11], v[6:7] op_sel_hi:[0, 1, 1]
	v_lshlrev_b32_e32 v10, 16, v63
	v_and_b32_e32 v11, 0xffff0000, v63
	v_pk_fma_f32 v[6:7], v[92:93], v[10:11], v[6:7] op_sel_hi:[0, 1, 1]
	v_pk_fma_f32 v[6:7], v[82:83], v[6:7], v[16:17] op_sel_hi:[0, 1, 1] neg_lo:[0, 0, 1] neg_hi:[0, 0, 1]
	v_cvt_pk_bf16_f32 v3, v6, v7
	v_pk_fma_f32 v[6:7], v[86:87], v[20:21], v[14:15] op_sel_hi:[0, 1, 1]
	v_lshlrev_b32_e32 v10, 16, v4
	v_and_b32_e32 v11, 0xffff0000, v4
	v_lshlrev_b32_e32 v28, 16, v44
	v_and_b32_e32 v29, 0xffff0000, v44
	v_pk_fma_f32 v[6:7], v[88:89], v[10:11], v[6:7] op_sel_hi:[0, 1, 1]
	v_lshlrev_b32_e32 v36, 16, v48
	v_and_b32_e32 v37, 0xffff0000, v48
	v_pk_fma_f32 v[6:7], v[90:91], v[28:29], v[6:7] op_sel_hi:[0, 1, 1]
	v_pk_fma_f32 v[6:7], v[94:95], v[36:37], v[6:7] op_sel_hi:[0, 1, 1]
	v_lshlrev_b32_e32 v14, 16, v12
	v_and_b32_e32 v15, 0xffff0000, v12
	v_pk_fma_f32 v[6:7], v[102:103], v[14:15], v[6:7] op_sel_hi:[0, 1, 1]
	v_lshlrev_b32_e32 v14, 16, v52
	v_and_b32_e32 v15, 0xffff0000, v52
	v_pk_fma_f32 v[6:7], v[100:101], v[14:15], v[6:7] op_sel_hi:[0, 1, 1]
	v_lshlrev_b32_e32 v14, 16, v56
	v_and_b32_e32 v15, 0xffff0000, v56
	v_pk_fma_f32 v[6:7], v[98:99], v[14:15], v[6:7] op_sel_hi:[0, 1, 1]
	v_lshlrev_b32_e32 v14, 16, v60
	v_and_b32_e32 v15, 0xffff0000, v60
	v_pk_fma_f32 v[6:7], v[96:97], v[14:15], v[6:7] op_sel_hi:[0, 1, 1]
	v_lshlrev_b32_e32 v14, 16, v64
	v_and_b32_e32 v15, 0xffff0000, v64
	v_pk_fma_f32 v[6:7], v[92:93], v[14:15], v[6:7] op_sel_hi:[0, 1, 1]
	v_pk_fma_f32 v[6:7], v[82:83], v[6:7], v[10:11] op_sel_hi:[0, 1, 1] neg_lo:[0, 0, 1] neg_hi:[0, 0, 1]
	v_cvt_pk_bf16_f32 v4, v6, v7
	v_pk_fma_f32 v[6:7], v[86:87], v[22:23], v[8:9] op_sel_hi:[0, 1, 1]
	v_lshlrev_b32_e32 v8, 16, v5
	v_and_b32_e32 v9, 0xffff0000, v5
	v_lshlrev_b32_e32 v30, 16, v45
	v_and_b32_e32 v31, 0xffff0000, v45
	v_pk_fma_f32 v[6:7], v[88:89], v[8:9], v[6:7] op_sel_hi:[0, 1, 1]
	v_lshlrev_b32_e32 v38, 16, v49
	v_and_b32_e32 v39, 0xffff0000, v49
	v_pk_fma_f32 v[6:7], v[90:91], v[30:31], v[6:7] op_sel_hi:[0, 1, 1]
	v_pk_fma_f32 v[6:7], v[94:95], v[38:39], v[6:7] op_sel_hi:[0, 1, 1]
	v_lshlrev_b32_e32 v10, 16, v13
	v_and_b32_e32 v11, 0xffff0000, v13
	v_pk_fma_f32 v[6:7], v[102:103], v[10:11], v[6:7] op_sel_hi:[0, 1, 1]
	v_lshlrev_b32_e32 v10, 16, v53
	v_and_b32_e32 v11, 0xffff0000, v53
	v_pk_fma_f32 v[6:7], v[100:101], v[10:11], v[6:7] op_sel_hi:[0, 1, 1]
	v_lshlrev_b32_e32 v10, 16, v57
	v_and_b32_e32 v11, 0xffff0000, v57
	v_pk_fma_f32 v[6:7], v[98:99], v[10:11], v[6:7] op_sel_hi:[0, 1, 1]
	v_lshlrev_b32_e32 v10, 16, v61
	v_and_b32_e32 v11, 0xffff0000, v61
	v_pk_fma_f32 v[6:7], v[96:97], v[10:11], v[6:7] op_sel_hi:[0, 1, 1]
	v_lshlrev_b32_e32 v10, 16, v65
	v_and_b32_e32 v11, 0xffff0000, v65
	v_pk_fma_f32 v[6:7], v[92:93], v[10:11], v[6:7] op_sel_hi:[0, 1, 1]
	v_pk_fma_f32 v[6:7], v[82:83], v[6:7], v[8:9] op_sel_hi:[0, 1, 1] neg_lo:[0, 0, 1] neg_hi:[0, 0, 1]
	v_cvt_pk_bf16_f32 v5, v6, v7
	s_nop 0
	s_nop 0
	s_nop 0
	s_nop 0
	s_nop 0
	s_nop 0
	s_nop 0
	s_nop 0
	s_nop 0
	s_nop 0
	s_nop 0
	s_nop 0
	s_nop 0
	s_nop 0
	s_nop 0
	s_nop 0
	s_mov_b64 s[0:1], 0x400
	v_lshlrev_b32_e32 v0, 3, v83
	s_waitcnt vmcnt(21)
	v_lshlrev_b32_e32 v140, 16, v148
	v_and_b32_e32 v141, 0xffff0000, v148
	v_lshlrev_b32_e32 v6, 16, v149
	v_and_b32_e32 v7, 0xffff0000, v149
	s_waitcnt vmcnt(20)
	v_lshlrev_b32_e32 v142, 16, v152
	v_and_b32_e32 v143, 0xffff0000, v152
	v_pk_fma_f32 v[6:7], v[84:85], v[6:7], 0 op_sel_hi:[0, 1, 0]
	v_lshlrev_b32_e32 v10, 16, v153
	v_and_b32_e32 v11, 0xffff0000, v153
	v_pk_fma_f32 v[6:7], v[114:115], v[10:11], v[6:7] op_sel_hi:[0, 1, 1]
	s_waitcnt vmcnt(19)
	v_lshlrev_b32_e32 v10, 16, v157
	v_and_b32_e32 v11, 0xffff0000, v157
	v_pk_fma_f32 v[6:7], v[112:113], v[10:11], v[6:7] op_sel_hi:[0, 1, 1]
	s_waitcnt vmcnt(18)
	v_lshlrev_b32_e32 v10, 16, v161
	v_and_b32_e32 v11, 0xffff0000, v161
	v_pk_fma_f32 v[6:7], v[110:111], v[10:11], v[6:7] op_sel_hi:[0, 1, 1]
	s_waitcnt vmcnt(17)
	v_lshlrev_b32_e32 v10, 16, v165
	v_and_b32_e32 v11, 0xffff0000, v165
	v_pk_fma_f32 v[6:7], v[108:109], v[10:11], v[6:7] op_sel_hi:[0, 1, 1]
	s_waitcnt vmcnt(16)
	v_lshlrev_b32_e32 v10, 16, v169
	v_and_b32_e32 v11, 0xffff0000, v169
	v_pk_fma_f32 v[6:7], v[106:107], v[10:11], v[6:7] op_sel_hi:[0, 1, 1]
	s_waitcnt vmcnt(15)
	v_lshlrev_b32_e32 v10, 16, v173
	v_and_b32_e32 v11, 0xffff0000, v173
	v_pk_fma_f32 v[140:141], v[84:85], v[140:141], 0 op_sel_hi:[0, 1, 0]
	v_pk_fma_f32 v[10:11], v[104:105], v[10:11], v[6:7] op_sel_hi:[0, 1, 1]
	v_lshlrev_b32_e32 v6, 16, v150
	v_and_b32_e32 v7, 0xffff0000, v150
	v_pk_fma_f32 v[140:141], v[114:115], v[142:143], v[140:141] op_sel_hi:[0, 1, 1]
	v_lshlrev_b32_e32 v142, 16, v156
	v_and_b32_e32 v143, 0xffff0000, v156
	v_pk_fma_f32 v[6:7], v[84:85], v[6:7], 0 op_sel_hi:[0, 1, 0]
	v_lshlrev_b32_e32 v14, 16, v154
	v_and_b32_e32 v15, 0xffff0000, v154
	v_pk_fma_f32 v[6:7], v[114:115], v[14:15], v[6:7] op_sel_hi:[0, 1, 1]
	v_lshlrev_b32_e32 v14, 16, v158
	v_and_b32_e32 v15, 0xffff0000, v158
	v_pk_fma_f32 v[6:7], v[112:113], v[14:15], v[6:7] op_sel_hi:[0, 1, 1]
	v_lshlrev_b32_e32 v14, 16, v162
	v_and_b32_e32 v15, 0xffff0000, v162
	v_pk_fma_f32 v[6:7], v[110:111], v[14:15], v[6:7] op_sel_hi:[0, 1, 1]
	v_lshlrev_b32_e32 v14, 16, v166
	v_and_b32_e32 v15, 0xffff0000, v166
	v_pk_fma_f32 v[6:7], v[108:109], v[14:15], v[6:7] op_sel_hi:[0, 1, 1]
	v_lshlrev_b32_e32 v14, 16, v170
	v_and_b32_e32 v15, 0xffff0000, v170
	v_pk_fma_f32 v[6:7], v[106:107], v[14:15], v[6:7] op_sel_hi:[0, 1, 1]
	v_lshlrev_b32_e32 v14, 16, v174
	v_and_b32_e32 v15, 0xffff0000, v174
	v_pk_fma_f32 v[14:15], v[104:105], v[14:15], v[6:7] op_sel_hi:[0, 1, 1]
	v_lshlrev_b32_e32 v6, 16, v151
	v_and_b32_e32 v7, 0xffff0000, v151
	v_pk_fma_f32 v[6:7], v[84:85], v[6:7], 0 op_sel_hi:[0, 1, 0]
	v_lshlrev_b32_e32 v8, 16, v155
	v_and_b32_e32 v9, 0xffff0000, v155
	v_pk_fma_f32 v[6:7], v[114:115], v[8:9], v[6:7] op_sel_hi:[0, 1, 1]
	v_lshlrev_b32_e32 v8, 16, v159
	v_and_b32_e32 v9, 0xffff0000, v159
	v_pk_fma_f32 v[140:141], v[112:113], v[142:143], v[140:141] op_sel_hi:[0, 1, 1]
	v_lshlrev_b32_e32 v142, 16, v160
	v_and_b32_e32 v143, 0xffff0000, v160
	v_pk_fma_f32 v[6:7], v[112:113], v[8:9], v[6:7] op_sel_hi:[0, 1, 1]
	v_lshlrev_b32_e32 v8, 16, v163
	v_and_b32_e32 v9, 0xffff0000, v163
	v_pk_fma_f32 v[140:141], v[110:111], v[142:143], v[140:141] op_sel_hi:[0, 1, 1]
	v_lshlrev_b32_e32 v142, 16, v164
	v_and_b32_e32 v143, 0xffff0000, v164
	v_pk_fma_f32 v[6:7], v[110:111], v[8:9], v[6:7] op_sel_hi:[0, 1, 1]
	v_lshlrev_b32_e32 v8, 16, v167
	v_and_b32_e32 v9, 0xffff0000, v167
	v_pk_fma_f32 v[140:141], v[108:109], v[142:143], v[140:141] op_sel_hi:[0, 1, 1]
	v_lshlrev_b32_e32 v142, 16, v168
	v_and_b32_e32 v143, 0xffff0000, v168
	v_pk_fma_f32 v[6:7], v[108:109], v[8:9], v[6:7] op_sel_hi:[0, 1, 1]
	v_lshlrev_b32_e32 v8, 16, v171
	v_and_b32_e32 v9, 0xffff0000, v171
	v_pk_fma_f32 v[140:141], v[106:107], v[142:143], v[140:141] op_sel_hi:[0, 1, 1]
	v_lshlrev_b32_e32 v142, 16, v172
	v_and_b32_e32 v143, 0xffff0000, v172
	v_pk_fma_f32 v[6:7], v[106:107], v[8:9], v[6:7] op_sel_hi:[0, 1, 1]
	v_lshlrev_b32_e32 v8, 16, v175
	v_and_b32_e32 v9, 0xffff0000, v175
	v_pk_fma_f32 v[140:141], v[104:105], v[142:143], v[140:141] op_sel_hi:[0, 1, 1]
	v_pk_fma_f32 v[12:13], v[104:105], v[8:9], v[6:7] op_sel_hi:[0, 1, 1]
	s_waitcnt vmcnt(14)
	v_lshlrev_b32_e32 v6, 16, v176
	v_and_b32_e32 v7, 0xffff0000, v176
	v_lshlrev_b32_e32 v16, 16, v178
	v_and_b32_e32 v17, 0xffff0000, v178
	v_lshlrev_b32_e32 v18, 16, v179
	v_and_b32_e32 v19, 0xffff0000, v179
	v_pk_fma_f32 v[6:7], v[86:87], v[6:7], v[140:141] op_sel_hi:[0, 1, 1]
	s_waitcnt vmcnt(13)
	v_lshlrev_b32_e32 v40, 16, v180
	v_and_b32_e32 v41, 0xffff0000, v180
	s_waitcnt vmcnt(12)
	v_lshlrev_b32_e32 v20, 16, v184
	v_and_b32_e32 v21, 0xffff0000, v184
	v_pk_fma_f32 v[6:7], v[88:89], v[40:41], v[6:7] op_sel_hi:[0, 1, 1]
	s_waitcnt vmcnt(11)
	v_lshlrev_b32_e32 v28, 16, v188
	v_and_b32_e32 v29, 0xffff0000, v188
	v_pk_fma_f32 v[6:7], v[90:91], v[20:21], v[6:7] op_sel_hi:[0, 1, 1]
	v_pk_fma_f32 v[6:7], v[94:95], v[28:29], v[6:7] op_sel_hi:[0, 1, 1]
	s_waitcnt vmcnt(10)
	v_lshlrev_b32_e32 v20, 16, v192
	v_and_b32_e32 v21, 0xffff0000, v192
	v_lshlrev_b32_e32 v8, 16, v177
	v_and_b32_e32 v9, 0xffff0000, v177
	v_pk_fma_f32 v[6:7], v[102:103], v[20:21], v[6:7] op_sel_hi:[0, 1, 1]
	s_waitcnt vmcnt(9)
	v_lshlrev_b32_e32 v20, 16, v196
	v_and_b32_e32 v21, 0xffff0000, v196
	v_pk_fma_f32 v[6:7], v[100:101], v[20:21], v[6:7] op_sel_hi:[0, 1, 1]
	s_waitcnt vmcnt(8)
	v_lshlrev_b32_e32 v20, 16, v200
	v_and_b32_e32 v21, 0xffff0000, v200
	v_pk_fma_f32 v[8:9], v[86:87], v[8:9], v[10:11] op_sel_hi:[0, 1, 1]
	v_lshlrev_b32_e32 v10, 16, v181
	v_and_b32_e32 v11, 0xffff0000, v181
	v_lshlrev_b32_e32 v22, 16, v185
	v_and_b32_e32 v23, 0xffff0000, v185
	v_pk_fma_f32 v[6:7], v[98:99], v[20:21], v[6:7] op_sel_hi:[0, 1, 1]
	s_waitcnt vmcnt(7)
	v_lshlrev_b32_e32 v20, 16, v204
	v_and_b32_e32 v21, 0xffff0000, v204
	v_pk_fma_f32 v[8:9], v[88:89], v[10:11], v[8:9] op_sel_hi:[0, 1, 1]
	v_lshlrev_b32_e32 v30, 16, v189
	v_and_b32_e32 v31, 0xffff0000, v189
	v_pk_fma_f32 v[6:7], v[96:97], v[20:21], v[6:7] op_sel_hi:[0, 1, 1]
	s_waitcnt vmcnt(6)
	v_lshlrev_b32_e32 v20, 16, v222
	v_and_b32_e32 v21, 0xffff0000, v222
	v_pk_fma_f32 v[8:9], v[90:91], v[22:23], v[8:9] op_sel_hi:[0, 1, 1]
	v_pk_fma_f32 v[6:7], v[92:93], v[20:21], v[6:7] op_sel_hi:[0, 1, 1]
	v_pk_fma_f32 v[8:9], v[94:95], v[30:31], v[8:9] op_sel_hi:[0, 1, 1]
	v_lshlrev_b32_e32 v20, 16, v193
	v_and_b32_e32 v21, 0xffff0000, v193
	v_pk_fma_f32 v[8:9], v[102:103], v[20:21], v[8:9] op_sel_hi:[0, 1, 1]
	v_lshlrev_b32_e32 v20, 16, v197
	v_and_b32_e32 v21, 0xffff0000, v197
	v_pk_fma_f32 v[8:9], v[100:101], v[20:21], v[8:9] op_sel_hi:[0, 1, 1]
	v_lshlrev_b32_e32 v20, 16, v201
	v_and_b32_e32 v21, 0xffff0000, v201
	v_pk_fma_f32 v[8:9], v[98:99], v[20:21], v[8:9] op_sel_hi:[0, 1, 1]
	v_lshlrev_b32_e32 v20, 16, v205
	v_and_b32_e32 v21, 0xffff0000, v205
	v_pk_fma_f32 v[8:9], v[96:97], v[20:21], v[8:9] op_sel_hi:[0, 1, 1]
	v_lshlrev_b32_e32 v20, 16, v223
	v_and_b32_e32 v21, 0xffff0000, v223
	v_pk_fma_f32 v[8:9], v[92:93], v[20:21], v[8:9] op_sel_hi:[0, 1, 1]
	v_pk_fma_f32 v[6:7], v[82:83], v[6:7], v[40:41] op_sel_hi:[0, 1, 1] neg_lo:[0, 0, 1] neg_hi:[0, 0, 1]
	v_pk_fma_f32 v[8:9], v[82:83], v[8:9], v[10:11] op_sel_hi:[0, 1, 1] neg_lo:[0, 0, 1] neg_hi:[0, 0, 1]
	v_cvt_pk_bf16_f32 v6, v6, v7
	v_cvt_pk_bf16_f32 v7, v8, v9
	v_pk_fma_f32 v[8:9], v[86:87], v[16:17], v[14:15] op_sel_hi:[0, 1, 1]
	v_lshlrev_b32_e32 v10, 16, v182
	v_and_b32_e32 v11, 0xffff0000, v182
	v_lshlrev_b32_e32 v24, 16, v186
	v_and_b32_e32 v25, 0xffff0000, v186
	v_pk_fma_f32 v[8:9], v[88:89], v[10:11], v[8:9] op_sel_hi:[0, 1, 1]
	v_lshlrev_b32_e32 v32, 16, v190
	v_and_b32_e32 v33, 0xffff0000, v190
	v_pk_fma_f32 v[8:9], v[90:91], v[24:25], v[8:9] op_sel_hi:[0, 1, 1]
	v_pk_fma_f32 v[8:9], v[94:95], v[32:33], v[8:9] op_sel_hi:[0, 1, 1]
	v_lshlrev_b32_e32 v14, 16, v194
	v_and_b32_e32 v15, 0xffff0000, v194
	v_pk_fma_f32 v[8:9], v[102:103], v[14:15], v[8:9] op_sel_hi:[0, 1, 1]
	v_lshlrev_b32_e32 v14, 16, v198
	v_and_b32_e32 v15, 0xffff0000, v198
	v_pk_fma_f32 v[8:9], v[100:101], v[14:15], v[8:9] op_sel_hi:[0, 1, 1]
	v_lshlrev_b32_e32 v14, 16, v202
	v_and_b32_e32 v15, 0xffff0000, v202
	v_pk_fma_f32 v[8:9], v[98:99], v[14:15], v[8:9] op_sel_hi:[0, 1, 1]
	v_lshlrev_b32_e32 v14, 16, v206
	v_and_b32_e32 v15, 0xffff0000, v206
	v_pk_fma_f32 v[8:9], v[96:97], v[14:15], v[8:9] op_sel_hi:[0, 1, 1]
	v_lshlrev_b32_e32 v14, 16, v224
	v_and_b32_e32 v15, 0xffff0000, v224
	v_pk_fma_f32 v[8:9], v[92:93], v[14:15], v[8:9] op_sel_hi:[0, 1, 1]
	v_pk_fma_f32 v[8:9], v[82:83], v[8:9], v[10:11] op_sel_hi:[0, 1, 1] neg_lo:[0, 0, 1] neg_hi:[0, 0, 1]
	v_pk_fma_f32 v[10:11], v[86:87], v[18:19], v[12:13] op_sel_hi:[0, 1, 1]
	v_lshlrev_b32_e32 v12, 16, v183
	v_and_b32_e32 v13, 0xffff0000, v183
	v_lshlrev_b32_e32 v26, 16, v187
	v_and_b32_e32 v27, 0xffff0000, v187
	v_pk_fma_f32 v[10:11], v[88:89], v[12:13], v[10:11] op_sel_hi:[0, 1, 1]
	v_lshlrev_b32_e32 v38, 16, v191
	v_and_b32_e32 v39, 0xffff0000, v191
	v_pk_fma_f32 v[10:11], v[90:91], v[26:27], v[10:11] op_sel_hi:[0, 1, 1]
	v_pk_fma_f32 v[10:11], v[94:95], v[38:39], v[10:11] op_sel_hi:[0, 1, 1]
	v_lshlrev_b32_e32 v14, 16, v195
	v_and_b32_e32 v15, 0xffff0000, v195
	v_pk_fma_f32 v[10:11], v[102:103], v[14:15], v[10:11] op_sel_hi:[0, 1, 1]
	v_lshlrev_b32_e32 v14, 16, v199
	v_and_b32_e32 v15, 0xffff0000, v199
	v_pk_fma_f32 v[10:11], v[100:101], v[14:15], v[10:11] op_sel_hi:[0, 1, 1]
	v_lshlrev_b32_e32 v14, 16, v203
	v_and_b32_e32 v15, 0xffff0000, v203
	v_pk_fma_f32 v[10:11], v[98:99], v[14:15], v[10:11] op_sel_hi:[0, 1, 1]
	v_lshlrev_b32_e32 v14, 16, v207
	v_and_b32_e32 v15, 0xffff0000, v207
	v_pk_fma_f32 v[10:11], v[96:97], v[14:15], v[10:11] op_sel_hi:[0, 1, 1]
	v_lshlrev_b32_e32 v14, 16, v225
	v_and_b32_e32 v15, 0xffff0000, v225
	v_pk_fma_f32 v[10:11], v[92:93], v[14:15], v[10:11] op_sel_hi:[0, 1, 1]
	v_pk_fma_f32 v[10:11], v[82:83], v[10:11], v[12:13] op_sel_hi:[0, 1, 1] neg_lo:[0, 0, 1] neg_hi:[0, 0, 1]
	v_cvt_pk_bf16_f32 v8, v8, v9
	v_cvt_pk_bf16_f32 v9, v10, v11
	s_nop 0
	s_nop 0
	s_nop 0
	s_nop 0
	s_nop 0
	s_nop 0
	global_load_dwordx4 v[34:37], v[138:139], off offset:896
	global_load_dwordx4 v[38:41], v[122:123], off offset:896
	global_load_dwordx4 v[42:45], v[124:125], off offset:896
	global_load_dwordx4 v[46:49], v[76:77], off offset:896
	global_load_dwordx4 v[50:53], v[74:75], off offset:896
	global_load_dwordx4 v[54:57], v[70:71], off offset:896
	global_load_dwordx4 v[58:61], v[72:73], off offset:896
	global_load_dwordx4 v[62:65], v[116:117], off offset:896
	global_load_dwordx4 v[66:69], v[118:119], off offset:896
	global_load_dwordx4 v[140:143], v[120:121], off offset:896
	s_waitcnt vmcnt(15)
	v_lshlrev_b32_e32 v144, 16, v226
	v_and_b32_e32 v145, 0xffff0000, v226
	v_lshlrev_b32_e32 v10, 16, v227
	v_and_b32_e32 v11, 0xffff0000, v227
	s_waitcnt vmcnt(14)
	v_lshlrev_b32_e32 v146, 16, v230
	v_and_b32_e32 v147, 0xffff0000, v230
	v_pk_fma_f32 v[10:11], v[84:85], v[10:11], 0 op_sel_hi:[0, 1, 0]
	v_lshlrev_b32_e32 v14, 16, v231
	v_and_b32_e32 v15, 0xffff0000, v231
	v_pk_fma_f32 v[10:11], v[114:115], v[14:15], v[10:11] op_sel_hi:[0, 1, 1]
	s_waitcnt vmcnt(13)
	v_lshlrev_b32_e32 v14, 16, v235
	v_and_b32_e32 v15, 0xffff0000, v235
	v_pk_fma_f32 v[10:11], v[112:113], v[14:15], v[10:11] op_sel_hi:[0, 1, 1]
	s_waitcnt vmcnt(12)
	v_lshlrev_b32_e32 v14, 16, v239
	v_and_b32_e32 v15, 0xffff0000, v239
	v_pk_fma_f32 v[10:11], v[110:111], v[14:15], v[10:11] op_sel_hi:[0, 1, 1]
	s_waitcnt vmcnt(11)
	v_lshlrev_b32_e32 v14, 16, v243
	v_and_b32_e32 v15, 0xffff0000, v243
	v_pk_fma_f32 v[10:11], v[108:109], v[14:15], v[10:11] op_sel_hi:[0, 1, 1]
	s_waitcnt vmcnt(10)
	v_lshlrev_b32_e32 v14, 16, v247
	v_and_b32_e32 v15, 0xffff0000, v247
	v_pk_fma_f32 v[10:11], v[106:107], v[14:15], v[10:11] op_sel_hi:[0, 1, 1]
	s_waitcnt vmcnt(9)
	v_lshlrev_b32_e32 v14, 16, v35
	v_and_b32_e32 v15, 0xffff0000, v35
	v_pk_fma_f32 v[144:145], v[84:85], v[144:145], 0 op_sel_hi:[0, 1, 0]
	v_pk_fma_f32 v[14:15], v[104:105], v[14:15], v[10:11] op_sel_hi:[0, 1, 1]
	v_lshlrev_b32_e32 v10, 16, v228
	v_and_b32_e32 v11, 0xffff0000, v228
	v_pk_fma_f32 v[144:145], v[114:115], v[146:147], v[144:145] op_sel_hi:[0, 1, 1]
	v_lshlrev_b32_e32 v146, 16, v234
	v_and_b32_e32 v147, 0xffff0000, v234
	v_pk_fma_f32 v[10:11], v[84:85], v[10:11], 0 op_sel_hi:[0, 1, 0]
	v_lshlrev_b32_e32 v18, 16, v232
	v_and_b32_e32 v19, 0xffff0000, v232
	v_pk_fma_f32 v[10:11], v[114:115], v[18:19], v[10:11] op_sel_hi:[0, 1, 1]
	v_lshlrev_b32_e32 v18, 16, v236
	v_and_b32_e32 v19, 0xffff0000, v236
	v_pk_fma_f32 v[10:11], v[112:113], v[18:19], v[10:11] op_sel_hi:[0, 1, 1]
	v_lshlrev_b32_e32 v18, 16, v240
	v_and_b32_e32 v19, 0xffff0000, v240
	v_pk_fma_f32 v[10:11], v[110:111], v[18:19], v[10:11] op_sel_hi:[0, 1, 1]
	v_lshlrev_b32_e32 v18, 16, v244
	v_and_b32_e32 v19, 0xffff0000, v244
	v_pk_fma_f32 v[10:11], v[108:109], v[18:19], v[10:11] op_sel_hi:[0, 1, 1]
	v_lshlrev_b32_e32 v18, 16, v248
	v_and_b32_e32 v19, 0xffff0000, v248
	v_pk_fma_f32 v[10:11], v[106:107], v[18:19], v[10:11] op_sel_hi:[0, 1, 1]
	v_lshlrev_b32_e32 v18, 16, v36
	v_and_b32_e32 v19, 0xffff0000, v36
	v_pk_fma_f32 v[18:19], v[104:105], v[18:19], v[10:11] op_sel_hi:[0, 1, 1]
	v_lshlrev_b32_e32 v10, 16, v229
	v_and_b32_e32 v11, 0xffff0000, v229
	v_pk_fma_f32 v[10:11], v[84:85], v[10:11], 0 op_sel_hi:[0, 1, 0]
	v_lshlrev_b32_e32 v12, 16, v233
	v_and_b32_e32 v13, 0xffff0000, v233
	v_pk_fma_f32 v[10:11], v[114:115], v[12:13], v[10:11] op_sel_hi:[0, 1, 1]
	v_lshlrev_b32_e32 v12, 16, v237
	v_and_b32_e32 v13, 0xffff0000, v237
	v_pk_fma_f32 v[144:145], v[112:113], v[146:147], v[144:145] op_sel_hi:[0, 1, 1]
	v_lshlrev_b32_e32 v146, 16, v238
	v_and_b32_e32 v147, 0xffff0000, v238
	v_pk_fma_f32 v[10:11], v[112:113], v[12:13], v[10:11] op_sel_hi:[0, 1, 1]
	v_lshlrev_b32_e32 v12, 16, v241
	v_and_b32_e32 v13, 0xffff0000, v241
	v_pk_fma_f32 v[144:145], v[110:111], v[146:147], v[144:145] op_sel_hi:[0, 1, 1]
	v_lshlrev_b32_e32 v146, 16, v242
	v_and_b32_e32 v147, 0xffff0000, v242
	v_pk_fma_f32 v[10:11], v[110:111], v[12:13], v[10:11] op_sel_hi:[0, 1, 1]
	v_lshlrev_b32_e32 v12, 16, v245
	v_and_b32_e32 v13, 0xffff0000, v245
	v_pk_fma_f32 v[144:145], v[108:109], v[146:147], v[144:145] op_sel_hi:[0, 1, 1]
	v_lshlrev_b32_e32 v146, 16, v246
	v_and_b32_e32 v147, 0xffff0000, v246
	v_pk_fma_f32 v[10:11], v[108:109], v[12:13], v[10:11] op_sel_hi:[0, 1, 1]
	v_lshlrev_b32_e32 v12, 16, v249
	v_and_b32_e32 v13, 0xffff0000, v249
	v_pk_fma_f32 v[144:145], v[106:107], v[146:147], v[144:145] op_sel_hi:[0, 1, 1]
	v_lshlrev_b32_e32 v146, 16, v34
	v_and_b32_e32 v147, 0xffff0000, v34
	v_pk_fma_f32 v[10:11], v[106:107], v[12:13], v[10:11] op_sel_hi:[0, 1, 1]
	v_lshlrev_b32_e32 v12, 16, v37
	v_and_b32_e32 v13, 0xffff0000, v37
	v_pk_fma_f32 v[144:145], v[104:105], v[146:147], v[144:145] op_sel_hi:[0, 1, 1]
	v_pk_fma_f32 v[16:17], v[104:105], v[12:13], v[10:11] op_sel_hi:[0, 1, 1]
	s_waitcnt vmcnt(8)
	v_lshlrev_b32_e32 v10, 16, v38
	v_and_b32_e32 v11, 0xffff0000, v38
	v_lshlrev_b32_e32 v20, 16, v40
	v_and_b32_e32 v21, 0xffff0000, v40
	v_lshlrev_b32_e32 v22, 16, v41
	v_and_b32_e32 v23, 0xffff0000, v41
	v_pk_fma_f32 v[10:11], v[86:87], v[10:11], v[144:145] op_sel_hi:[0, 1, 1]
	s_waitcnt vmcnt(7)
	v_lshlrev_b32_e32 v40, 16, v42
	v_and_b32_e32 v41, 0xffff0000, v42
	s_waitcnt vmcnt(6)
	v_lshlrev_b32_e32 v24, 16, v46
	v_and_b32_e32 v25, 0xffff0000, v46
	v_pk_fma_f32 v[10:11], v[88:89], v[40:41], v[10:11] op_sel_hi:[0, 1, 1]
	s_waitcnt vmcnt(5)
	v_lshlrev_b32_e32 v32, 16, v50
	v_and_b32_e32 v33, 0xffff0000, v50
	v_pk_fma_f32 v[10:11], v[90:91], v[24:25], v[10:11] op_sel_hi:[0, 1, 1]
	v_pk_fma_f32 v[10:11], v[94:95], v[32:33], v[10:11] op_sel_hi:[0, 1, 1]
	s_waitcnt vmcnt(4)
	v_lshlrev_b32_e32 v24, 16, v54
	v_and_b32_e32 v25, 0xffff0000, v54
	v_lshlrev_b32_e32 v12, 16, v39
	v_and_b32_e32 v13, 0xffff0000, v39
	v_pk_fma_f32 v[10:11], v[102:103], v[24:25], v[10:11] op_sel_hi:[0, 1, 1]
	s_waitcnt vmcnt(3)
	v_lshlrev_b32_e32 v24, 16, v58
	v_and_b32_e32 v25, 0xffff0000, v58
	v_pk_fma_f32 v[10:11], v[100:101], v[24:25], v[10:11] op_sel_hi:[0, 1, 1]
	s_waitcnt vmcnt(2)
	v_lshlrev_b32_e32 v24, 16, v62
	v_and_b32_e32 v25, 0xffff0000, v62
	v_pk_fma_f32 v[12:13], v[86:87], v[12:13], v[14:15] op_sel_hi:[0, 1, 1]
	v_lshlrev_b32_e32 v14, 16, v43
	v_and_b32_e32 v15, 0xffff0000, v43
	v_lshlrev_b32_e32 v26, 16, v47
	v_and_b32_e32 v27, 0xffff0000, v47
	v_pk_fma_f32 v[10:11], v[98:99], v[24:25], v[10:11] op_sel_hi:[0, 1, 1]
	s_waitcnt vmcnt(1)
	v_lshlrev_b32_e32 v24, 16, v66
	v_and_b32_e32 v25, 0xffff0000, v66
	v_pk_fma_f32 v[12:13], v[88:89], v[14:15], v[12:13] op_sel_hi:[0, 1, 1]
	v_lshlrev_b32_e32 v34, 16, v51
	v_and_b32_e32 v35, 0xffff0000, v51
	v_pk_fma_f32 v[10:11], v[96:97], v[24:25], v[10:11] op_sel_hi:[0, 1, 1]
	s_waitcnt vmcnt(0)
	v_lshlrev_b32_e32 v24, 16, v140
	v_and_b32_e32 v25, 0xffff0000, v140
	v_pk_fma_f32 v[12:13], v[90:91], v[26:27], v[12:13] op_sel_hi:[0, 1, 1]
	v_pk_fma_f32 v[10:11], v[92:93], v[24:25], v[10:11] op_sel_hi:[0, 1, 1]
	v_pk_fma_f32 v[12:13], v[94:95], v[34:35], v[12:13] op_sel_hi:[0, 1, 1]
	v_lshlrev_b32_e32 v24, 16, v55
	v_and_b32_e32 v25, 0xffff0000, v55
	v_pk_fma_f32 v[12:13], v[102:103], v[24:25], v[12:13] op_sel_hi:[0, 1, 1]
	v_lshlrev_b32_e32 v24, 16, v59
	v_and_b32_e32 v25, 0xffff0000, v59
	v_pk_fma_f32 v[12:13], v[100:101], v[24:25], v[12:13] op_sel_hi:[0, 1, 1]
	v_lshlrev_b32_e32 v24, 16, v63
	v_and_b32_e32 v25, 0xffff0000, v63
	v_pk_fma_f32 v[12:13], v[98:99], v[24:25], v[12:13] op_sel_hi:[0, 1, 1]
	v_lshlrev_b32_e32 v24, 16, v67
	v_and_b32_e32 v25, 0xffff0000, v67
	v_pk_fma_f32 v[12:13], v[96:97], v[24:25], v[12:13] op_sel_hi:[0, 1, 1]
	v_lshlrev_b32_e32 v24, 16, v141
	v_and_b32_e32 v25, 0xffff0000, v141
	v_pk_fma_f32 v[12:13], v[92:93], v[24:25], v[12:13] op_sel_hi:[0, 1, 1]
	v_pk_fma_f32 v[10:11], v[82:83], v[10:11], v[40:41] op_sel_hi:[0, 1, 1] neg_lo:[0, 0, 1] neg_hi:[0, 0, 1]
	v_pk_fma_f32 v[12:13], v[82:83], v[12:13], v[14:15] op_sel_hi:[0, 1, 1] neg_lo:[0, 0, 1] neg_hi:[0, 0, 1]
	v_cvt_pk_bf16_f32 v10, v10, v11
	v_cvt_pk_bf16_f32 v11, v12, v13
	v_pk_fma_f32 v[12:13], v[86:87], v[20:21], v[18:19] op_sel_hi:[0, 1, 1]
	v_lshlrev_b32_e32 v14, 16, v44
	v_and_b32_e32 v15, 0xffff0000, v44
	v_lshlrev_b32_e32 v28, 16, v48
	v_and_b32_e32 v29, 0xffff0000, v48
	v_pk_fma_f32 v[12:13], v[88:89], v[14:15], v[12:13] op_sel_hi:[0, 1, 1]
	v_lshlrev_b32_e32 v36, 16, v52
	v_and_b32_e32 v37, 0xffff0000, v52
	v_pk_fma_f32 v[12:13], v[90:91], v[28:29], v[12:13] op_sel_hi:[0, 1, 1]
	v_pk_fma_f32 v[12:13], v[94:95], v[36:37], v[12:13] op_sel_hi:[0, 1, 1]
	v_lshlrev_b32_e32 v18, 16, v56
	v_and_b32_e32 v19, 0xffff0000, v56
	v_pk_fma_f32 v[12:13], v[102:103], v[18:19], v[12:13] op_sel_hi:[0, 1, 1]
	v_lshlrev_b32_e32 v18, 16, v60
	v_and_b32_e32 v19, 0xffff0000, v60
	v_pk_fma_f32 v[12:13], v[100:101], v[18:19], v[12:13] op_sel_hi:[0, 1, 1]
	v_lshlrev_b32_e32 v18, 16, v64
	v_and_b32_e32 v19, 0xffff0000, v64
	v_pk_fma_f32 v[12:13], v[98:99], v[18:19], v[12:13] op_sel_hi:[0, 1, 1]
	v_lshlrev_b32_e32 v18, 16, v68
	v_and_b32_e32 v19, 0xffff0000, v68
	v_pk_fma_f32 v[12:13], v[96:97], v[18:19], v[12:13] op_sel_hi:[0, 1, 1]
	v_lshlrev_b32_e32 v18, 16, v142
	v_and_b32_e32 v19, 0xffff0000, v142
	v_pk_fma_f32 v[12:13], v[92:93], v[18:19], v[12:13] op_sel_hi:[0, 1, 1]
	v_pk_fma_f32 v[12:13], v[82:83], v[12:13], v[14:15] op_sel_hi:[0, 1, 1] neg_lo:[0, 0, 1] neg_hi:[0, 0, 1]
	v_pk_fma_f32 v[14:15], v[86:87], v[22:23], v[16:17] op_sel_hi:[0, 1, 1]
	v_lshlrev_b32_e32 v16, 16, v45
	v_and_b32_e32 v17, 0xffff0000, v45
	v_lshlrev_b32_e32 v30, 16, v49
	v_and_b32_e32 v31, 0xffff0000, v49
	v_pk_fma_f32 v[14:15], v[88:89], v[16:17], v[14:15] op_sel_hi:[0, 1, 1]
	v_lshlrev_b32_e32 v38, 16, v53
	v_and_b32_e32 v39, 0xffff0000, v53
	v_pk_fma_f32 v[14:15], v[90:91], v[30:31], v[14:15] op_sel_hi:[0, 1, 1]
	v_pk_fma_f32 v[14:15], v[94:95], v[38:39], v[14:15] op_sel_hi:[0, 1, 1]
	v_lshlrev_b32_e32 v18, 16, v57
	v_and_b32_e32 v19, 0xffff0000, v57
	v_pk_fma_f32 v[14:15], v[102:103], v[18:19], v[14:15] op_sel_hi:[0, 1, 1]
	v_lshlrev_b32_e32 v18, 16, v61
	v_and_b32_e32 v19, 0xffff0000, v61
	v_pk_fma_f32 v[14:15], v[100:101], v[18:19], v[14:15] op_sel_hi:[0, 1, 1]
	v_lshlrev_b32_e32 v18, 16, v65
	v_and_b32_e32 v19, 0xffff0000, v65
	v_pk_fma_f32 v[14:15], v[98:99], v[18:19], v[14:15] op_sel_hi:[0, 1, 1]
	v_lshlrev_b32_e32 v18, 16, v69
	v_and_b32_e32 v19, 0xffff0000, v69
	v_pk_fma_f32 v[14:15], v[96:97], v[18:19], v[14:15] op_sel_hi:[0, 1, 1]
	v_lshlrev_b32_e32 v18, 16, v143
	v_and_b32_e32 v19, 0xffff0000, v143
	v_pk_fma_f32 v[14:15], v[92:93], v[18:19], v[14:15] op_sel_hi:[0, 1, 1]
	v_pk_fma_f32 v[14:15], v[82:83], v[14:15], v[16:17] op_sel_hi:[0, 1, 1] neg_lo:[0, 0, 1] neg_hi:[0, 0, 1]
	v_cvt_pk_bf16_f32 v12, v12, v13
	v_cvt_pk_bf16_f32 v13, v14, v15
	global_load_dwordx4 v[14:17], v[126:127], off offset:960
	global_load_dwordx4 v[18:21], v[128:129], off offset:960
	global_load_dwordx4 v[22:25], v[130:131], off offset:960
	global_load_dwordx4 v[26:29], v[132:133], off offset:960
	global_load_dwordx4 v[30:33], v[134:135], off offset:960
	global_load_dwordx4 v[34:37], v[136:137], off offset:960
	global_load_dwordx4 v[38:41], v[138:139], off offset:960
	global_load_dwordx4 v[50:53], v[122:123], off offset:960
	global_load_dwordx4 v[42:45], v[124:125], off offset:960
	global_load_dwordx4 v[62:65], v[76:77], off offset:960
	s_nop 0
	global_load_dwordx4 v[74:77], v[74:75], off offset:960
	s_nop 0
	global_load_dwordx4 v[46:49], v[70:71], off offset:960
	global_load_dwordx4 v[54:57], v[72:73], off offset:960
	global_load_dwordx4 v[58:61], v[116:117], off offset:960
	global_load_dwordx4 v[66:69], v[118:119], off offset:960
	s_nop 0
	global_load_dwordx4 v[70:73], v[120:121], off offset:960
	s_waitcnt vmcnt(15)
	v_lshlrev_b32_e32 v116, 16, v14
	v_and_b32_e32 v117, 0xffff0000, v14
	v_lshlrev_b32_e32 v14, 16, v15
	v_and_b32_e32 v15, 0xffff0000, v15
	s_waitcnt vmcnt(14)
	v_lshlrev_b32_e32 v118, 16, v18
	v_and_b32_e32 v119, 0xffff0000, v18
	v_pk_fma_f32 v[14:15], v[84:85], v[14:15], 0 op_sel_hi:[0, 1, 0]
	v_lshlrev_b32_e32 v18, 16, v19
	v_and_b32_e32 v19, 0xffff0000, v19
	v_pk_fma_f32 v[14:15], v[114:115], v[18:19], v[14:15] op_sel_hi:[0, 1, 1]
	s_waitcnt vmcnt(13)
	v_lshlrev_b32_e32 v18, 16, v23
	v_and_b32_e32 v19, 0xffff0000, v23
	v_pk_fma_f32 v[14:15], v[112:113], v[18:19], v[14:15] op_sel_hi:[0, 1, 1]
	s_waitcnt vmcnt(12)
	v_lshlrev_b32_e32 v18, 16, v27
	v_and_b32_e32 v19, 0xffff0000, v27
	v_pk_fma_f32 v[14:15], v[110:111], v[18:19], v[14:15] op_sel_hi:[0, 1, 1]
	s_waitcnt vmcnt(11)
	v_lshlrev_b32_e32 v18, 16, v31
	v_and_b32_e32 v19, 0xffff0000, v31
	v_pk_fma_f32 v[14:15], v[108:109], v[18:19], v[14:15] op_sel_hi:[0, 1, 1]
	s_waitcnt vmcnt(10)
	v_lshlrev_b32_e32 v18, 16, v35
	v_and_b32_e32 v19, 0xffff0000, v35
	v_pk_fma_f32 v[14:15], v[106:107], v[18:19], v[14:15] op_sel_hi:[0, 1, 1]
	s_waitcnt vmcnt(9)
	v_lshlrev_b32_e32 v18, 16, v39
	v_and_b32_e32 v19, 0xffff0000, v39
	v_pk_fma_f32 v[116:117], v[84:85], v[116:117], 0 op_sel_hi:[0, 1, 0]
	v_pk_fma_f32 v[18:19], v[104:105], v[18:19], v[14:15] op_sel_hi:[0, 1, 1]
	v_lshlrev_b32_e32 v14, 16, v16
	v_and_b32_e32 v15, 0xffff0000, v16
	v_pk_fma_f32 v[116:117], v[114:115], v[118:119], v[116:117] op_sel_hi:[0, 1, 1]
	v_lshlrev_b32_e32 v118, 16, v22
	v_and_b32_e32 v119, 0xffff0000, v22
	v_pk_fma_f32 v[14:15], v[84:85], v[14:15], 0 op_sel_hi:[0, 1, 0]
	v_lshlrev_b32_e32 v22, 16, v20
	v_and_b32_e32 v23, 0xffff0000, v20
	v_pk_fma_f32 v[14:15], v[114:115], v[22:23], v[14:15] op_sel_hi:[0, 1, 1]
	v_lshlrev_b32_e32 v22, 16, v24
	v_and_b32_e32 v23, 0xffff0000, v24
	v_pk_fma_f32 v[14:15], v[112:113], v[22:23], v[14:15] op_sel_hi:[0, 1, 1]
	v_lshlrev_b32_e32 v22, 16, v28
	v_and_b32_e32 v23, 0xffff0000, v28
	v_pk_fma_f32 v[14:15], v[110:111], v[22:23], v[14:15] op_sel_hi:[0, 1, 1]
	v_lshlrev_b32_e32 v22, 16, v32
	v_and_b32_e32 v23, 0xffff0000, v32
	v_pk_fma_f32 v[14:15], v[108:109], v[22:23], v[14:15] op_sel_hi:[0, 1, 1]
	v_lshlrev_b32_e32 v22, 16, v36
	v_and_b32_e32 v23, 0xffff0000, v36
	v_pk_fma_f32 v[14:15], v[106:107], v[22:23], v[14:15] op_sel_hi:[0, 1, 1]
	v_lshlrev_b32_e32 v22, 16, v40
	v_and_b32_e32 v23, 0xffff0000, v40
	v_pk_fma_f32 v[22:23], v[104:105], v[22:23], v[14:15] op_sel_hi:[0, 1, 1]
	v_lshlrev_b32_e32 v14, 16, v17
	v_and_b32_e32 v15, 0xffff0000, v17
	v_pk_fma_f32 v[14:15], v[84:85], v[14:15], 0 op_sel_hi:[0, 1, 0]
	v_lshlrev_b32_e32 v16, 16, v21
	v_and_b32_e32 v17, 0xffff0000, v21
	v_pk_fma_f32 v[14:15], v[114:115], v[16:17], v[14:15] op_sel_hi:[0, 1, 1]
	v_lshlrev_b32_e32 v16, 16, v25
	v_and_b32_e32 v17, 0xffff0000, v25
	v_pk_fma_f32 v[116:117], v[112:113], v[118:119], v[116:117] op_sel_hi:[0, 1, 1]
	v_lshlrev_b32_e32 v118, 16, v26
	v_and_b32_e32 v119, 0xffff0000, v26
	v_pk_fma_f32 v[14:15], v[112:113], v[16:17], v[14:15] op_sel_hi:[0, 1, 1]
	v_lshlrev_b32_e32 v16, 16, v29
	v_and_b32_e32 v17, 0xffff0000, v29
	v_pk_fma_f32 v[116:117], v[110:111], v[118:119], v[116:117] op_sel_hi:[0, 1, 1]
	v_lshlrev_b32_e32 v118, 16, v30
	v_and_b32_e32 v119, 0xffff0000, v30
	v_pk_fma_f32 v[14:15], v[110:111], v[16:17], v[14:15] op_sel_hi:[0, 1, 1]
	v_lshlrev_b32_e32 v16, 16, v33
	v_and_b32_e32 v17, 0xffff0000, v33
	v_pk_fma_f32 v[116:117], v[108:109], v[118:119], v[116:117] op_sel_hi:[0, 1, 1]
	v_lshlrev_b32_e32 v118, 16, v34
	v_and_b32_e32 v119, 0xffff0000, v34
	v_pk_fma_f32 v[14:15], v[108:109], v[16:17], v[14:15] op_sel_hi:[0, 1, 1]
	v_lshlrev_b32_e32 v16, 16, v37
	v_and_b32_e32 v17, 0xffff0000, v37
	v_pk_fma_f32 v[116:117], v[106:107], v[118:119], v[116:117] op_sel_hi:[0, 1, 1]
	v_lshlrev_b32_e32 v118, 16, v38
	v_and_b32_e32 v119, 0xffff0000, v38
	v_pk_fma_f32 v[14:15], v[106:107], v[16:17], v[14:15] op_sel_hi:[0, 1, 1]
	v_lshlrev_b32_e32 v16, 16, v41
	v_and_b32_e32 v17, 0xffff0000, v41
	v_pk_fma_f32 v[116:117], v[104:105], v[118:119], v[116:117] op_sel_hi:[0, 1, 1]
	v_pk_fma_f32 v[20:21], v[104:105], v[16:17], v[14:15] op_sel_hi:[0, 1, 1]
	s_waitcnt vmcnt(8)
	v_lshlrev_b32_e32 v14, 16, v50
	v_and_b32_e32 v15, 0xffff0000, v50
	v_lshlrev_b32_e32 v24, 16, v52
	v_and_b32_e32 v25, 0xffff0000, v52
	v_lshlrev_b32_e32 v26, 16, v53
	v_and_b32_e32 v27, 0xffff0000, v53
	v_pk_fma_f32 v[14:15], v[86:87], v[14:15], v[116:117] op_sel_hi:[0, 1, 1]
	s_waitcnt vmcnt(7)
	v_lshlrev_b32_e32 v52, 16, v42
	v_and_b32_e32 v53, 0xffff0000, v42
	s_waitcnt vmcnt(6)
	v_lshlrev_b32_e32 v28, 16, v62
	v_and_b32_e32 v29, 0xffff0000, v62
	v_pk_fma_f32 v[14:15], v[88:89], v[52:53], v[14:15] op_sel_hi:[0, 1, 1]
	s_waitcnt vmcnt(5)
	v_lshlrev_b32_e32 v36, 16, v74
	v_and_b32_e32 v37, 0xffff0000, v74
	v_pk_fma_f32 v[14:15], v[90:91], v[28:29], v[14:15] op_sel_hi:[0, 1, 1]
	v_pk_fma_f32 v[14:15], v[94:95], v[36:37], v[14:15] op_sel_hi:[0, 1, 1]
	s_waitcnt vmcnt(4)
	v_lshlrev_b32_e32 v28, 16, v46
	v_and_b32_e32 v29, 0xffff0000, v46
	v_lshlrev_b32_e32 v16, 16, v51
	v_and_b32_e32 v17, 0xffff0000, v51
	v_pk_fma_f32 v[14:15], v[102:103], v[28:29], v[14:15] op_sel_hi:[0, 1, 1]
	s_waitcnt vmcnt(3)
	v_lshlrev_b32_e32 v28, 16, v54
	v_and_b32_e32 v29, 0xffff0000, v54
	v_pk_fma_f32 v[14:15], v[100:101], v[28:29], v[14:15] op_sel_hi:[0, 1, 1]
	s_waitcnt vmcnt(2)
	v_lshlrev_b32_e32 v28, 16, v58
	v_and_b32_e32 v29, 0xffff0000, v58
	v_pk_fma_f32 v[16:17], v[86:87], v[16:17], v[18:19] op_sel_hi:[0, 1, 1]
	v_lshlrev_b32_e32 v18, 16, v43
	v_and_b32_e32 v19, 0xffff0000, v43
	v_lshlrev_b32_e32 v30, 16, v63
	v_and_b32_e32 v31, 0xffff0000, v63
	v_pk_fma_f32 v[14:15], v[98:99], v[28:29], v[14:15] op_sel_hi:[0, 1, 1]
	s_waitcnt vmcnt(1)
	v_lshlrev_b32_e32 v28, 16, v66
	v_and_b32_e32 v29, 0xffff0000, v66
	v_pk_fma_f32 v[16:17], v[88:89], v[18:19], v[16:17] op_sel_hi:[0, 1, 1]
	v_lshlrev_b32_e32 v38, 16, v75
	v_and_b32_e32 v39, 0xffff0000, v75
	v_pk_fma_f32 v[14:15], v[96:97], v[28:29], v[14:15] op_sel_hi:[0, 1, 1]
	s_waitcnt vmcnt(0)
	v_lshlrev_b32_e32 v28, 16, v70
	v_and_b32_e32 v29, 0xffff0000, v70
	v_pk_fma_f32 v[16:17], v[90:91], v[30:31], v[16:17] op_sel_hi:[0, 1, 1]
	v_pk_fma_f32 v[14:15], v[92:93], v[28:29], v[14:15] op_sel_hi:[0, 1, 1]
	v_pk_fma_f32 v[16:17], v[94:95], v[38:39], v[16:17] op_sel_hi:[0, 1, 1]
	v_lshlrev_b32_e32 v28, 16, v47
	v_and_b32_e32 v29, 0xffff0000, v47
	v_pk_fma_f32 v[16:17], v[102:103], v[28:29], v[16:17] op_sel_hi:[0, 1, 1]
	v_lshlrev_b32_e32 v28, 16, v55
	v_and_b32_e32 v29, 0xffff0000, v55
	v_pk_fma_f32 v[16:17], v[100:101], v[28:29], v[16:17] op_sel_hi:[0, 1, 1]
	v_lshlrev_b32_e32 v28, 16, v59
	v_and_b32_e32 v29, 0xffff0000, v59
	v_pk_fma_f32 v[16:17], v[98:99], v[28:29], v[16:17] op_sel_hi:[0, 1, 1]
	v_lshlrev_b32_e32 v28, 16, v67
	v_and_b32_e32 v29, 0xffff0000, v67
	v_pk_fma_f32 v[16:17], v[96:97], v[28:29], v[16:17] op_sel_hi:[0, 1, 1]
	v_lshlrev_b32_e32 v28, 16, v71
	v_and_b32_e32 v29, 0xffff0000, v71
	v_pk_fma_f32 v[16:17], v[92:93], v[28:29], v[16:17] op_sel_hi:[0, 1, 1]
	v_pk_fma_f32 v[14:15], v[82:83], v[14:15], v[52:53] op_sel_hi:[0, 1, 1] neg_lo:[0, 0, 1] neg_hi:[0, 0, 1]
	v_pk_fma_f32 v[16:17], v[82:83], v[16:17], v[18:19] op_sel_hi:[0, 1, 1] neg_lo:[0, 0, 1] neg_hi:[0, 0, 1]
	v_cvt_pk_bf16_f32 v14, v14, v15
	v_cvt_pk_bf16_f32 v15, v16, v17
	v_pk_fma_f32 v[16:17], v[86:87], v[24:25], v[22:23] op_sel_hi:[0, 1, 1]
	v_lshlrev_b32_e32 v18, 16, v44
	v_and_b32_e32 v19, 0xffff0000, v44
	v_lshlrev_b32_e32 v32, 16, v64
	v_and_b32_e32 v33, 0xffff0000, v64
	v_pk_fma_f32 v[16:17], v[88:89], v[18:19], v[16:17] op_sel_hi:[0, 1, 1]
	v_lshlrev_b32_e32 v40, 16, v76
	v_and_b32_e32 v41, 0xffff0000, v76
	v_pk_fma_f32 v[16:17], v[90:91], v[32:33], v[16:17] op_sel_hi:[0, 1, 1]
	v_pk_fma_f32 v[16:17], v[94:95], v[40:41], v[16:17] op_sel_hi:[0, 1, 1]
	v_lshlrev_b32_e32 v22, 16, v48
	v_and_b32_e32 v23, 0xffff0000, v48
	v_pk_fma_f32 v[16:17], v[102:103], v[22:23], v[16:17] op_sel_hi:[0, 1, 1]
	v_lshlrev_b32_e32 v22, 16, v56
	v_and_b32_e32 v23, 0xffff0000, v56
	v_pk_fma_f32 v[16:17], v[100:101], v[22:23], v[16:17] op_sel_hi:[0, 1, 1]
	v_lshlrev_b32_e32 v22, 16, v60
	v_and_b32_e32 v23, 0xffff0000, v60
	v_pk_fma_f32 v[16:17], v[98:99], v[22:23], v[16:17] op_sel_hi:[0, 1, 1]
	v_lshlrev_b32_e32 v22, 16, v68
	v_and_b32_e32 v23, 0xffff0000, v68
	v_pk_fma_f32 v[16:17], v[96:97], v[22:23], v[16:17] op_sel_hi:[0, 1, 1]
	v_lshlrev_b32_e32 v22, 16, v72
	v_and_b32_e32 v23, 0xffff0000, v72
	v_pk_fma_f32 v[16:17], v[92:93], v[22:23], v[16:17] op_sel_hi:[0, 1, 1]
	v_pk_fma_f32 v[16:17], v[82:83], v[16:17], v[18:19] op_sel_hi:[0, 1, 1] neg_lo:[0, 0, 1] neg_hi:[0, 0, 1]
	v_pk_fma_f32 v[18:19], v[86:87], v[26:27], v[20:21] op_sel_hi:[0, 1, 1]
	v_lshlrev_b32_e32 v20, 16, v45
	v_and_b32_e32 v21, 0xffff0000, v45
	v_lshlrev_b32_e32 v34, 16, v65
	v_and_b32_e32 v35, 0xffff0000, v65
	v_pk_fma_f32 v[18:19], v[88:89], v[20:21], v[18:19] op_sel_hi:[0, 1, 1]
	v_lshlrev_b32_e32 v50, 16, v77
	v_and_b32_e32 v51, 0xffff0000, v77
	v_pk_fma_f32 v[18:19], v[90:91], v[34:35], v[18:19] op_sel_hi:[0, 1, 1]
	v_pk_fma_f32 v[18:19], v[94:95], v[50:51], v[18:19] op_sel_hi:[0, 1, 1]
	v_lshlrev_b32_e32 v22, 16, v49
	v_and_b32_e32 v23, 0xffff0000, v49
	v_pk_fma_f32 v[18:19], v[102:103], v[22:23], v[18:19] op_sel_hi:[0, 1, 1]
	v_lshlrev_b32_e32 v22, 16, v57
	v_and_b32_e32 v23, 0xffff0000, v57
	v_pk_fma_f32 v[18:19], v[100:101], v[22:23], v[18:19] op_sel_hi:[0, 1, 1]
	v_lshlrev_b32_e32 v22, 16, v61
	v_and_b32_e32 v23, 0xffff0000, v61
	v_pk_fma_f32 v[18:19], v[98:99], v[22:23], v[18:19] op_sel_hi:[0, 1, 1]
	v_lshlrev_b32_e32 v22, 16, v69
	v_and_b32_e32 v23, 0xffff0000, v69
	v_pk_fma_f32 v[18:19], v[96:97], v[22:23], v[18:19] op_sel_hi:[0, 1, 1]
	v_lshlrev_b32_e32 v22, 16, v73
	v_and_b32_e32 v23, 0xffff0000, v73
	v_pk_fma_f32 v[18:19], v[92:93], v[22:23], v[18:19] op_sel_hi:[0, 1, 1]
	v_pk_fma_f32 v[18:19], v[82:83], v[18:19], v[20:21] op_sel_hi:[0, 1, 1] neg_lo:[0, 0, 1] neg_hi:[0, 0, 1]
	v_lshlrev_b64 v[20:21], 11, v[80:81]
	v_cvt_pk_bf16_f32 v16, v16, v17
	v_cvt_pk_bf16_f32 v17, v18, v19
	v_lshl_add_u64 v[18:19], s[74:75], 0, v[78:79]
	v_lshl_add_u64 v[30:31], s[84:85], 0, v[20:21]
	v_lshlrev_b32_e32 v20, 8, v85
	v_mov_b32_e32 v21, v1
	v_lshl_add_u64 v[28:29], v[18:19], 0, v[20:21]
	v_add_co_u32_e32 v56, vcc, 0x1000, v28
	s_nop 1
	v_addc_co_u32_e32 v57, vcc, 0, v29, vcc
	v_add_co_u32_e32 v58, vcc, 0x3000, v28
	s_nop 1
	v_addc_co_u32_e32 v59, vcc, 0, v29, vcc
	v_add_co_u32_e32 v60, vcc, 0x5000, v28
	s_nop 1
	v_addc_co_u32_e32 v61, vcc, 0, v29, vcc
	v_add_co_u32_e32 v62, vcc, 0x7000, v28
	s_nop 1
	v_addc_co_u32_e32 v63, vcc, 0, v29, vcc
	global_load_dwordx4 v[100:103], v78, s[30:31] offset:1536
	global_load_dwordx4 v[120:123], v78, s[30:31] offset:1600
	global_load_dwordx4 v[140:143], v78, s[30:31] offset:1664
	global_load_dwordx4 v[160:163], v78, s[30:31] offset:1728
	global_load_dwordx4 v[180:183], v78, s[30:31] offset:1792
	global_load_dwordx4 v[200:203], v78, s[30:31] offset:1856
	global_load_dwordx4 v[234:237], v78, s[30:31] offset:1920
	v_and_b32_e32 v56, 15, v209
	v_bfe_u32 v57, v209, 4, 2
	v_mul_u32_u24_e32 v56, 0x110, v56
	v_lshl_add_u32 v56, v57, 4, v56
	v_add_u32_e32 v56, 0x19800, v56
	ds_read_b128 v[84:87], v56 offset:0
	ds_read_b128 v[88:91], v56 offset:64
	ds_read_b128 v[92:95], v56 offset:128
	ds_read_b128 v[96:99], v56 offset:192
	ds_read_b128 v[104:107], v56 offset:4352
	ds_read_b128 v[108:111], v56 offset:4416
	ds_read_b128 v[112:115], v56 offset:4480
	ds_read_b128 v[116:119], v56 offset:4544
	ds_read_b128 v[124:127], v56 offset:8704
	ds_read_b128 v[128:131], v56 offset:8768
	ds_read_b128 v[132:135], v56 offset:8832
	ds_read_b128 v[136:139], v56 offset:8896
	ds_read_b128 v[144:147], v56 offset:13056
	ds_read_b128 v[148:151], v56 offset:13120
	ds_read_b128 v[152:155], v56 offset:13184
	ds_read_b128 v[156:159], v56 offset:13248
	s_nop 0
	s_nop 0
	s_waitcnt lgkmcnt(12)
	v_mfma_f32_16x16x32_bf16 v[18:21], v[84:87], v[2:5], 0
	v_lshl_add_u64 v[26:27], v[30:31], 0, s[0:1]
	s_movk_i32 s0, 0x1000
	v_mfma_f32_16x16x32_bf16 v[18:21], v[88:91], v[6:9], v[18:21]
	s_nop 0
	v_mfma_f32_16x16x32_bf16 v[18:21], v[92:95], v[10:13], v[18:21]
	s_nop 0
	v_mfma_f32_16x16x32_bf16 v[18:21], v[96:99], v[14:17], v[18:21]
	s_nop 0
	s_waitcnt vmcnt(6)
	s_nop 5
	v_pk_mul_f32 v[20:21], v[20:21], v[102:103]
	v_add_co_u32_e32 v24, vcc, s0, v28
	v_pk_mul_f32 v[18:19], v[18:19], v[100:101]
	s_nop 0
	v_addc_co_u32_e32 v25, vcc, 0, v29, vcc
	s_movk_i32 s0, 0x2000
	v_cvt_pk_bf16_f32 v22, v18, v19
	v_cvt_pk_bf16_f32 v23, v20, v21
	v_lshl_add_u64 v[18:19], v[30:31], 0, v[0:1]
	v_add_co_u32_e32 v34, vcc, s0, v28
	global_store_dwordx2 v[18:19], v[22:23], off offset:1792
	s_nop 0
	v_addc_co_u32_e32 v35, vcc, 0, v29, vcc
	s_nop 0
	s_nop 0
	s_waitcnt lgkmcnt(8)
	v_mfma_f32_16x16x32_bf16 v[20:23], v[104:107], v[2:5], 0
	s_movk_i32 s0, 0x3000
	v_mov_b32_e32 v0, 0x1f0
	v_lshl_or_b32 v0, v83, 2, v0
	v_mfma_f32_16x16x32_bf16 v[20:23], v[108:111], v[6:9], v[20:23]
	s_nop 0
	v_mfma_f32_16x16x32_bf16 v[20:23], v[112:115], v[10:13], v[20:23]
	s_nop 0
	v_add_co_u32_e32 v24, vcc, s0, v28
	v_mfma_f32_16x16x32_bf16 v[20:23], v[116:119], v[14:17], v[20:23]
	s_nop 0
	v_addc_co_u32_e32 v25, vcc, 0, v29, vcc
	s_movk_i32 s0, 0x4000
	s_waitcnt vmcnt(6)
	s_nop 3
	v_pk_mul_f32 v[22:23], v[22:23], v[122:123]
	v_pk_mul_f32 v[20:21], v[20:21], v[120:121]
	s_nop 0
	v_cvt_pk_bf16_f32 v20, v20, v21
	v_cvt_pk_bf16_f32 v21, v22, v23
	global_store_dwordx2 v[18:19], v[20:21], off offset:1824
	s_nop 0
	s_nop 0
	s_nop 0
	s_waitcnt lgkmcnt(4)
	v_mfma_f32_16x16x32_bf16 v[20:23], v[124:127], v[2:5], 0
	v_mfma_f32_16x16x32_bf16 v[20:23], v[128:131], v[6:9], v[20:23]
	s_nop 0
	v_mfma_f32_16x16x32_bf16 v[20:23], v[132:135], v[10:13], v[20:23]
	s_nop 0
	v_add_co_u32_e32 v34, vcc, s0, v28
	v_mfma_f32_16x16x32_bf16 v[20:23], v[136:139], v[14:17], v[20:23]
	s_nop 0
	v_addc_co_u32_e32 v35, vcc, 0, v29, vcc
	s_movk_i32 s0, 0x5000
	s_waitcnt vmcnt(6)
	s_nop 3
	v_pk_mul_f32 v[22:23], v[22:23], v[142:143]
	v_pk_mul_f32 v[20:21], v[20:21], v[140:141]
	s_nop 0
	v_cvt_pk_bf16_f32 v20, v20, v21
	v_cvt_pk_bf16_f32 v21, v22, v23
	global_store_dwordx2 v[18:19], v[20:21], off offset:1856
	s_nop 0
	s_nop 0
	s_nop 0
	s_waitcnt lgkmcnt(0)
	v_mfma_f32_16x16x32_bf16 v[20:23], v[144:147], v[2:5], 0
	v_mfma_f32_16x16x32_bf16 v[20:23], v[148:151], v[6:9], v[20:23]
	s_nop 0
	v_mfma_f32_16x16x32_bf16 v[20:23], v[152:155], v[10:13], v[20:23]
	s_nop 0
	v_add_co_u32_e32 v24, vcc, s0, v28
	v_mfma_f32_16x16x32_bf16 v[20:23], v[156:159], v[14:17], v[20:23]
	s_nop 0
	v_addc_co_u32_e32 v25, vcc, 0, v29, vcc
	s_movk_i32 s0, 0x6000
	s_waitcnt vmcnt(6)
	s_nop 3
	v_pk_mul_f32 v[22:23], v[22:23], v[162:163]
	v_pk_mul_f32 v[20:21], v[20:21], v[160:161]
	s_nop 0
	v_cvt_pk_bf16_f32 v20, v20, v21
	v_cvt_pk_bf16_f32 v21, v22, v23
	global_store_dwordx2 v[18:19], v[20:21], off offset:1888
	s_nop 0
	s_nop 0
	s_nop 0
	ds_read_b128 v[164:167], v56 offset:17408
	ds_read_b128 v[168:171], v56 offset:17472
	ds_read_b128 v[172:175], v56 offset:17536
	ds_read_b128 v[176:179], v56 offset:17600
	ds_read_b128 v[184:187], v56 offset:21760
	ds_read_b128 v[188:191], v56 offset:21824
	ds_read_b128 v[192:195], v56 offset:21888
	ds_read_b128 v[196:199], v56 offset:21952
	ds_read_b128 v[204:207], v56 offset:26112
	ds_read_b128 v[222:225], v56 offset:26176
	ds_read_b128 v[226:229], v56 offset:26240
	ds_read_b128 v[230:233], v56 offset:26304
	ds_read_b128 v[238:241], v56 offset:30464
	ds_read_b128 v[242:245], v56 offset:30528
	ds_read_b128 v[246:249], v56 offset:30592
	ds_read_b128 v[52:55], v56 offset:30656
	s_waitcnt lgkmcnt(12)
	v_mfma_f32_16x16x32_bf16 v[20:23], v[164:167], v[2:5], 0
	v_mfma_f32_16x16x32_bf16 v[20:23], v[168:171], v[6:9], v[20:23]
	s_nop 0
	v_mfma_f32_16x16x32_bf16 v[20:23], v[172:175], v[10:13], v[20:23]
	s_nop 0
	v_add_co_u32_e32 v34, vcc, s0, v28
	v_mfma_f32_16x16x32_bf16 v[20:23], v[176:179], v[14:17], v[20:23]
	s_nop 0
	v_addc_co_u32_e32 v35, vcc, 0, v29, vcc
	s_waitcnt vmcnt(6)
	s_nop 4
	v_pk_mul_f32 v[22:23], v[22:23], v[182:183]
	v_pk_mul_f32 v[20:21], v[20:21], v[180:181]
	s_nop 0
	v_cvt_pk_bf16_f32 v20, v20, v21
	v_cvt_pk_bf16_f32 v21, v22, v23
	global_store_dwordx2 v[18:19], v[20:21], off offset:1920
	s_nop 0
	s_nop 0
	s_nop 0
	s_waitcnt lgkmcnt(8)
	v_mfma_f32_16x16x32_bf16 v[20:23], v[184:187], v[2:5], 0
	v_mfma_f32_16x16x32_bf16 v[20:23], v[188:191], v[6:9], v[20:23]
	s_nop 0
	v_mfma_f32_16x16x32_bf16 v[20:23], v[192:195], v[10:13], v[20:23]
	s_nop 0
	v_mfma_f32_16x16x32_bf16 v[20:23], v[196:199], v[14:17], v[20:23]
	s_nop 0
	s_waitcnt vmcnt(6)
	s_nop 5
	v_pk_mul_f32 v[22:23], v[22:23], v[202:203]
	v_pk_mul_f32 v[20:21], v[20:21], v[200:201]
	s_nop 0
	v_cvt_pk_bf16_f32 v20, v20, v21
	v_cvt_pk_bf16_f32 v21, v22, v23
	global_store_dwordx2 v[18:19], v[20:21], off offset:1952
	s_nop 0
	s_nop 0
	s_nop 0
	s_waitcnt lgkmcnt(4)
	v_mfma_f32_16x16x32_bf16 v[20:23], v[204:207], v[2:5], 0
	v_mfma_f32_16x16x32_bf16 v[20:23], v[222:225], v[6:9], v[20:23]
	s_nop 0
	v_mfma_f32_16x16x32_bf16 v[20:23], v[226:229], v[10:13], v[20:23]
	s_nop 0
	v_mfma_f32_16x16x32_bf16 v[20:23], v[230:233], v[14:17], v[20:23]
	s_nop 0
	s_waitcnt vmcnt(6)
	s_nop 5
	v_pk_mul_f32 v[22:23], v[22:23], v[236:237]
	v_pk_mul_f32 v[20:21], v[20:21], v[234:235]
	s_nop 0
	v_cvt_pk_bf16_f32 v20, v20, v21
	v_cvt_pk_bf16_f32 v21, v22, v23
	v_add_co_u32_e32 v22, vcc, 0x7000, v28
	global_store_dwordx2 v[18:19], v[20:21], off offset:1984
	s_nop 0
	v_addc_co_u32_e32 v23, vcc, 0, v29, vcc
	s_nop 0
	s_waitcnt lgkmcnt(0)
	v_mfma_f32_16x16x32_bf16 v[2:5], v[238:241], v[2:5], 0
	s_nop 0
	v_mfma_f32_16x16x32_bf16 v[2:5], v[242:245], v[6:9], v[2:5]
	s_nop 0
	v_mfma_f32_16x16x32_bf16 v[2:5], v[246:249], v[10:13], v[2:5]
	s_nop 0
	v_mfma_f32_16x16x32_bf16 v[2:5], v[52:55], v[14:17], v[2:5]
	s_cbranch_execnz .LBB0_579
.LBB0_593:
	v_mov_b32_e32 v0, v209
	v_mov_b32_e32 v29, v1
	v_readfirstlane_b32 s0, v0
	s_ashr_i32 s0, s0, 2
	v_and_b32_e32 v23, 15, v0
	s_nop 1
	v_bfi_b32 v2, -16, s0, v0
	v_add_u32_e32 v20, s59, v2
	s_mov_b32 s0, 0x38e38e39
	v_bfe_u32 v34, v0, 4, 2
	v_mul_hi_i32 v0, v20, s0
	v_lshrrev_b32_e32 v3, 31, v0
	v_ashrrev_i32_e32 v0, 13, v0
	v_add_u32_e32 v0, v0, v3
	v_mul_i32_i24_e32 v0, 0x9000, v0
	v_sub_u32_e32 v0, v20, v0
	s_mov_b32 s0, 0x8000
	v_cmp_gt_i32_e32 vcc, s0, v0
	v_lshlrev_b32_e32 v28, 4, v34
	v_ashrrev_i32_e32 v21, 31, v20
	v_cndmask_b32_e32 v3, v220, v221, vcc
	v_and_b32_e32 v11, v3, v0
	v_cndmask_b32_e32 v10, v217, v210, vcc
	v_add_u32_e32 v3, -1, v11
	v_add_u32_e32 v4, 1, v11
	v_max_i32_e32 v0, 0, v3
	v_min_u32_e32 v4, v4, v10
	v_sub_u32_e32 v0, v4, v0
	v_cvt_f32_i32_e32 v0, v0
	v_div_scale_f32 v4, s[0:1], v0, v0, 1.0
	v_rcp_f32_e32 v5, v4
	v_readlane_b32 s0, v253, 62
	v_readlane_b32 s1, v253, 63
	v_fma_f32 v6, -v4, v5, 1.0
	v_fmac_f32_e32 v5, v6, v5
	v_div_scale_f32 v6, vcc, 1.0, v0, 1.0
	v_mul_f32_e32 v7, v6, v5
	v_fma_f32 v8, -v4, v7, v6
	v_fmac_f32_e32 v7, v8, v5
	v_fma_f32 v4, -v4, v7, v6
	v_div_fmas_f32 v4, v4, v5, v7
	v_cmp_lt_u32_e32 vcc, v3, v10
	v_lshl_add_u64 v[8:9], s[0:1], 0, v[28:29]
	v_lshlrev_b64 v[6:7], 10, v[20:21]
	v_cndmask_b32_e32 v3, v11, v3, vcc
	v_add_u32_e32 v2, v2, v3
	v_sub_u32_e32 v2, v2, v11
	v_add_u32_e32 v2, s59, v2
	v_ashrrev_i32_e32 v3, 31, v2
	v_lshlrev_b64 v[2:3], 10, v[2:3]
	v_lshl_add_u64 v[14:15], v[8:9], 0, v[2:3]
	v_div_fixup_f32 v18, v4, v0, 1.0
	global_load_dwordx4 v[2:5], v[14:15], off
	v_lshl_add_u64 v[16:17], v[8:9], 0, v[6:7]
	global_load_dwordx4 v[6:9], v[16:17], off
	global_load_dwordx4 v[92:95], v[14:15], off offset:64
	global_load_dwordx4 v[96:99], v[16:17], off offset:64
	global_load_dwordx4 v[100:103], v[14:15], off offset:128
	global_load_dwordx4 v[104:107], v[16:17], off offset:128
	global_load_dwordx4 v[108:111], v[14:15], off offset:192
	global_load_dwordx4 v[112:115], v[16:17], off offset:192
	v_cndmask_b32_e64 v22, 0, 1.0, vcc
	v_cmp_lt_u32_e32 vcc, v11, v10
	v_lshlrev_b64 v[20:21], 11, v[20:21]
	s_mov_b64 s[0:1], 0x400
	v_cndmask_b32_e64 v24, 0, 1.0, vcc
	v_lshlrev_b32_e32 v0, 3, v34
	s_waitcnt vmcnt(7)
	v_lshlrev_b32_e32 v10, 16, v2
	v_and_b32_e32 v11, 0xffff0000, v2
	v_pk_fma_f32 v[10:11], v[22:23], v[10:11], 0 op_sel_hi:[0, 1, 0]
	s_waitcnt vmcnt(6)
	v_lshlrev_b32_e32 v12, 16, v6
	v_and_b32_e32 v13, 0xffff0000, v6
	v_pk_fma_f32 v[10:11], v[24:25], v[12:13], v[10:11] op_sel_hi:[0, 1, 1]
	v_pk_fma_f32 v[10:11], v[18:19], v[10:11], v[12:13] op_sel_hi:[0, 1, 1] neg_lo:[0, 0, 1] neg_hi:[0, 0, 1]
	v_cvt_pk_bf16_f32 v2, v10, v11
	v_lshlrev_b32_e32 v10, 16, v3
	v_and_b32_e32 v11, 0xffff0000, v3
	v_pk_fma_f32 v[10:11], v[22:23], v[10:11], 0 op_sel_hi:[0, 1, 0]
	v_lshlrev_b32_e32 v6, 16, v7
	v_and_b32_e32 v7, 0xffff0000, v7
	v_pk_fma_f32 v[10:11], v[24:25], v[6:7], v[10:11] op_sel_hi:[0, 1, 1]
	v_pk_fma_f32 v[6:7], v[18:19], v[10:11], v[6:7] op_sel_hi:[0, 1, 1] neg_lo:[0, 0, 1] neg_hi:[0, 0, 1]
	v_cvt_pk_bf16_f32 v3, v6, v7
	v_lshlrev_b32_e32 v6, 16, v4
	v_and_b32_e32 v7, 0xffff0000, v4
	v_pk_fma_f32 v[6:7], v[22:23], v[6:7], 0 op_sel_hi:[0, 1, 0]
	v_lshlrev_b32_e32 v10, 16, v8
	v_and_b32_e32 v11, 0xffff0000, v8
	v_pk_fma_f32 v[6:7], v[24:25], v[10:11], v[6:7] op_sel_hi:[0, 1, 1]
	v_pk_fma_f32 v[6:7], v[18:19], v[6:7], v[10:11] op_sel_hi:[0, 1, 1] neg_lo:[0, 0, 1] neg_hi:[0, 0, 1]
	v_cvt_pk_bf16_f32 v4, v6, v7
	v_lshlrev_b32_e32 v6, 16, v5
	v_and_b32_e32 v7, 0xffff0000, v5
	v_pk_fma_f32 v[6:7], v[22:23], v[6:7], 0 op_sel_hi:[0, 1, 0]
	v_lshlrev_b32_e32 v8, 16, v9
	v_and_b32_e32 v9, 0xffff0000, v9
	v_pk_fma_f32 v[6:7], v[24:25], v[8:9], v[6:7] op_sel_hi:[0, 1, 1]
	v_pk_fma_f32 v[6:7], v[18:19], v[6:7], v[8:9] op_sel_hi:[0, 1, 1] neg_lo:[0, 0, 1] neg_hi:[0, 0, 1]
	v_cvt_pk_bf16_f32 v5, v6, v7
	s_nop 0
	s_nop 0
	s_waitcnt vmcnt(5)
	v_lshlrev_b32_e32 v26, 16, v92
	v_and_b32_e32 v27, 0xffff0000, v92
	v_pk_fma_f32 v[26:27], v[22:23], v[26:27], 0 op_sel_hi:[0, 1, 0]
	s_waitcnt vmcnt(4)
	v_lshlrev_b32_e32 v30, 16, v96
	v_and_b32_e32 v31, 0xffff0000, v96
	v_pk_fma_f32 v[26:27], v[24:25], v[30:31], v[26:27] op_sel_hi:[0, 1, 1]
	v_pk_fma_f32 v[26:27], v[18:19], v[26:27], v[30:31] op_sel_hi:[0, 1, 1] neg_lo:[0, 0, 1] neg_hi:[0, 0, 1]
	v_cvt_pk_bf16_f32 v6, v26, v27
	v_lshlrev_b32_e32 v26, 16, v93
	v_and_b32_e32 v27, 0xffff0000, v93
	v_pk_fma_f32 v[26:27], v[22:23], v[26:27], 0 op_sel_hi:[0, 1, 0]
	v_lshlrev_b32_e32 v10, 16, v97
	v_and_b32_e32 v11, 0xffff0000, v97
	v_pk_fma_f32 v[26:27], v[24:25], v[10:11], v[26:27] op_sel_hi:[0, 1, 1]
	v_pk_fma_f32 v[10:11], v[18:19], v[26:27], v[10:11] op_sel_hi:[0, 1, 1] neg_lo:[0, 0, 1] neg_hi:[0, 0, 1]
	v_cvt_pk_bf16_f32 v7, v10, v11
	v_lshlrev_b32_e32 v10, 16, v94
	v_and_b32_e32 v11, 0xffff0000, v94
	v_pk_fma_f32 v[10:11], v[22:23], v[10:11], 0 op_sel_hi:[0, 1, 0]
	v_lshlrev_b32_e32 v26, 16, v98
	v_and_b32_e32 v27, 0xffff0000, v98
	v_pk_fma_f32 v[10:11], v[24:25], v[26:27], v[10:11] op_sel_hi:[0, 1, 1]
	v_pk_fma_f32 v[10:11], v[18:19], v[10:11], v[26:27] op_sel_hi:[0, 1, 1] neg_lo:[0, 0, 1] neg_hi:[0, 0, 1]
	v_cvt_pk_bf16_f32 v8, v10, v11
	v_lshlrev_b32_e32 v10, 16, v95
	v_and_b32_e32 v11, 0xffff0000, v95
	v_pk_fma_f32 v[10:11], v[22:23], v[10:11], 0 op_sel_hi:[0, 1, 0]
	v_lshlrev_b32_e32 v12, 16, v99
	v_and_b32_e32 v13, 0xffff0000, v99
	v_pk_fma_f32 v[10:11], v[24:25], v[12:13], v[10:11] op_sel_hi:[0, 1, 1]
	v_pk_fma_f32 v[10:11], v[18:19], v[10:11], v[12:13] op_sel_hi:[0, 1, 1] neg_lo:[0, 0, 1] neg_hi:[0, 0, 1]
	v_cvt_pk_bf16_f32 v9, v10, v11
	s_nop 0
	s_nop 0
	s_waitcnt vmcnt(3)
	v_lshlrev_b32_e32 v26, 16, v100
	v_and_b32_e32 v27, 0xffff0000, v100
	v_pk_fma_f32 v[26:27], v[22:23], v[26:27], 0 op_sel_hi:[0, 1, 0]
	s_waitcnt vmcnt(2)
	v_lshlrev_b32_e32 v36, 16, v104
	v_and_b32_e32 v37, 0xffff0000, v104
	v_pk_fma_f32 v[26:27], v[24:25], v[36:37], v[26:27] op_sel_hi:[0, 1, 1]
	v_pk_fma_f32 v[26:27], v[18:19], v[26:27], v[36:37] op_sel_hi:[0, 1, 1] neg_lo:[0, 0, 1] neg_hi:[0, 0, 1]
	v_cvt_pk_bf16_f32 v10, v26, v27
	v_lshlrev_b32_e32 v26, 16, v101
	v_and_b32_e32 v27, 0xffff0000, v101
	v_pk_fma_f32 v[26:27], v[22:23], v[26:27], 0 op_sel_hi:[0, 1, 0]
	v_lshlrev_b32_e32 v30, 16, v105
	v_and_b32_e32 v31, 0xffff0000, v105
	v_pk_fma_f32 v[26:27], v[24:25], v[30:31], v[26:27] op_sel_hi:[0, 1, 1]
	v_pk_fma_f32 v[26:27], v[18:19], v[26:27], v[30:31] op_sel_hi:[0, 1, 1] neg_lo:[0, 0, 1] neg_hi:[0, 0, 1]
	v_cvt_pk_bf16_f32 v11, v26, v27
	v_lshlrev_b32_e32 v26, 16, v102
	v_and_b32_e32 v27, 0xffff0000, v102
	v_pk_fma_f32 v[26:27], v[22:23], v[26:27], 0 op_sel_hi:[0, 1, 0]
	v_lshlrev_b32_e32 v30, 16, v106
	v_and_b32_e32 v31, 0xffff0000, v106
	v_pk_fma_f32 v[26:27], v[24:25], v[30:31], v[26:27] op_sel_hi:[0, 1, 1]
	v_pk_fma_f32 v[26:27], v[18:19], v[26:27], v[30:31] op_sel_hi:[0, 1, 1] neg_lo:[0, 0, 1] neg_hi:[0, 0, 1]
	v_cvt_pk_bf16_f32 v12, v26, v27
	v_lshlrev_b32_e32 v26, 16, v103
	v_and_b32_e32 v27, 0xffff0000, v103
	v_pk_fma_f32 v[26:27], v[22:23], v[26:27], 0 op_sel_hi:[0, 1, 0]
	v_lshlrev_b32_e32 v30, 16, v107
	v_and_b32_e32 v31, 0xffff0000, v107
	v_pk_fma_f32 v[26:27], v[24:25], v[30:31], v[26:27] op_sel_hi:[0, 1, 1]
	v_pk_fma_f32 v[26:27], v[18:19], v[26:27], v[30:31] op_sel_hi:[0, 1, 1] neg_lo:[0, 0, 1] neg_hi:[0, 0, 1]
	s_nop 0
	s_nop 0
	s_nop 0
	v_cvt_pk_bf16_f32 v13, v26, v27
	s_waitcnt vmcnt(1)
	v_lshlrev_b32_e32 v26, 16, v108
	v_and_b32_e32 v27, 0xffff0000, v108
	v_pk_fma_f32 v[26:27], v[22:23], v[26:27], 0 op_sel_hi:[0, 1, 0]
	s_waitcnt vmcnt(0)
	v_lshlrev_b32_e32 v36, 16, v112
	v_and_b32_e32 v37, 0xffff0000, v112
	v_pk_fma_f32 v[26:27], v[24:25], v[36:37], v[26:27] op_sel_hi:[0, 1, 1]
	v_pk_fma_f32 v[26:27], v[18:19], v[26:27], v[36:37] op_sel_hi:[0, 1, 1] neg_lo:[0, 0, 1] neg_hi:[0, 0, 1]
	v_cvt_pk_bf16_f32 v14, v26, v27
	v_lshlrev_b32_e32 v26, 16, v109
	v_and_b32_e32 v27, 0xffff0000, v109
	v_pk_fma_f32 v[26:27], v[22:23], v[26:27], 0 op_sel_hi:[0, 1, 0]
	v_lshlrev_b32_e32 v30, 16, v113
	v_and_b32_e32 v31, 0xffff0000, v113
	v_pk_fma_f32 v[26:27], v[24:25], v[30:31], v[26:27] op_sel_hi:[0, 1, 1]
	v_pk_fma_f32 v[26:27], v[18:19], v[26:27], v[30:31] op_sel_hi:[0, 1, 1] neg_lo:[0, 0, 1] neg_hi:[0, 0, 1]
	v_cvt_pk_bf16_f32 v15, v26, v27
	v_lshlrev_b32_e32 v26, 16, v110
	v_and_b32_e32 v27, 0xffff0000, v110
	v_pk_fma_f32 v[26:27], v[22:23], v[26:27], 0 op_sel_hi:[0, 1, 0]
	v_lshlrev_b32_e32 v30, 16, v114
	v_and_b32_e32 v31, 0xffff0000, v114
	v_pk_fma_f32 v[26:27], v[24:25], v[30:31], v[26:27] op_sel_hi:[0, 1, 1]
	v_pk_fma_f32 v[26:27], v[18:19], v[26:27], v[30:31] op_sel_hi:[0, 1, 1] neg_lo:[0, 0, 1] neg_hi:[0, 0, 1]
	v_cvt_pk_bf16_f32 v16, v26, v27
	v_lshlrev_b32_e32 v26, 16, v111
	v_and_b32_e32 v27, 0xffff0000, v111
	v_pk_fma_f32 v[26:27], v[22:23], v[26:27], 0 op_sel_hi:[0, 1, 0]
	v_lshlrev_b32_e32 v30, 16, v115
	v_and_b32_e32 v31, 0xffff0000, v115
	v_pk_fma_f32 v[24:25], v[24:25], v[30:31], v[26:27] op_sel_hi:[0, 1, 1]
	v_pk_fma_f32 v[18:19], v[18:19], v[24:25], v[30:31] op_sel_hi:[0, 1, 1] neg_lo:[0, 0, 1] neg_hi:[0, 0, 1]
	v_cvt_pk_bf16_f32 v17, v18, v19
	v_lshl_add_u64 v[18:19], s[38:39], 0, v[28:29]
	v_lshl_add_u64 v[30:31], s[84:85], 0, v[20:21]
	v_lshlrev_b32_e32 v20, 8, v23
	v_mov_b32_e32 v21, v1
	v_lshl_add_u64 v[32:33], v[18:19], 0, v[20:21]
	v_add_co_u32_e32 v56, vcc, 0x1000, v32
	s_nop 1
	v_addc_co_u32_e32 v57, vcc, 0, v33, vcc
	v_add_co_u32_e32 v58, vcc, 0x3000, v32
	s_nop 1
	v_addc_co_u32_e32 v59, vcc, 0, v33, vcc
	v_add_co_u32_e32 v60, vcc, 0x5000, v32
	s_nop 1
	v_addc_co_u32_e32 v61, vcc, 0, v33, vcc
	v_add_co_u32_e32 v62, vcc, 0x7000, v32
	s_nop 1
	v_addc_co_u32_e32 v63, vcc, 0, v33, vcc
	global_load_dwordx4 v[100:103], v28, s[30:31]
	global_load_dwordx4 v[120:123], v28, s[30:31] offset:64
	global_load_dwordx4 v[140:143], v28, s[30:31] offset:128
	global_load_dwordx4 v[160:163], v28, s[30:31] offset:192
	global_load_dwordx4 v[180:183], v28, s[30:31] offset:256
	global_load_dwordx4 v[200:203], v28, s[30:31] offset:320
	global_load_dwordx4 v[234:237], v28, s[30:31] offset:384
	v_and_b32_e32 v56, 15, v209
	v_bfe_u32 v57, v209, 4, 2
	v_mul_u32_u24_e32 v56, 0x110, v56
	v_lshl_add_u32 v56, v57, 4, v56
	ds_read_b128 v[84:87], v56 offset:0
	ds_read_b128 v[88:91], v56 offset:64
	ds_read_b128 v[92:95], v56 offset:128
	ds_read_b128 v[96:99], v56 offset:192
	ds_read_b128 v[104:107], v56 offset:4352
	ds_read_b128 v[108:111], v56 offset:4416
	ds_read_b128 v[112:115], v56 offset:4480
	ds_read_b128 v[116:119], v56 offset:4544
	ds_read_b128 v[124:127], v56 offset:8704
	ds_read_b128 v[128:131], v56 offset:8768
	ds_read_b128 v[132:135], v56 offset:8832
	ds_read_b128 v[136:139], v56 offset:8896
	ds_read_b128 v[144:147], v56 offset:13056
	ds_read_b128 v[148:151], v56 offset:13120
	ds_read_b128 v[152:155], v56 offset:13184
	ds_read_b128 v[156:159], v56 offset:13248
	s_nop 0
	s_nop 0
	s_waitcnt lgkmcnt(12)
	v_mfma_f32_16x16x32_bf16 v[18:21], v[84:87], v[2:5], 0
	v_lshl_add_u64 v[26:27], v[30:31], 0, s[0:1]
	s_movk_i32 s0, 0x1000
	v_mfma_f32_16x16x32_bf16 v[18:21], v[88:91], v[6:9], v[18:21]
	s_nop 0
	v_mfma_f32_16x16x32_bf16 v[18:21], v[92:95], v[10:13], v[18:21]
	s_nop 0
	v_mfma_f32_16x16x32_bf16 v[18:21], v[96:99], v[14:17], v[18:21]
	s_nop 0
	s_waitcnt vmcnt(6)
	s_nop 5
	v_pk_mul_f32 v[20:21], v[20:21], v[102:103]
	v_add_co_u32_e32 v24, vcc, s0, v32
	v_pk_mul_f32 v[18:19], v[18:19], v[100:101]
	s_nop 0
	v_addc_co_u32_e32 v25, vcc, 0, v33, vcc
	s_movk_i32 s0, 0x2000
	v_cvt_pk_bf16_f32 v22, v18, v19
	v_cvt_pk_bf16_f32 v23, v20, v21
	v_lshl_add_u64 v[18:19], v[30:31], 0, v[0:1]
	v_add_co_u32_e32 v30, vcc, s0, v32
	global_store_dwordx2 v[18:19], v[22:23], off offset:1024
	s_nop 0
	v_addc_co_u32_e32 v31, vcc, 0, v33, vcc
	s_nop 0
	s_nop 0
	s_waitcnt lgkmcnt(8)
	v_mfma_f32_16x16x32_bf16 v[20:23], v[104:107], v[2:5], 0
	s_movk_i32 s0, 0x3000
	v_mov_b32_e32 v0, 0x70
	v_lshl_or_b32 v0, v34, 2, v0
	v_mfma_f32_16x16x32_bf16 v[20:23], v[108:111], v[6:9], v[20:23]
	s_nop 0
	v_mfma_f32_16x16x32_bf16 v[20:23], v[112:115], v[10:13], v[20:23]
	s_nop 0
	v_add_co_u32_e32 v24, vcc, s0, v32
	v_mfma_f32_16x16x32_bf16 v[20:23], v[116:119], v[14:17], v[20:23]
	s_nop 0
	v_addc_co_u32_e32 v25, vcc, 0, v33, vcc
	s_movk_i32 s0, 0x4000
	s_waitcnt vmcnt(6)
	s_nop 3
	v_pk_mul_f32 v[22:23], v[22:23], v[122:123]
	v_pk_mul_f32 v[20:21], v[20:21], v[120:121]
	s_nop 0
	v_cvt_pk_bf16_f32 v20, v20, v21
	v_cvt_pk_bf16_f32 v21, v22, v23
	global_store_dwordx2 v[18:19], v[20:21], off offset:1056
	s_nop 0
	s_nop 0
	s_nop 0
	s_waitcnt lgkmcnt(4)
	v_mfma_f32_16x16x32_bf16 v[20:23], v[124:127], v[2:5], 0
	v_mfma_f32_16x16x32_bf16 v[20:23], v[128:131], v[6:9], v[20:23]
	s_nop 0
	v_mfma_f32_16x16x32_bf16 v[20:23], v[132:135], v[10:13], v[20:23]
	s_nop 0
	v_add_co_u32_e32 v30, vcc, s0, v32
	v_mfma_f32_16x16x32_bf16 v[20:23], v[136:139], v[14:17], v[20:23]
	s_nop 0
	v_addc_co_u32_e32 v31, vcc, 0, v33, vcc
	s_movk_i32 s0, 0x5000
	s_waitcnt vmcnt(6)
	s_nop 3
	v_pk_mul_f32 v[22:23], v[22:23], v[142:143]
	v_pk_mul_f32 v[20:21], v[20:21], v[140:141]
	s_nop 0
	v_cvt_pk_bf16_f32 v20, v20, v21
	v_cvt_pk_bf16_f32 v21, v22, v23
	global_store_dwordx2 v[18:19], v[20:21], off offset:1088
	s_nop 0
	s_nop 0
	s_nop 0
	s_waitcnt lgkmcnt(0)
	v_mfma_f32_16x16x32_bf16 v[20:23], v[144:147], v[2:5], 0
	v_mfma_f32_16x16x32_bf16 v[20:23], v[148:151], v[6:9], v[20:23]
	s_nop 0
	v_mfma_f32_16x16x32_bf16 v[20:23], v[152:155], v[10:13], v[20:23]
	s_nop 0
	v_add_co_u32_e32 v24, vcc, s0, v32
	v_mfma_f32_16x16x32_bf16 v[20:23], v[156:159], v[14:17], v[20:23]
	s_nop 0
	v_addc_co_u32_e32 v25, vcc, 0, v33, vcc
	s_movk_i32 s0, 0x6000
	s_waitcnt vmcnt(6)
	s_nop 3
	v_pk_mul_f32 v[22:23], v[22:23], v[162:163]
	v_pk_mul_f32 v[20:21], v[20:21], v[160:161]
	s_nop 0
	v_cvt_pk_bf16_f32 v20, v20, v21
	v_cvt_pk_bf16_f32 v21, v22, v23
	global_store_dwordx2 v[18:19], v[20:21], off offset:1120
	s_nop 0
	s_nop 0
	s_nop 0
	ds_read_b128 v[164:167], v56 offset:17408
	ds_read_b128 v[168:171], v56 offset:17472
	ds_read_b128 v[172:175], v56 offset:17536
	ds_read_b128 v[176:179], v56 offset:17600
	ds_read_b128 v[184:187], v56 offset:21760
	ds_read_b128 v[188:191], v56 offset:21824
	ds_read_b128 v[192:195], v56 offset:21888
	ds_read_b128 v[196:199], v56 offset:21952
	ds_read_b128 v[204:207], v56 offset:26112
	ds_read_b128 v[222:225], v56 offset:26176
	ds_read_b128 v[226:229], v56 offset:26240
	ds_read_b128 v[230:233], v56 offset:26304
	ds_read_b128 v[238:241], v56 offset:30464
	ds_read_b128 v[242:245], v56 offset:30528
	ds_read_b128 v[246:249], v56 offset:30592
	ds_read_b128 v[52:55], v56 offset:30656
	s_waitcnt lgkmcnt(12)
	v_mfma_f32_16x16x32_bf16 v[20:23], v[164:167], v[2:5], 0
	v_mfma_f32_16x16x32_bf16 v[20:23], v[168:171], v[6:9], v[20:23]
	s_nop 0
	v_mfma_f32_16x16x32_bf16 v[20:23], v[172:175], v[10:13], v[20:23]
	s_nop 0
	v_add_co_u32_e32 v30, vcc, s0, v32
	v_mfma_f32_16x16x32_bf16 v[20:23], v[176:179], v[14:17], v[20:23]
	s_nop 0
	v_addc_co_u32_e32 v31, vcc, 0, v33, vcc
	s_waitcnt vmcnt(6)
	s_nop 4
	v_pk_mul_f32 v[22:23], v[22:23], v[182:183]
	v_pk_mul_f32 v[20:21], v[20:21], v[180:181]
	s_nop 0
	v_cvt_pk_bf16_f32 v20, v20, v21
	v_cvt_pk_bf16_f32 v21, v22, v23
	global_store_dwordx2 v[18:19], v[20:21], off offset:1152
	s_nop 0
	s_nop 0
	s_nop 0
	s_waitcnt lgkmcnt(8)
	v_mfma_f32_16x16x32_bf16 v[20:23], v[184:187], v[2:5], 0
	v_mfma_f32_16x16x32_bf16 v[20:23], v[188:191], v[6:9], v[20:23]
	s_nop 0
	v_mfma_f32_16x16x32_bf16 v[20:23], v[192:195], v[10:13], v[20:23]
	s_nop 0
	v_mfma_f32_16x16x32_bf16 v[20:23], v[196:199], v[14:17], v[20:23]
	s_nop 0
	s_waitcnt vmcnt(6)
	s_nop 5
	v_pk_mul_f32 v[22:23], v[22:23], v[202:203]
	v_pk_mul_f32 v[20:21], v[20:21], v[200:201]
	s_nop 0
	v_cvt_pk_bf16_f32 v20, v20, v21
	v_cvt_pk_bf16_f32 v21, v22, v23
	global_store_dwordx2 v[18:19], v[20:21], off offset:1184
	s_nop 0
	s_nop 0
	s_nop 0
	s_waitcnt lgkmcnt(4)
	v_mfma_f32_16x16x32_bf16 v[20:23], v[204:207], v[2:5], 0
	v_mfma_f32_16x16x32_bf16 v[20:23], v[222:225], v[6:9], v[20:23]
	s_nop 0
	v_mfma_f32_16x16x32_bf16 v[20:23], v[226:229], v[10:13], v[20:23]
	s_nop 0
	s_nop 0
	s_nop 0
	v_mfma_f32_16x16x32_bf16 v[20:23], v[230:233], v[14:17], v[20:23]
	s_waitcnt vmcnt(6)
	s_nop 6
	v_pk_mul_f32 v[22:23], v[22:23], v[236:237]
	v_pk_mul_f32 v[20:21], v[20:21], v[234:235]
	s_nop 0
	v_cvt_pk_bf16_f32 v20, v20, v21
	v_cvt_pk_bf16_f32 v21, v22, v23
	v_add_co_u32_e32 v22, vcc, 0x7000, v32
	global_store_dwordx2 v[18:19], v[20:21], off offset:1216
	s_nop 0
	v_addc_co_u32_e32 v23, vcc, 0, v33, vcc
	s_nop 0
	s_waitcnt lgkmcnt(0)
	v_mfma_f32_16x16x32_bf16 v[2:5], v[238:241], v[2:5], 0
	s_nop 0
	v_mfma_f32_16x16x32_bf16 v[2:5], v[242:245], v[6:9], v[2:5]
	s_nop 0
	v_mfma_f32_16x16x32_bf16 v[2:5], v[246:249], v[10:13], v[2:5]
	s_nop 0
	v_mfma_f32_16x16x32_bf16 v[2:5], v[52:55], v[14:17], v[2:5]
	s_branch .LBB0_579
